# v29 + snake MFMA order inside GEMM MMA blocks (consecutive MFMAs always share one operand)
# speedup vs baseline: 1.0124x; 1.0124x over previous
; #define PG8_STAGE(bufoff, gbase, voff) do { _Pragma("unroll") for (int _i = 0; _i < 2; ++_i) \
;         __builtin_amdgcn_global_load_lds((const unsigned*)((const char*)(gbase) + (voff)[_i]), (PG8_LAS unsigned*)(lds + (bufoff) + ldsw + _i * 8192), 16, 0, 0); } while (0)
; #define PG8_LDA(dst, b, h) do { _Pragma("unroll") for (int m = 0; m < 4; ++m) _Pragma("unroll") for (int k = 0; k < 2; ++k) dst[m][k] = *(const PG8_LAS bf16x8*)(lds + PG8_SA(b, h) + aoff + m * 2048 + k * 1024); } while (0)
; #define PG8_LDB(dst, b, h) do { _Pragma("unroll") for (int n = 0; n < 2; ++n) _Pragma("unroll") for (int k = 0; k < 2; ++k) dst[n][k] = *(const PG8_LAS bf16x8*)(lds + PG8_SB(b, h) + boff + n * 2048 + k * 1024); } while (0)
; #define PG8_MMA(ai, bj, At, Bt) do { __builtin_amdgcn_s_setprio(1); _Pragma("unroll") for (int m = 0; m < 4; ++m) _Pragma("unroll") for (int n = 0; n < 2; ++n) _Pragma("unroll") for (int k = 0; k < 2; ++k) \
;         acc[ai][bj][m][n] = __builtin_amdgcn_mfma_f32_16x16x32_bf16(Bt[n][k], At[m][k], acc[ai][bj][m][n], 0, 0, 0); __builtin_amdgcn_s_setprio(0); } while (0)
; #define PG8_WAIT_V(n) asm volatile("s_waitcnt vmcnt(" #n ")" ::: "memory")
; #define PG8_WAIT_L(n) asm volatile("s_waitcnt lgkmcnt(" #n ")" ::: "memory")
; template <class Epi, class Sched, bool ALIGN_EPI = false, bool SP2 = false>
; __device__ __forceinline__ void gemm_phase(PG8_LAS unsigned char* lds, const Gemm g, const Sched& S, const Epi& E) {
;     ...
;             const bool last = (t == nt - 2);
;             const char* a1 = cA + (size_t)(t + 1) * kstep;
;             const char* a2 = last ? nA : cA + (size_t)(t + 2) * kstep; const char* b2 = last ? nB : cB + (size_t)(t + 2) * kstep;
;             const char* a3 = a2 + kstep; const char* b3 = b2 + kstep;
;             if (last && has_next) S.a_ready(nxt);
;             if constexpr (SP2) {
;             PG8_LDB(B0, 0, 0); PG8_LDB(B1, 0, 1); PG8_SCHED; PG8_LDA(At, 0, 0); PG8_STAGE(PG8_SA(1, 1), a1 + hstep, voffA);
;             PG8_WAIT_V(8); PG8_WAIT_L(0); PG8_BAR; PG8_MMA(0, 0, At, B0); PG8_MMA(0, 1, At, B1); PG8_BAR; PG8_SCHED;
;             PG8_LDA(At, 0, 1); PG8_STAGE(PG8_SB(0, 0), b2, voffB); PG8_STAGE(PG8_SB(0, 1), b2 + hstepB, voffB); PG8_STAGE(PG8_SA(0, 0), a2, voffA);
;             PG8_WAIT_V(8); PG8_WAIT_L(0); PG8_BAR; PG8_MMA(1, 0, At, B0); PG8_MMA(1, 1, At, B1); PG8_BAR; PG8_SCHED;
.LBB0_764:
	ds_read_b128 v[158:161], v155
	ds_read_b128 v[162:165], v155 offset:1024
	ds_read_b128 v[166:169], v155 offset:2048
	ds_read_b128 v[176:179], v155 offset:3072
	ds_read_b128 v[180:183], v156
	ds_read_b128 v[184:187], v156 offset:1024
	ds_read_b128 v[188:191], v156 offset:2048
	ds_read_b128 v[192:195], v156 offset:3072
	s_add_u32 s42, s38, 0xfff80080
	s_addc_u32 s43, s39, -1
	s_cmp_eq_u32 s49, 28
	s_cselect_b32 s59, s7, s43
	s_cselect_b32 s58, s29, s42
	s_cselect_b32 s43, s27, s48
	s_cselect_b32 s42, s40, s41
	v_lshl_add_u64 v[146:147], s[38:39], 0, v[140:141]
	s_add_i32 m0, s37, 0xc000
	ds_read_b128 v[196:199], v157
	ds_read_b128 v[202:205], v157 offset:1024
	ds_read_b128 v[206:209], v157 offset:2048
	ds_read_b128 v[210:213], v157 offset:3072
	ds_read_b128 v[214:217], v157 offset:4096
	ds_read_b128 v[218:221], v157 offset:5120
	ds_read_b128 v[222:225], v157 offset:6144
	ds_read_b128 v[226:229], v157 offset:7168
	global_load_lds_dwordx4 v[146:147], off
	v_lshl_add_u64 v[146:147], s[38:39], 0, v[138:139]
	s_add_i32 m0, s37, 0xe000
	s_nop 0
	global_load_lds_dwordx4 v[146:147], off
	s_waitcnt vmcnt(8)
	s_waitcnt lgkmcnt(0)
	s_barrier
	s_setprio 1
	s_waitcnt lgkmcnt(0)
	v_mfma_f32_16x16x32_bf16 v[124:127], v[158:161], v[196:199], v[124:127]
	v_mfma_f32_16x16x32_bf16 v[120:123], v[166:169], v[196:199], v[120:123]
	v_mfma_f32_16x16x32_bf16 v[104:107], v[166:169], v[206:209], v[104:107]
	v_mfma_f32_16x16x32_bf16 v[108:111], v[158:161], v[206:209], v[108:111]
	v_mfma_f32_16x16x32_bf16 v[92:95], v[158:161], v[214:217], v[92:95]
	v_mfma_f32_16x16x32_bf16 v[88:91], v[166:169], v[214:217], v[88:91]
	v_mfma_f32_16x16x32_bf16 v[72:75], v[166:169], v[222:225], v[72:75]
	v_mfma_f32_16x16x32_bf16 v[76:79], v[158:161], v[222:225], v[76:79]
	v_mfma_f32_16x16x32_bf16 v[124:127], v[162:165], v[202:205], v[124:127]
	v_mfma_f32_16x16x32_bf16 v[120:123], v[176:179], v[202:205], v[120:123]
	v_mfma_f32_16x16x32_bf16 v[104:107], v[176:179], v[210:213], v[104:107]
	v_mfma_f32_16x16x32_bf16 v[108:111], v[162:165], v[210:213], v[108:111]
	v_mfma_f32_16x16x32_bf16 v[92:95], v[162:165], v[218:221], v[92:95]
	v_mfma_f32_16x16x32_bf16 v[88:91], v[176:179], v[218:221], v[88:91]
	v_mfma_f32_16x16x32_bf16 v[72:75], v[176:179], v[226:229], v[72:75]
	v_mfma_f32_16x16x32_bf16 v[76:79], v[162:165], v[226:229], v[76:79]
	s_setprio 0
	s_setprio 1
	v_mfma_f32_16x16x32_bf16 v[116:119], v[180:183], v[196:199], v[116:119]
	v_mfma_f32_16x16x32_bf16 v[112:115], v[188:191], v[196:199], v[112:115]
	v_mfma_f32_16x16x32_bf16 v[96:99], v[188:191], v[206:209], v[96:99]
	v_mfma_f32_16x16x32_bf16 v[100:103], v[180:183], v[206:209], v[100:103]
	v_mfma_f32_16x16x32_bf16 v[84:87], v[180:183], v[214:217], v[84:87]
	v_mfma_f32_16x16x32_bf16 v[80:83], v[188:191], v[214:217], v[80:83]
	v_mfma_f32_16x16x32_bf16 v[64:67], v[188:191], v[222:225], v[64:67]
	v_mfma_f32_16x16x32_bf16 v[68:71], v[180:183], v[222:225], v[68:71]
	v_mfma_f32_16x16x32_bf16 v[116:119], v[184:187], v[202:205], v[116:119]
	v_mfma_f32_16x16x32_bf16 v[112:115], v[192:195], v[202:205], v[112:115]
	v_mfma_f32_16x16x32_bf16 v[96:99], v[192:195], v[210:213], v[96:99]
	v_mfma_f32_16x16x32_bf16 v[100:103], v[184:187], v[210:213], v[100:103]
	v_mfma_f32_16x16x32_bf16 v[84:87], v[184:187], v[218:221], v[84:87]
	v_mfma_f32_16x16x32_bf16 v[80:83], v[192:195], v[218:221], v[80:83]
	v_mfma_f32_16x16x32_bf16 v[64:67], v[192:195], v[226:229], v[64:67]
	v_mfma_f32_16x16x32_bf16 v[68:71], v[184:187], v[226:229], v[68:71]
	s_setprio 0
	s_barrier
	s_add_i32 s50, s69, s53
	v_lshl_add_u64 v[146:147], s[42:43], 0, v[130:131]
	s_mov_b32 m0, s50
	ds_read_b128 v[196:199], v157 offset:16384
	ds_read_b128 v[202:205], v157 offset:17408
	ds_read_b128 v[206:209], v157 offset:18432
	ds_read_b128 v[210:213], v157 offset:19456
	ds_read_b128 v[214:217], v157 offset:20480
	ds_read_b128 v[218:221], v157 offset:21504
	ds_read_b128 v[222:225], v157 offset:22528
	ds_read_b128 v[226:229], v157 offset:23552
	global_load_lds_dwordx4 v[146:147], off
	s_add_i32 m0, s50, 0x2000
	s_add_u32 s50, s42, 0x20000
	v_lshl_add_u64 v[230:231], s[42:43], 0, v[134:135]
	s_addc_u32 s51, s43, 0
	s_add_i32 s54, s70, s53
	global_load_lds_dwordx4 v[230:231], off
	v_lshl_add_u64 v[232:233], s[50:51], 0, v[130:131]
	s_mov_b32 m0, s54
	v_lshl_add_u64 v[234:235], s[58:59], 0, v[132:133]
	global_load_lds_dwordx4 v[232:233], off
	v_lshl_add_u64 v[232:233], s[50:51], 0, v[134:135]
	s_add_i32 m0, s54, 0x2000
	s_nop 0
	global_load_lds_dwordx4 v[232:233], off
	v_lshl_add_u64 v[232:233], s[58:59], 0, v[128:129]
	s_mov_b32 m0, s37
	s_nop 0
	global_load_lds_dwordx4 v[232:233], off
	s_mov_b32 m0, s60
	s_nop 0
	global_load_lds_dwordx4 v[234:235], off
	s_waitcnt vmcnt(8)
	s_waitcnt lgkmcnt(0)
	s_barrier
; #define PG8_STAGE(bufoff, gbase, voff) do { _Pragma("unroll") for (int _i = 0; _i < 2; ++_i) \
;         __builtin_amdgcn_global_load_lds((const unsigned*)((const char*)(gbase) + (voff)[_i]), (PG8_LAS unsigned*)(lds + (bufoff) + ldsw + _i * 8192), 16, 0, 0); } while (0)
; #define PG8_LDA(dst, b, h) do { _Pragma("unroll") for (int m = 0; m < 4; ++m) _Pragma("unroll") for (int k = 0; k < 2; ++k) dst[m][k] = *(const PG8_LAS bf16x8*)(lds + PG8_SA(b, h) + aoff + m * 2048 + k * 1024); } while (0)
; #define PG8_LDB(dst, b, h) do { _Pragma("unroll") for (int n = 0; n < 2; ++n) _Pragma("unroll") for (int k = 0; k < 2; ++k) dst[n][k] = *(const PG8_LAS bf16x8*)(lds + PG8_SB(b, h) + boff + n * 2048 + k * 1024); } while (0)
; #define PG8_MMA(ai, bj, At, Bt) do { __builtin_amdgcn_s_setprio(1); _Pragma("unroll") for (int m = 0; m < 4; ++m) _Pragma("unroll") for (int n = 0; n < 2; ++n) _Pragma("unroll") for (int k = 0; k < 2; ++k) \
;         acc[ai][bj][m][n] = __builtin_amdgcn_mfma_f32_16x16x32_bf16(Bt[n][k], At[m][k], acc[ai][bj][m][n], 0, 0, 0); __builtin_amdgcn_s_setprio(0); } while (0)
; #define PG8_WAIT_V(n) asm volatile("s_waitcnt vmcnt(" #n ")" ::: "memory")
; #define PG8_WAIT_L(n) asm volatile("s_waitcnt lgkmcnt(" #n ")" ::: "memory")
; #define PG8_BAR __builtin_amdgcn_s_barrier()
; #define PG8_SCHED __builtin_amdgcn_sched_barrier(0)
; template <class Epi, class Sched, bool ALIGN_EPI = false, bool SP2 = false>
; __device__ __forceinline__ void gemm_phase(PG8_LAS unsigned char* lds, const Gemm g, const Sched& S, const Epi& E) {
;     ...
;             PG8_WAIT_V(8); PG8_WAIT_L(0); PG8_BAR; PG8_MMA(1, 0, At, B0); PG8_MMA(1, 1, At, B1); PG8_BAR; PG8_SCHED;
;             PG8_LDB(B0, 1, 0); PG8_LDB(B1, 1, 1); PG8_SCHED; PG8_LDA(At, 1, 0); PG8_STAGE(PG8_SA(0, 1), a2 + hstep, voffA);
;             PG8_WAIT_V(8); PG8_WAIT_L(0); PG8_BAR; PG8_MMA(0, 0, At, B0); PG8_MMA(0, 1, At, B1); PG8_BAR; PG8_SCHED;
	s_setprio 1
	s_waitcnt lgkmcnt(0)
	v_mfma_f32_16x16x32_bf16 v[60:63], v[158:161], v[196:199], v[60:63]
	v_mfma_f32_16x16x32_bf16 v[56:59], v[166:169], v[196:199], v[56:59]
	v_mfma_f32_16x16x32_bf16 v[40:43], v[166:169], v[206:209], v[40:43]
	v_mfma_f32_16x16x32_bf16 v[44:47], v[158:161], v[206:209], v[44:47]
	v_mfma_f32_16x16x32_bf16 v[28:31], v[158:161], v[214:217], v[28:31]
	v_mfma_f32_16x16x32_bf16 v[24:27], v[166:169], v[214:217], v[24:27]
	v_mfma_f32_16x16x32_bf16 v[8:11], v[166:169], v[222:225], v[8:11]
	v_mfma_f32_16x16x32_bf16 v[12:15], v[158:161], v[222:225], v[12:15]
	v_mfma_f32_16x16x32_bf16 v[60:63], v[162:165], v[202:205], v[60:63]
	v_mfma_f32_16x16x32_bf16 v[56:59], v[176:179], v[202:205], v[56:59]
	v_mfma_f32_16x16x32_bf16 v[40:43], v[176:179], v[210:213], v[40:43]
	v_mfma_f32_16x16x32_bf16 v[44:47], v[162:165], v[210:213], v[44:47]
	v_mfma_f32_16x16x32_bf16 v[28:31], v[162:165], v[218:221], v[28:31]
	v_mfma_f32_16x16x32_bf16 v[24:27], v[176:179], v[218:221], v[24:27]
	v_mfma_f32_16x16x32_bf16 v[8:11], v[176:179], v[226:229], v[8:11]
	v_mfma_f32_16x16x32_bf16 v[12:15], v[162:165], v[226:229], v[12:15]
	s_setprio 0
	s_setprio 1
	v_mfma_f32_16x16x32_bf16 v[52:55], v[180:183], v[196:199], v[52:55]
	v_mfma_f32_16x16x32_bf16 v[48:51], v[188:191], v[196:199], v[48:51]
	v_mfma_f32_16x16x32_bf16 v[32:35], v[188:191], v[206:209], v[32:35]
	v_mfma_f32_16x16x32_bf16 v[36:39], v[180:183], v[206:209], v[36:39]
	v_mfma_f32_16x16x32_bf16 v[20:23], v[180:183], v[214:217], v[20:23]
	v_mfma_f32_16x16x32_bf16 v[16:19], v[188:191], v[214:217], v[16:19]
	v_mfma_f32_16x16x32_bf16 v[0:3], v[188:191], v[222:225], v[0:3]
	v_mfma_f32_16x16x32_bf16 v[4:7], v[180:183], v[222:225], v[4:7]
	v_mfma_f32_16x16x32_bf16 v[52:55], v[184:187], v[202:205], v[52:55]
	v_mfma_f32_16x16x32_bf16 v[48:51], v[192:195], v[202:205], v[48:51]
	v_mfma_f32_16x16x32_bf16 v[32:35], v[192:195], v[210:213], v[32:35]
	v_mfma_f32_16x16x32_bf16 v[36:39], v[184:187], v[210:213], v[36:39]
	v_mfma_f32_16x16x32_bf16 v[20:23], v[184:187], v[218:221], v[20:23]
	v_mfma_f32_16x16x32_bf16 v[16:19], v[192:195], v[218:221], v[16:19]
	v_mfma_f32_16x16x32_bf16 v[0:3], v[192:195], v[226:229], v[0:3]
	v_mfma_f32_16x16x32_bf16 v[4:7], v[184:187], v[226:229], v[4:7]
	s_setprio 0
	s_barrier
	s_add_i32 s54, 0, 0x18000
	v_add_u32_e32 v171, s54, v150
	s_add_i32 s55, 0, 0x1c000
	ds_read_b128 v[158:161], v171
	ds_read_b128 v[162:165], v171 offset:1024
	ds_read_b128 v[166:169], v171 offset:2048
	ds_read_b128 v[176:179], v171 offset:3072
	v_add_u32_e32 v171, s55, v150
	ds_read_b128 v[180:183], v171
	ds_read_b128 v[184:187], v171 offset:1024
	ds_read_b128 v[188:191], v171 offset:2048
	ds_read_b128 v[192:195], v171 offset:3072
	s_add_u32 s50, s58, 0x80000
	s_addc_u32 s51, s59, 0
	s_mov_b32 m0, s61
	v_lshl_add_u64 v[236:237], s[50:51], 0, v[128:129]
	ds_read_b128 v[196:199], v157 offset:32768
	ds_read_b128 v[202:205], v157 offset:33792
	ds_read_b128 v[206:209], v157 offset:34816
	ds_read_b128 v[210:213], v157 offset:35840
	ds_read_b128 v[214:217], v157 offset:36864
	ds_read_b128 v[218:221], v157 offset:37888
	ds_read_b128 v[222:225], v157 offset:38912
	ds_read_b128 v[226:229], v157 offset:39936
	global_load_lds_dwordx4 v[236:237], off
	v_lshl_add_u64 v[236:237], s[50:51], 0, v[132:133]
	s_mov_b32 m0, s62
	s_nop 0
	global_load_lds_dwordx4 v[236:237], off
	s_waitcnt vmcnt(8)
	s_waitcnt lgkmcnt(0)
	s_barrier
	s_setprio 1
	s_waitcnt lgkmcnt(0)
	v_mfma_f32_16x16x32_bf16 v[124:127], v[158:161], v[196:199], v[124:127]
	v_mfma_f32_16x16x32_bf16 v[120:123], v[166:169], v[196:199], v[120:123]
	v_mfma_f32_16x16x32_bf16 v[104:107], v[166:169], v[206:209], v[104:107]
	v_mfma_f32_16x16x32_bf16 v[108:111], v[158:161], v[206:209], v[108:111]
	v_mfma_f32_16x16x32_bf16 v[92:95], v[158:161], v[214:217], v[92:95]
	v_mfma_f32_16x16x32_bf16 v[88:91], v[166:169], v[214:217], v[88:91]
	v_mfma_f32_16x16x32_bf16 v[72:75], v[166:169], v[222:225], v[72:75]
	v_mfma_f32_16x16x32_bf16 v[76:79], v[158:161], v[222:225], v[76:79]
	v_mfma_f32_16x16x32_bf16 v[124:127], v[162:165], v[202:205], v[124:127]
	v_mfma_f32_16x16x32_bf16 v[120:123], v[176:179], v[202:205], v[120:123]
	v_mfma_f32_16x16x32_bf16 v[104:107], v[176:179], v[210:213], v[104:107]
	v_mfma_f32_16x16x32_bf16 v[108:111], v[162:165], v[210:213], v[108:111]
	v_mfma_f32_16x16x32_bf16 v[92:95], v[162:165], v[218:221], v[92:95]
	v_mfma_f32_16x16x32_bf16 v[88:91], v[176:179], v[218:221], v[88:91]
	v_mfma_f32_16x16x32_bf16 v[72:75], v[176:179], v[226:229], v[72:75]
	v_mfma_f32_16x16x32_bf16 v[76:79], v[162:165], v[226:229], v[76:79]
	s_setprio 0
	s_setprio 1
	v_mfma_f32_16x16x32_bf16 v[116:119], v[180:183], v[196:199], v[116:119]
	v_mfma_f32_16x16x32_bf16 v[112:115], v[188:191], v[196:199], v[112:115]
	v_mfma_f32_16x16x32_bf16 v[96:99], v[188:191], v[206:209], v[96:99]
	v_mfma_f32_16x16x32_bf16 v[100:103], v[180:183], v[206:209], v[100:103]
	v_mfma_f32_16x16x32_bf16 v[84:87], v[180:183], v[214:217], v[84:87]
	v_mfma_f32_16x16x32_bf16 v[80:83], v[188:191], v[214:217], v[80:83]
	v_mfma_f32_16x16x32_bf16 v[64:67], v[188:191], v[222:225], v[64:67]
	v_mfma_f32_16x16x32_bf16 v[68:71], v[180:183], v[222:225], v[68:71]
	v_mfma_f32_16x16x32_bf16 v[116:119], v[184:187], v[202:205], v[116:119]
	v_mfma_f32_16x16x32_bf16 v[112:115], v[192:195], v[202:205], v[112:115]
	v_mfma_f32_16x16x32_bf16 v[96:99], v[192:195], v[210:213], v[96:99]
	v_mfma_f32_16x16x32_bf16 v[100:103], v[184:187], v[210:213], v[100:103]
	v_mfma_f32_16x16x32_bf16 v[84:87], v[184:187], v[218:221], v[84:87]
	v_mfma_f32_16x16x32_bf16 v[80:83], v[192:195], v[218:221], v[80:83]
	v_mfma_f32_16x16x32_bf16 v[64:67], v[192:195], v[226:229], v[64:67]
	v_mfma_f32_16x16x32_bf16 v[68:71], v[184:187], v[226:229], v[68:71]
	s_setprio 0
	s_barrier
; #define PG8_STAGE(bufoff, gbase, voff) do { _Pragma("unroll") for (int _i = 0; _i < 2; ++_i) \
;         __builtin_amdgcn_global_load_lds((const unsigned*)((const char*)(gbase) + (voff)[_i]), (PG8_LAS unsigned*)(lds + (bufoff) + ldsw + _i * 8192), 16, 0, 0); } while (0)
; #define PG8_LDA(dst, b, h) do { _Pragma("unroll") for (int m = 0; m < 4; ++m) _Pragma("unroll") for (int k = 0; k < 2; ++k) dst[m][k] = *(const PG8_LAS bf16x8*)(lds + PG8_SA(b, h) + aoff + m * 2048 + k * 1024); } while (0)
; #define PG8_MMA(ai, bj, At, Bt) do { __builtin_amdgcn_s_setprio(1); _Pragma("unroll") for (int m = 0; m < 4; ++m) _Pragma("unroll") for (int n = 0; n < 2; ++n) _Pragma("unroll") for (int k = 0; k < 2; ++k) \
;         acc[ai][bj][m][n] = __builtin_amdgcn_mfma_f32_16x16x32_bf16(Bt[n][k], At[m][k], acc[ai][bj][m][n], 0, 0, 0); __builtin_amdgcn_s_setprio(0); } while (0)
; #define PG8_WAIT_V(n) asm volatile("s_waitcnt vmcnt(" #n ")" ::: "memory")
; #define PG8_WAIT_L(n) asm volatile("s_waitcnt lgkmcnt(" #n ")" ::: "memory")
; #define PG8_BAR __builtin_amdgcn_s_barrier()
; #define PG8_SCHED __builtin_amdgcn_sched_barrier(0)
; template <class Epi, class Sched, bool ALIGN_EPI = false, bool SP2 = false>
; __device__ __forceinline__ void gemm_phase(PG8_LAS unsigned char* lds, const Gemm g, const Sched& S, const Epi& E) {
;     ...
;             PG8_LDA(At, 1, 1); PG8_STAGE(PG8_SB(1, 0), b3, voffB); PG8_STAGE(PG8_SB(1, 1), b3 + hstepB, voffB); PG8_STAGE(PG8_SA(1, 0), a3, voffA);
;             PG8_WAIT_V(8); PG8_WAIT_L(0); PG8_BAR; PG8_MMA(1, 0, At, B0); PG8_MMA(1, 1, At, B1); PG8_BAR; PG8_SCHED;
	s_add_i32 s50, s54, s53
	v_lshl_add_u64 v[146:147], v[146:147], 0, s[18:19]
	s_mov_b32 m0, s50
	ds_read_b128 v[196:199], v157 offset:49152
	ds_read_b128 v[202:205], v157 offset:50176
	ds_read_b128 v[206:209], v157 offset:51200
	ds_read_b128 v[210:213], v157 offset:52224
	ds_read_b128 v[214:217], v157 offset:53248
	ds_read_b128 v[218:221], v157 offset:54272
	ds_read_b128 v[222:225], v157 offset:55296
	ds_read_b128 v[226:229], v157 offset:56320
	global_load_lds_dwordx4 v[146:147], off
	s_add_i32 m0, s50, 0x2000
	s_add_u32 s42, s42, 0x20080
	v_lshl_add_u64 v[146:147], v[230:231], 0, s[18:19]
	s_addc_u32 s43, s43, 0
	s_add_i32 s50, s55, s53
	global_load_lds_dwordx4 v[146:147], off
	v_lshl_add_u64 v[146:147], s[42:43], 0, v[130:131]
	s_mov_b32 m0, s50
	s_nop 0
	global_load_lds_dwordx4 v[146:147], off
	v_lshl_add_u64 v[146:147], s[42:43], 0, v[134:135]
	s_add_i32 m0, s50, 0x2000
	s_nop 0
	global_load_lds_dwordx4 v[146:147], off
	v_lshl_add_u64 v[146:147], v[232:233], 0, s[18:19]
	s_mov_b32 m0, s63
	s_nop 0
	global_load_lds_dwordx4 v[146:147], off
	v_lshl_add_u64 v[146:147], v[234:235], 0, s[18:19]
	s_mov_b32 m0, s64
	s_nop 0
	global_load_lds_dwordx4 v[146:147], off
	s_waitcnt vmcnt(8)
	s_waitcnt lgkmcnt(0)
	s_barrier
	s_setprio 1
	s_waitcnt lgkmcnt(0)
	v_mfma_f32_16x16x32_bf16 v[60:63], v[158:161], v[196:199], v[60:63]
	v_mfma_f32_16x16x32_bf16 v[56:59], v[166:169], v[196:199], v[56:59]
	v_mfma_f32_16x16x32_bf16 v[40:43], v[166:169], v[206:209], v[40:43]
	v_mfma_f32_16x16x32_bf16 v[44:47], v[158:161], v[206:209], v[44:47]
	v_mfma_f32_16x16x32_bf16 v[28:31], v[158:161], v[214:217], v[28:31]
	v_mfma_f32_16x16x32_bf16 v[24:27], v[166:169], v[214:217], v[24:27]
	v_mfma_f32_16x16x32_bf16 v[8:11], v[166:169], v[222:225], v[8:11]
	v_mfma_f32_16x16x32_bf16 v[12:15], v[158:161], v[222:225], v[12:15]
	v_mfma_f32_16x16x32_bf16 v[60:63], v[162:165], v[202:205], v[60:63]
	v_mfma_f32_16x16x32_bf16 v[56:59], v[176:179], v[202:205], v[56:59]
	v_mfma_f32_16x16x32_bf16 v[40:43], v[176:179], v[210:213], v[40:43]
	v_mfma_f32_16x16x32_bf16 v[44:47], v[162:165], v[210:213], v[44:47]
	v_mfma_f32_16x16x32_bf16 v[28:31], v[162:165], v[218:221], v[28:31]
	v_mfma_f32_16x16x32_bf16 v[24:27], v[176:179], v[218:221], v[24:27]
	v_mfma_f32_16x16x32_bf16 v[8:11], v[176:179], v[226:229], v[8:11]
	v_mfma_f32_16x16x32_bf16 v[12:15], v[162:165], v[226:229], v[12:15]
	s_setprio 0
	s_setprio 1
	v_mfma_f32_16x16x32_bf16 v[52:55], v[180:183], v[196:199], v[52:55]
	v_mfma_f32_16x16x32_bf16 v[48:51], v[188:191], v[196:199], v[48:51]
	v_mfma_f32_16x16x32_bf16 v[32:35], v[188:191], v[206:209], v[32:35]
	v_mfma_f32_16x16x32_bf16 v[36:39], v[180:183], v[206:209], v[36:39]
	v_mfma_f32_16x16x32_bf16 v[20:23], v[180:183], v[214:217], v[20:23]
	v_mfma_f32_16x16x32_bf16 v[16:19], v[188:191], v[214:217], v[16:19]
	v_mfma_f32_16x16x32_bf16 v[0:3], v[188:191], v[222:225], v[0:3]
	v_mfma_f32_16x16x32_bf16 v[4:7], v[180:183], v[222:225], v[4:7]
	v_mfma_f32_16x16x32_bf16 v[52:55], v[184:187], v[202:205], v[52:55]
	v_mfma_f32_16x16x32_bf16 v[48:51], v[192:195], v[202:205], v[48:51]
	v_mfma_f32_16x16x32_bf16 v[32:35], v[192:195], v[210:213], v[32:35]
	v_mfma_f32_16x16x32_bf16 v[36:39], v[184:187], v[210:213], v[36:39]
	v_mfma_f32_16x16x32_bf16 v[20:23], v[184:187], v[218:221], v[20:23]
	v_mfma_f32_16x16x32_bf16 v[16:19], v[192:195], v[218:221], v[16:19]
	v_mfma_f32_16x16x32_bf16 v[0:3], v[192:195], v[226:229], v[0:3]
	v_mfma_f32_16x16x32_bf16 v[4:7], v[184:187], v[226:229], v[4:7]
	s_setprio 0
	s_barrier
	s_add_i32 s49, s49, 2
	s_add_u32 s41, s41, 0x100
	s_addc_u32 s48, s48, 0
	s_add_u32 s38, s38, 0x100
	s_addc_u32 s39, s39, 0
	s_cmp_gt_u32 s49, 29
	s_cbranch_scc0 .LBB0_764
	s_and_b64 vcc, exec, s[24:25]
	s_cbranch_vccz .LBB0_767
	s_barrier

; #define PG8_STAGE(bufoff, gbase, voff) do { _Pragma("unroll") for (int _i = 0; _i < 2; ++_i) \
;         __builtin_amdgcn_global_load_lds((const unsigned*)((const char*)(gbase) + (voff)[_i]), (PG8_LAS unsigned*)(lds + (bufoff) + ldsw + _i * 8192), 16, 0, 0); } while (0)
; #define PG8_LDA(dst, b, h) do { _Pragma("unroll") for (int m = 0; m < 4; ++m) _Pragma("unroll") for (int k = 0; k < 2; ++k) dst[m][k] = *(const PG8_LAS bf16x8*)(lds + PG8_SA(b, h) + aoff + m * 2048 + k * 1024); } while (0)
; #define PG8_LDB(dst, b, h) do { _Pragma("unroll") for (int n = 0; n < 2; ++n) _Pragma("unroll") for (int k = 0; k < 2; ++k) dst[n][k] = *(const PG8_LAS bf16x8*)(lds + PG8_SB(b, h) + boff + n * 2048 + k * 1024); } while (0)
; #define PG8_MMA(ai, bj, At, Bt) do { __builtin_amdgcn_s_setprio(1); _Pragma("unroll") for (int m = 0; m < 4; ++m) _Pragma("unroll") for (int n = 0; n < 2; ++n) _Pragma("unroll") for (int k = 0; k < 2; ++k) \
;         acc[ai][bj][m][n] = __builtin_amdgcn_mfma_f32_16x16x32_bf16(Bt[n][k], At[m][k], acc[ai][bj][m][n], 0, 0, 0); __builtin_amdgcn_s_setprio(0); } while (0)
; #define PG8_WAIT_V(n) asm volatile("s_waitcnt vmcnt(" #n ")" ::: "memory")
; #define PG8_WAIT_L(n) asm volatile("s_waitcnt lgkmcnt(" #n ")" ::: "memory")
; template <class Epi, class Sched, bool ALIGN_EPI = false, bool SP2 = false>
; __device__ __forceinline__ void gemm_phase(PG8_LAS unsigned char* lds, const Gemm g, const Sched& S, const Epi& E) {
;     ...
;             const bool last = (t == nt - 2);
;             const char* a1 = cA + (size_t)(t + 1) * kstep;
;             const char* a2 = last ? nA : cA + (size_t)(t + 2) * kstep; const char* b2 = last ? nB : cB + (size_t)(t + 2) * kstep;
;             const char* a3 = a2 + kstep; const char* b3 = b2 + kstep;
;             if (last && has_next) S.a_ready(nxt);
;             if constexpr (SP2) {
;             PG8_LDB(B0, 0, 0); PG8_LDB(B1, 0, 1); PG8_SCHED; PG8_LDA(At, 0, 0); PG8_STAGE(PG8_SA(1, 1), a1 + hstep, voffA);
;             PG8_WAIT_V(8); PG8_WAIT_L(0); PG8_BAR; PG8_MMA(0, 0, At, B0); PG8_MMA(0, 1, At, B1); PG8_BAR; PG8_SCHED;
;             PG8_LDA(At, 0, 1); PG8_STAGE(PG8_SB(0, 0), b2, voffB); PG8_STAGE(PG8_SB(0, 1), b2 + hstepB, voffB); PG8_STAGE(PG8_SA(0, 0), a2, voffA);
;             PG8_WAIT_V(8); PG8_WAIT_L(0); PG8_BAR; PG8_MMA(1, 0, At, B0); PG8_MMA(1, 1, At, B1); PG8_BAR; PG8_SCHED;
.LBB0_820:
	ds_read_b128 v[158:161], v154
	ds_read_b128 v[162:165], v154 offset:1024
	ds_read_b128 v[166:169], v154 offset:2048
	ds_read_b128 v[176:179], v154 offset:3072
	ds_read_b128 v[180:183], v155
	ds_read_b128 v[184:187], v155 offset:1024
	ds_read_b128 v[188:191], v155 offset:2048
	ds_read_b128 v[192:195], v155 offset:3072
	s_add_u32 s36, s34, 0xfff80080
	s_addc_u32 s37, s35, -1
	s_cmp_eq_u32 s50, 28
	s_cselect_b32 s39, s25, s37
	s_cselect_b32 s38, s40, s36
	s_cselect_b32 s37, s17, s49
	s_cselect_b32 s36, s41, s48
	v_lshl_add_u64 v[146:147], s[34:35], 0, v[140:141]
	s_add_i32 m0, s31, 0xc000
	ds_read_b128 v[196:199], v156
	ds_read_b128 v[202:205], v156 offset:1024
	ds_read_b128 v[206:209], v156 offset:2048
	ds_read_b128 v[210:213], v156 offset:3072
	ds_read_b128 v[214:217], v156 offset:4096
	ds_read_b128 v[218:221], v156 offset:5120
	ds_read_b128 v[222:225], v156 offset:6144
	ds_read_b128 v[226:229], v156 offset:7168
	global_load_lds_dwordx4 v[146:147], off
	v_lshl_add_u64 v[146:147], s[34:35], 0, v[138:139]
	s_add_i32 m0, s31, 0xe000
	s_nop 0
	global_load_lds_dwordx4 v[146:147], off
	s_waitcnt vmcnt(8)
	s_waitcnt lgkmcnt(0)
	s_barrier
	s_setprio 1
	s_waitcnt lgkmcnt(0)
	v_mfma_f32_16x16x32_bf16 v[124:127], v[158:161], v[196:199], v[124:127]
	v_mfma_f32_16x16x32_bf16 v[120:123], v[166:169], v[196:199], v[120:123]
	v_mfma_f32_16x16x32_bf16 v[108:111], v[166:169], v[206:209], v[108:111]
	v_mfma_f32_16x16x32_bf16 v[116:119], v[158:161], v[206:209], v[116:119]
	v_mfma_f32_16x16x32_bf16 v[96:99], v[158:161], v[214:217], v[96:99]
	v_mfma_f32_16x16x32_bf16 v[88:91], v[166:169], v[214:217], v[88:91]
	v_mfma_f32_16x16x32_bf16 v[72:75], v[166:169], v[222:225], v[72:75]
	v_mfma_f32_16x16x32_bf16 v[80:83], v[158:161], v[222:225], v[80:83]
	v_mfma_f32_16x16x32_bf16 v[124:127], v[162:165], v[202:205], v[124:127]
	v_mfma_f32_16x16x32_bf16 v[120:123], v[176:179], v[202:205], v[120:123]
	v_mfma_f32_16x16x32_bf16 v[108:111], v[176:179], v[210:213], v[108:111]
	v_mfma_f32_16x16x32_bf16 v[116:119], v[162:165], v[210:213], v[116:119]
	v_mfma_f32_16x16x32_bf16 v[96:99], v[162:165], v[218:221], v[96:99]
	v_mfma_f32_16x16x32_bf16 v[88:91], v[176:179], v[218:221], v[88:91]
	v_mfma_f32_16x16x32_bf16 v[72:75], v[176:179], v[226:229], v[72:75]
	v_mfma_f32_16x16x32_bf16 v[80:83], v[162:165], v[226:229], v[80:83]
	s_setprio 0
	s_setprio 1
	v_mfma_f32_16x16x32_bf16 v[112:115], v[180:183], v[196:199], v[112:115]
	v_mfma_f32_16x16x32_bf16 v[104:107], v[188:191], v[196:199], v[104:107]
	v_mfma_f32_16x16x32_bf16 v[92:95], v[188:191], v[206:209], v[92:95]
	v_mfma_f32_16x16x32_bf16 v[100:103], v[180:183], v[206:209], v[100:103]
	v_mfma_f32_16x16x32_bf16 v[84:87], v[180:183], v[214:217], v[84:87]
	v_mfma_f32_16x16x32_bf16 v[76:79], v[188:191], v[214:217], v[76:79]
	v_mfma_f32_16x16x32_bf16 v[64:67], v[188:191], v[222:225], v[64:67]
	v_mfma_f32_16x16x32_bf16 v[68:71], v[180:183], v[222:225], v[68:71]
	v_mfma_f32_16x16x32_bf16 v[112:115], v[184:187], v[202:205], v[112:115]
	v_mfma_f32_16x16x32_bf16 v[104:107], v[192:195], v[202:205], v[104:107]
	v_mfma_f32_16x16x32_bf16 v[92:95], v[192:195], v[210:213], v[92:95]
	v_mfma_f32_16x16x32_bf16 v[100:103], v[184:187], v[210:213], v[100:103]
	v_mfma_f32_16x16x32_bf16 v[84:87], v[184:187], v[218:221], v[84:87]
	v_mfma_f32_16x16x32_bf16 v[76:79], v[192:195], v[218:221], v[76:79]
	v_mfma_f32_16x16x32_bf16 v[64:67], v[192:195], v[226:229], v[64:67]
	v_mfma_f32_16x16x32_bf16 v[68:71], v[184:187], v[226:229], v[68:71]
	s_setprio 0
	s_barrier
	s_add_i32 s51, s66, s43
	v_lshl_add_u64 v[146:147], s[36:37], 0, v[130:131]
	s_mov_b32 m0, s51
	ds_read_b128 v[196:199], v156 offset:16384
	ds_read_b128 v[202:205], v156 offset:17408
	ds_read_b128 v[206:209], v156 offset:18432
	ds_read_b128 v[210:213], v156 offset:19456
	ds_read_b128 v[214:217], v156 offset:20480
	ds_read_b128 v[218:221], v156 offset:21504
	ds_read_b128 v[222:225], v156 offset:22528
	ds_read_b128 v[226:229], v156 offset:23552
	global_load_lds_dwordx4 v[146:147], off
	s_add_i32 m0, s51, 0x2000
	s_add_u32 s54, s36, 0x20000
	v_lshl_add_u64 v[230:231], s[36:37], 0, v[134:135]
	s_addc_u32 s55, s37, 0
	s_add_i32 s51, s67, s43
	global_load_lds_dwordx4 v[230:231], off
	v_lshl_add_u64 v[232:233], s[54:55], 0, v[130:131]
	s_mov_b32 m0, s51
	v_lshl_add_u64 v[234:235], s[38:39], 0, v[132:133]
	global_load_lds_dwordx4 v[232:233], off
	v_lshl_add_u64 v[232:233], s[54:55], 0, v[134:135]
	s_add_i32 m0, s51, 0x2000
	s_nop 0
	global_load_lds_dwordx4 v[232:233], off
	v_lshl_add_u64 v[232:233], s[38:39], 0, v[128:129]
	s_mov_b32 m0, s31
	s_nop 0
	global_load_lds_dwordx4 v[232:233], off
	s_mov_b32 m0, s59
	s_nop 0
	global_load_lds_dwordx4 v[234:235], off
	s_waitcnt vmcnt(8)
	s_waitcnt lgkmcnt(0)
	s_barrier
; #define PG8_STAGE(bufoff, gbase, voff) do { _Pragma("unroll") for (int _i = 0; _i < 2; ++_i) \
;         __builtin_amdgcn_global_load_lds((const unsigned*)((const char*)(gbase) + (voff)[_i]), (PG8_LAS unsigned*)(lds + (bufoff) + ldsw + _i * 8192), 16, 0, 0); } while (0)
; #define PG8_LDA(dst, b, h) do { _Pragma("unroll") for (int m = 0; m < 4; ++m) _Pragma("unroll") for (int k = 0; k < 2; ++k) dst[m][k] = *(const PG8_LAS bf16x8*)(lds + PG8_SA(b, h) + aoff + m * 2048 + k * 1024); } while (0)
; #define PG8_LDB(dst, b, h) do { _Pragma("unroll") for (int n = 0; n < 2; ++n) _Pragma("unroll") for (int k = 0; k < 2; ++k) dst[n][k] = *(const PG8_LAS bf16x8*)(lds + PG8_SB(b, h) + boff + n * 2048 + k * 1024); } while (0)
; #define PG8_MMA(ai, bj, At, Bt) do { __builtin_amdgcn_s_setprio(1); _Pragma("unroll") for (int m = 0; m < 4; ++m) _Pragma("unroll") for (int n = 0; n < 2; ++n) _Pragma("unroll") for (int k = 0; k < 2; ++k) \
;         acc[ai][bj][m][n] = __builtin_amdgcn_mfma_f32_16x16x32_bf16(Bt[n][k], At[m][k], acc[ai][bj][m][n], 0, 0, 0); __builtin_amdgcn_s_setprio(0); } while (0)
; #define PG8_WAIT_V(n) asm volatile("s_waitcnt vmcnt(" #n ")" ::: "memory")
; #define PG8_WAIT_L(n) asm volatile("s_waitcnt lgkmcnt(" #n ")" ::: "memory")
; #define PG8_BAR __builtin_amdgcn_s_barrier()
; #define PG8_SCHED __builtin_amdgcn_sched_barrier(0)
; template <class Epi, class Sched, bool ALIGN_EPI = false, bool SP2 = false>
; __device__ __forceinline__ void gemm_phase(PG8_LAS unsigned char* lds, const Gemm g, const Sched& S, const Epi& E) {
;     ...
;             PG8_WAIT_V(8); PG8_WAIT_L(0); PG8_BAR; PG8_MMA(1, 0, At, B0); PG8_MMA(1, 1, At, B1); PG8_BAR; PG8_SCHED;
;             PG8_LDB(B0, 1, 0); PG8_LDB(B1, 1, 1); PG8_SCHED; PG8_LDA(At, 1, 0); PG8_STAGE(PG8_SA(0, 1), a2 + hstep, voffA);
;             PG8_WAIT_V(8); PG8_WAIT_L(0); PG8_BAR; PG8_MMA(0, 0, At, B0); PG8_MMA(0, 1, At, B1); PG8_BAR; PG8_SCHED;
	s_setprio 1
	s_waitcnt lgkmcnt(0)
	v_mfma_f32_16x16x32_bf16 v[60:63], v[158:161], v[196:199], v[60:63]
	v_mfma_f32_16x16x32_bf16 v[56:59], v[166:169], v[196:199], v[56:59]
	v_mfma_f32_16x16x32_bf16 v[40:43], v[166:169], v[206:209], v[40:43]
	v_mfma_f32_16x16x32_bf16 v[48:51], v[158:161], v[206:209], v[48:51]
	v_mfma_f32_16x16x32_bf16 v[32:35], v[158:161], v[214:217], v[32:35]
	v_mfma_f32_16x16x32_bf16 v[24:27], v[166:169], v[214:217], v[24:27]
	v_mfma_f32_16x16x32_bf16 v[8:11], v[166:169], v[222:225], v[8:11]
	v_mfma_f32_16x16x32_bf16 v[16:19], v[158:161], v[222:225], v[16:19]
	v_mfma_f32_16x16x32_bf16 v[60:63], v[162:165], v[202:205], v[60:63]
	v_mfma_f32_16x16x32_bf16 v[56:59], v[176:179], v[202:205], v[56:59]
	v_mfma_f32_16x16x32_bf16 v[40:43], v[176:179], v[210:213], v[40:43]
	v_mfma_f32_16x16x32_bf16 v[48:51], v[162:165], v[210:213], v[48:51]
	v_mfma_f32_16x16x32_bf16 v[32:35], v[162:165], v[218:221], v[32:35]
	v_mfma_f32_16x16x32_bf16 v[24:27], v[176:179], v[218:221], v[24:27]
	v_mfma_f32_16x16x32_bf16 v[8:11], v[176:179], v[226:229], v[8:11]
	v_mfma_f32_16x16x32_bf16 v[16:19], v[162:165], v[226:229], v[16:19]
	s_setprio 0
	s_setprio 1
	v_mfma_f32_16x16x32_bf16 v[52:55], v[180:183], v[196:199], v[52:55]
	v_mfma_f32_16x16x32_bf16 v[44:47], v[188:191], v[196:199], v[44:47]
	v_mfma_f32_16x16x32_bf16 v[28:31], v[188:191], v[206:209], v[28:31]
	v_mfma_f32_16x16x32_bf16 v[36:39], v[180:183], v[206:209], v[36:39]
	v_mfma_f32_16x16x32_bf16 v[20:23], v[180:183], v[214:217], v[20:23]
	v_mfma_f32_16x16x32_bf16 v[12:15], v[188:191], v[214:217], v[12:15]
	v_mfma_f32_16x16x32_bf16 v[0:3], v[188:191], v[222:225], v[0:3]
	v_mfma_f32_16x16x32_bf16 v[4:7], v[180:183], v[222:225], v[4:7]
	v_mfma_f32_16x16x32_bf16 v[52:55], v[184:187], v[202:205], v[52:55]
	v_mfma_f32_16x16x32_bf16 v[44:47], v[192:195], v[202:205], v[44:47]
	v_mfma_f32_16x16x32_bf16 v[28:31], v[192:195], v[210:213], v[28:31]
	v_mfma_f32_16x16x32_bf16 v[36:39], v[184:187], v[210:213], v[36:39]
	v_mfma_f32_16x16x32_bf16 v[20:23], v[184:187], v[218:221], v[20:23]
	v_mfma_f32_16x16x32_bf16 v[12:15], v[192:195], v[218:221], v[12:15]
	v_mfma_f32_16x16x32_bf16 v[0:3], v[192:195], v[226:229], v[0:3]
	v_mfma_f32_16x16x32_bf16 v[4:7], v[184:187], v[226:229], v[4:7]
	s_setprio 0
	s_barrier
	s_add_i32 s51, 0, 0x18000
	v_add_u32_e32 v157, s51, v150
	s_add_i32 s54, 0, 0x1c000
	ds_read_b128 v[158:161], v157
	ds_read_b128 v[162:165], v157 offset:1024
	ds_read_b128 v[166:169], v157 offset:2048
	ds_read_b128 v[176:179], v157 offset:3072
	v_add_u32_e32 v157, s54, v150
	ds_read_b128 v[180:183], v157
	ds_read_b128 v[184:187], v157 offset:1024
	ds_read_b128 v[188:191], v157 offset:2048
	ds_read_b128 v[192:195], v157 offset:3072
	s_add_u32 s38, s38, 0x80000
	s_addc_u32 s39, s39, 0
	s_mov_b32 m0, s60
	v_lshl_add_u64 v[236:237], s[38:39], 0, v[128:129]
	ds_read_b128 v[196:199], v156 offset:32768
	ds_read_b128 v[202:205], v156 offset:33792
	ds_read_b128 v[206:209], v156 offset:34816
	ds_read_b128 v[210:213], v156 offset:35840
	ds_read_b128 v[214:217], v156 offset:36864
	ds_read_b128 v[218:221], v156 offset:37888
	ds_read_b128 v[222:225], v156 offset:38912
	ds_read_b128 v[226:229], v156 offset:39936
	global_load_lds_dwordx4 v[236:237], off
	v_lshl_add_u64 v[236:237], s[38:39], 0, v[132:133]
	s_mov_b32 m0, s61
	s_nop 0
	global_load_lds_dwordx4 v[236:237], off
	s_waitcnt vmcnt(8)
	s_waitcnt lgkmcnt(0)
	s_barrier
	s_setprio 1
	s_waitcnt lgkmcnt(0)
	v_mfma_f32_16x16x32_bf16 v[124:127], v[158:161], v[196:199], v[124:127]
	v_mfma_f32_16x16x32_bf16 v[120:123], v[166:169], v[196:199], v[120:123]
	v_mfma_f32_16x16x32_bf16 v[108:111], v[166:169], v[206:209], v[108:111]
	v_mfma_f32_16x16x32_bf16 v[116:119], v[158:161], v[206:209], v[116:119]
	v_mfma_f32_16x16x32_bf16 v[96:99], v[158:161], v[214:217], v[96:99]
	v_mfma_f32_16x16x32_bf16 v[88:91], v[166:169], v[214:217], v[88:91]
	v_mfma_f32_16x16x32_bf16 v[72:75], v[166:169], v[222:225], v[72:75]
	v_mfma_f32_16x16x32_bf16 v[80:83], v[158:161], v[222:225], v[80:83]
	v_mfma_f32_16x16x32_bf16 v[124:127], v[162:165], v[202:205], v[124:127]
	v_mfma_f32_16x16x32_bf16 v[120:123], v[176:179], v[202:205], v[120:123]
	v_mfma_f32_16x16x32_bf16 v[108:111], v[176:179], v[210:213], v[108:111]
	v_mfma_f32_16x16x32_bf16 v[116:119], v[162:165], v[210:213], v[116:119]
	v_mfma_f32_16x16x32_bf16 v[96:99], v[162:165], v[218:221], v[96:99]
	v_mfma_f32_16x16x32_bf16 v[88:91], v[176:179], v[218:221], v[88:91]
	v_mfma_f32_16x16x32_bf16 v[72:75], v[176:179], v[226:229], v[72:75]
	v_mfma_f32_16x16x32_bf16 v[80:83], v[162:165], v[226:229], v[80:83]
	s_setprio 0
	s_setprio 1
	v_mfma_f32_16x16x32_bf16 v[112:115], v[180:183], v[196:199], v[112:115]
	v_mfma_f32_16x16x32_bf16 v[104:107], v[188:191], v[196:199], v[104:107]
	v_mfma_f32_16x16x32_bf16 v[92:95], v[188:191], v[206:209], v[92:95]
	v_mfma_f32_16x16x32_bf16 v[100:103], v[180:183], v[206:209], v[100:103]
	v_mfma_f32_16x16x32_bf16 v[84:87], v[180:183], v[214:217], v[84:87]
	v_mfma_f32_16x16x32_bf16 v[76:79], v[188:191], v[214:217], v[76:79]
	v_mfma_f32_16x16x32_bf16 v[64:67], v[188:191], v[222:225], v[64:67]
	v_mfma_f32_16x16x32_bf16 v[68:71], v[180:183], v[222:225], v[68:71]
	v_mfma_f32_16x16x32_bf16 v[112:115], v[184:187], v[202:205], v[112:115]
	v_mfma_f32_16x16x32_bf16 v[104:107], v[192:195], v[202:205], v[104:107]
	v_mfma_f32_16x16x32_bf16 v[92:95], v[192:195], v[210:213], v[92:95]
	v_mfma_f32_16x16x32_bf16 v[100:103], v[184:187], v[210:213], v[100:103]
	v_mfma_f32_16x16x32_bf16 v[84:87], v[184:187], v[218:221], v[84:87]
	v_mfma_f32_16x16x32_bf16 v[76:79], v[192:195], v[218:221], v[76:79]
	v_mfma_f32_16x16x32_bf16 v[64:67], v[192:195], v[226:229], v[64:67]
	v_mfma_f32_16x16x32_bf16 v[68:71], v[184:187], v[226:229], v[68:71]
	s_setprio 0
	s_barrier
; #define PG8_STAGE(bufoff, gbase, voff) do { _Pragma("unroll") for (int _i = 0; _i < 2; ++_i) \
;         __builtin_amdgcn_global_load_lds((const unsigned*)((const char*)(gbase) + (voff)[_i]), (PG8_LAS unsigned*)(lds + (bufoff) + ldsw + _i * 8192), 16, 0, 0); } while (0)
; #define PG8_LDA(dst, b, h) do { _Pragma("unroll") for (int m = 0; m < 4; ++m) _Pragma("unroll") for (int k = 0; k < 2; ++k) dst[m][k] = *(const PG8_LAS bf16x8*)(lds + PG8_SA(b, h) + aoff + m * 2048 + k * 1024); } while (0)
; #define PG8_MMA(ai, bj, At, Bt) do { __builtin_amdgcn_s_setprio(1); _Pragma("unroll") for (int m = 0; m < 4; ++m) _Pragma("unroll") for (int n = 0; n < 2; ++n) _Pragma("unroll") for (int k = 0; k < 2; ++k) \
;         acc[ai][bj][m][n] = __builtin_amdgcn_mfma_f32_16x16x32_bf16(Bt[n][k], At[m][k], acc[ai][bj][m][n], 0, 0, 0); __builtin_amdgcn_s_setprio(0); } while (0)
; #define PG8_WAIT_V(n) asm volatile("s_waitcnt vmcnt(" #n ")" ::: "memory")
; #define PG8_WAIT_L(n) asm volatile("s_waitcnt lgkmcnt(" #n ")" ::: "memory")
; #define PG8_BAR __builtin_amdgcn_s_barrier()
; #define PG8_SCHED __builtin_amdgcn_sched_barrier(0)
; template <class Epi, class Sched, bool ALIGN_EPI = false, bool SP2 = false>
; __device__ __forceinline__ void gemm_phase(PG8_LAS unsigned char* lds, const Gemm g, const Sched& S, const Epi& E) {
;     ...
;             PG8_LDA(At, 1, 1); PG8_STAGE(PG8_SB(1, 0), b3, voffB); PG8_STAGE(PG8_SB(1, 1), b3 + hstepB, voffB); PG8_STAGE(PG8_SA(1, 0), a3, voffA);
;             PG8_WAIT_V(8); PG8_WAIT_L(0); PG8_BAR; PG8_MMA(1, 0, At, B0); PG8_MMA(1, 1, At, B1); PG8_BAR; PG8_SCHED;
	s_add_i32 s38, s51, s43
	v_lshl_add_u64 v[146:147], v[146:147], 0, s[12:13]
	s_mov_b32 m0, s38
	ds_read_b128 v[196:199], v156 offset:49152
	ds_read_b128 v[202:205], v156 offset:50176
	ds_read_b128 v[206:209], v156 offset:51200
	ds_read_b128 v[210:213], v156 offset:52224
	ds_read_b128 v[214:217], v156 offset:53248
	ds_read_b128 v[218:221], v156 offset:54272
	ds_read_b128 v[222:225], v156 offset:55296
	ds_read_b128 v[226:229], v156 offset:56320
	global_load_lds_dwordx4 v[146:147], off
	s_add_i32 m0, s38, 0x2000
	s_add_u32 s36, s36, 0x20080
	v_lshl_add_u64 v[146:147], v[230:231], 0, s[12:13]
	s_addc_u32 s37, s37, 0
	s_add_i32 s38, s54, s43
	global_load_lds_dwordx4 v[146:147], off
	v_lshl_add_u64 v[146:147], s[36:37], 0, v[130:131]
	s_mov_b32 m0, s38
	s_nop 0
	global_load_lds_dwordx4 v[146:147], off
	v_lshl_add_u64 v[146:147], s[36:37], 0, v[134:135]
	s_add_i32 m0, s38, 0x2000
	s_nop 0
	global_load_lds_dwordx4 v[146:147], off
	v_lshl_add_u64 v[146:147], v[232:233], 0, s[12:13]
	s_mov_b32 m0, s62
	s_nop 0
	global_load_lds_dwordx4 v[146:147], off
	v_lshl_add_u64 v[146:147], v[234:235], 0, s[12:13]
	s_mov_b32 m0, s63
	s_nop 0
	global_load_lds_dwordx4 v[146:147], off
	s_waitcnt vmcnt(8)
	s_waitcnt lgkmcnt(0)
	s_barrier
	s_setprio 1
	s_waitcnt lgkmcnt(0)
	v_mfma_f32_16x16x32_bf16 v[60:63], v[158:161], v[196:199], v[60:63]
	v_mfma_f32_16x16x32_bf16 v[56:59], v[166:169], v[196:199], v[56:59]
	v_mfma_f32_16x16x32_bf16 v[40:43], v[166:169], v[206:209], v[40:43]
	v_mfma_f32_16x16x32_bf16 v[48:51], v[158:161], v[206:209], v[48:51]
	v_mfma_f32_16x16x32_bf16 v[32:35], v[158:161], v[214:217], v[32:35]
	v_mfma_f32_16x16x32_bf16 v[24:27], v[166:169], v[214:217], v[24:27]
	v_mfma_f32_16x16x32_bf16 v[8:11], v[166:169], v[222:225], v[8:11]
	v_mfma_f32_16x16x32_bf16 v[16:19], v[158:161], v[222:225], v[16:19]
	v_mfma_f32_16x16x32_bf16 v[60:63], v[162:165], v[202:205], v[60:63]
	v_mfma_f32_16x16x32_bf16 v[56:59], v[176:179], v[202:205], v[56:59]
	v_mfma_f32_16x16x32_bf16 v[40:43], v[176:179], v[210:213], v[40:43]
	v_mfma_f32_16x16x32_bf16 v[48:51], v[162:165], v[210:213], v[48:51]
	v_mfma_f32_16x16x32_bf16 v[32:35], v[162:165], v[218:221], v[32:35]
	v_mfma_f32_16x16x32_bf16 v[24:27], v[176:179], v[218:221], v[24:27]
	v_mfma_f32_16x16x32_bf16 v[8:11], v[176:179], v[226:229], v[8:11]
	v_mfma_f32_16x16x32_bf16 v[16:19], v[162:165], v[226:229], v[16:19]
	s_setprio 0
	s_setprio 1
	v_mfma_f32_16x16x32_bf16 v[52:55], v[180:183], v[196:199], v[52:55]
	v_mfma_f32_16x16x32_bf16 v[44:47], v[188:191], v[196:199], v[44:47]
	v_mfma_f32_16x16x32_bf16 v[28:31], v[188:191], v[206:209], v[28:31]
	v_mfma_f32_16x16x32_bf16 v[36:39], v[180:183], v[206:209], v[36:39]
	v_mfma_f32_16x16x32_bf16 v[20:23], v[180:183], v[214:217], v[20:23]
	v_mfma_f32_16x16x32_bf16 v[12:15], v[188:191], v[214:217], v[12:15]
	v_mfma_f32_16x16x32_bf16 v[0:3], v[188:191], v[222:225], v[0:3]
	v_mfma_f32_16x16x32_bf16 v[4:7], v[180:183], v[222:225], v[4:7]
	v_mfma_f32_16x16x32_bf16 v[52:55], v[184:187], v[202:205], v[52:55]
	v_mfma_f32_16x16x32_bf16 v[44:47], v[192:195], v[202:205], v[44:47]
	v_mfma_f32_16x16x32_bf16 v[28:31], v[192:195], v[210:213], v[28:31]
	v_mfma_f32_16x16x32_bf16 v[36:39], v[184:187], v[210:213], v[36:39]
	v_mfma_f32_16x16x32_bf16 v[20:23], v[184:187], v[218:221], v[20:23]
	v_mfma_f32_16x16x32_bf16 v[12:15], v[192:195], v[218:221], v[12:15]
	v_mfma_f32_16x16x32_bf16 v[0:3], v[192:195], v[226:229], v[0:3]
	v_mfma_f32_16x16x32_bf16 v[4:7], v[184:187], v[226:229], v[4:7]
	s_setprio 0
	s_barrier
	s_add_i32 s50, s50, 2
	s_add_u32 s48, s48, 0x100
	s_addc_u32 s49, s49, 0
	s_add_u32 s34, s34, 0x100
	s_addc_u32 s35, s35, 0
	s_cmp_gt_u32 s50, 29
	s_cbranch_scc0 .LBB0_820
	s_and_b64 vcc, exec, s[14:15]
	s_cbranch_vccz .LBB0_823
	s_barrier

; #define PG8_STAGE(bufoff, gbase, voff) do { _Pragma("unroll") for (int _i = 0; _i < 2; ++_i) \
;         __builtin_amdgcn_global_load_lds((const unsigned*)((const char*)(gbase) + (voff)[_i]), (PG8_LAS unsigned*)(lds + (bufoff) + ldsw + _i * 8192), 16, 0, 0); } while (0)
; #define PG8_LDA(dst, b, h) do { _Pragma("unroll") for (int m = 0; m < 4; ++m) _Pragma("unroll") for (int k = 0; k < 2; ++k) dst[m][k] = *(const PG8_LAS bf16x8*)(lds + PG8_SA(b, h) + aoff + m * 2048 + k * 1024); } while (0)
; #define PG8_LDB(dst, b, h) do { _Pragma("unroll") for (int n = 0; n < 2; ++n) _Pragma("unroll") for (int k = 0; k < 2; ++k) dst[n][k] = *(const PG8_LAS bf16x8*)(lds + PG8_SB(b, h) + boff + n * 2048 + k * 1024); } while (0)
; #define PG8_MMA(ai, bj, At, Bt) do { __builtin_amdgcn_s_setprio(1); _Pragma("unroll") for (int m = 0; m < 4; ++m) _Pragma("unroll") for (int n = 0; n < 2; ++n) _Pragma("unroll") for (int k = 0; k < 2; ++k) \
;         acc[ai][bj][m][n] = __builtin_amdgcn_mfma_f32_16x16x32_bf16(Bt[n][k], At[m][k], acc[ai][bj][m][n], 0, 0, 0); __builtin_amdgcn_s_setprio(0); } while (0)
; #define PG8_WAIT_V(n) asm volatile("s_waitcnt vmcnt(" #n ")" ::: "memory")
; #define PG8_WAIT_L(n) asm volatile("s_waitcnt lgkmcnt(" #n ")" ::: "memory")
; template <class Epi, class Sched, bool ALIGN_EPI = false, bool SP2 = false>
; __device__ __forceinline__ void gemm_phase(PG8_LAS unsigned char* lds, const Gemm g, const Sched& S, const Epi& E) {
;     ...
;             const bool last = (t == nt - 2);
;             const char* a1 = cA + (size_t)(t + 1) * kstep;
;             const char* a2 = last ? nA : cA + (size_t)(t + 2) * kstep; const char* b2 = last ? nB : cB + (size_t)(t + 2) * kstep;
;             const char* a3 = a2 + kstep; const char* b3 = b2 + kstep;
;             if (last && has_next) S.a_ready(nxt);
;             if constexpr (SP2) {
;             PG8_LDB(B0, 0, 0); PG8_LDB(B1, 0, 1); PG8_SCHED; PG8_LDA(At, 0, 0); PG8_STAGE(PG8_SA(1, 1), a1 + hstep, voffA);
;             PG8_WAIT_V(8); PG8_WAIT_L(0); PG8_BAR; PG8_MMA(0, 0, At, B0); PG8_MMA(0, 1, At, B1); PG8_BAR; PG8_SCHED;
;             PG8_LDA(At, 0, 1); PG8_STAGE(PG8_SB(0, 0), b2, voffB); PG8_STAGE(PG8_SB(0, 1), b2 + hstepB, voffB); PG8_STAGE(PG8_SA(0, 0), a2, voffA);
;             PG8_WAIT_V(8); PG8_WAIT_L(0); PG8_BAR; PG8_MMA(1, 0, At, B0); PG8_MMA(1, 1, At, B1); PG8_BAR; PG8_SCHED;
.LBB0_956:
	ds_read_b128 v[154:157], v163
	ds_read_b128 v[166:169], v163 offset:1024
	ds_read_b128 v[176:179], v163 offset:2048
	ds_read_b128 v[180:183], v163 offset:3072
	ds_read_b128 v[184:187], v164
	ds_read_b128 v[188:191], v164 offset:1024
	ds_read_b128 v[192:195], v164 offset:2048
	ds_read_b128 v[196:199], v164 offset:3072
	s_add_u32 s36, s34, 0xfffe0080
	s_addc_u32 s37, s35, -1
	s_cmp_eq_u32 s49, 4
	s_cselect_b32 s39, s7, s37
	s_cselect_b32 s38, s25, s36
	s_cselect_b32 s37, s23, s48
	s_cselect_b32 s36, s40, s41
	v_lshl_add_u64 v[234:235], s[34:35], 0, v[148:149]
	s_add_i32 m0, s31, 0xc000
	ds_read_b128 v[202:205], v165
	ds_read_b128 v[206:209], v165 offset:1024
	ds_read_b128 v[210:213], v165 offset:2048
	ds_read_b128 v[214:217], v165 offset:3072
	ds_read_b128 v[218:221], v165 offset:4096
	ds_read_b128 v[222:225], v165 offset:5120
	ds_read_b128 v[226:229], v165 offset:6144
	ds_read_b128 v[230:233], v165 offset:7168
	global_load_lds_dwordx4 v[234:235], off
	v_lshl_add_u64 v[234:235], s[34:35], 0, v[146:147]
	s_add_i32 m0, s31, 0xe000
	s_nop 0
	global_load_lds_dwordx4 v[234:235], off
	s_waitcnt vmcnt(8)
	s_waitcnt lgkmcnt(0)
	s_barrier
	s_setprio 1
	s_waitcnt lgkmcnt(0)
	v_mfma_f32_16x16x32_bf16 v[124:127], v[154:157], v[202:205], v[124:127]
	v_mfma_f32_16x16x32_bf16 v[120:123], v[176:179], v[202:205], v[120:123]
	v_mfma_f32_16x16x32_bf16 v[104:107], v[176:179], v[210:213], v[104:107]
	v_mfma_f32_16x16x32_bf16 v[108:111], v[154:157], v[210:213], v[108:111]
	v_mfma_f32_16x16x32_bf16 v[92:95], v[154:157], v[218:221], v[92:95]
	v_mfma_f32_16x16x32_bf16 v[88:91], v[176:179], v[218:221], v[88:91]
	v_mfma_f32_16x16x32_bf16 v[72:75], v[176:179], v[226:229], v[72:75]
	v_mfma_f32_16x16x32_bf16 v[76:79], v[154:157], v[226:229], v[76:79]
	v_mfma_f32_16x16x32_bf16 v[124:127], v[166:169], v[206:209], v[124:127]
	v_mfma_f32_16x16x32_bf16 v[120:123], v[180:183], v[206:209], v[120:123]
	v_mfma_f32_16x16x32_bf16 v[104:107], v[180:183], v[214:217], v[104:107]
	v_mfma_f32_16x16x32_bf16 v[108:111], v[166:169], v[214:217], v[108:111]
	v_mfma_f32_16x16x32_bf16 v[92:95], v[166:169], v[222:225], v[92:95]
	v_mfma_f32_16x16x32_bf16 v[88:91], v[180:183], v[222:225], v[88:91]
	v_mfma_f32_16x16x32_bf16 v[72:75], v[180:183], v[230:233], v[72:75]
	v_mfma_f32_16x16x32_bf16 v[76:79], v[166:169], v[230:233], v[76:79]
	s_setprio 0
	s_setprio 1
	v_mfma_f32_16x16x32_bf16 v[116:119], v[184:187], v[202:205], v[116:119]
	v_mfma_f32_16x16x32_bf16 v[112:115], v[192:195], v[202:205], v[112:115]
	v_mfma_f32_16x16x32_bf16 v[96:99], v[192:195], v[210:213], v[96:99]
	v_mfma_f32_16x16x32_bf16 v[100:103], v[184:187], v[210:213], v[100:103]
	v_mfma_f32_16x16x32_bf16 v[84:87], v[184:187], v[218:221], v[84:87]
	v_mfma_f32_16x16x32_bf16 v[80:83], v[192:195], v[218:221], v[80:83]
	v_mfma_f32_16x16x32_bf16 v[64:67], v[192:195], v[226:229], v[64:67]
	v_mfma_f32_16x16x32_bf16 v[68:71], v[184:187], v[226:229], v[68:71]
	v_mfma_f32_16x16x32_bf16 v[116:119], v[188:191], v[206:209], v[116:119]
	v_mfma_f32_16x16x32_bf16 v[112:115], v[196:199], v[206:209], v[112:115]
	v_mfma_f32_16x16x32_bf16 v[96:99], v[196:199], v[214:217], v[96:99]
	v_mfma_f32_16x16x32_bf16 v[100:103], v[188:191], v[214:217], v[100:103]
	v_mfma_f32_16x16x32_bf16 v[84:87], v[188:191], v[222:225], v[84:87]
	v_mfma_f32_16x16x32_bf16 v[80:83], v[196:199], v[222:225], v[80:83]
	v_mfma_f32_16x16x32_bf16 v[64:67], v[196:199], v[230:233], v[64:67]
	v_mfma_f32_16x16x32_bf16 v[68:71], v[188:191], v[230:233], v[68:71]
	s_setprio 0
	s_barrier
	s_add_i32 s50, s69, s58
	v_lshl_add_u64 v[234:235], s[36:37], 0, v[130:131]
	s_mov_b32 m0, s50
	ds_read_b128 v[202:205], v165 offset:16384
	ds_read_b128 v[206:209], v165 offset:17408
	ds_read_b128 v[210:213], v165 offset:18432
	ds_read_b128 v[214:217], v165 offset:19456
	ds_read_b128 v[218:221], v165 offset:20480
	ds_read_b128 v[222:225], v165 offset:21504
	ds_read_b128 v[226:229], v165 offset:22528
	ds_read_b128 v[230:233], v165 offset:23552
	global_load_lds_dwordx4 v[234:235], off
	s_add_i32 m0, s50, 0x2000
	s_add_u32 s50, s36, 0x8000
	v_lshl_add_u64 v[236:237], s[36:37], 0, v[134:135]
	s_addc_u32 s51, s37, 0
	s_add_i32 s54, s70, s58
	global_load_lds_dwordx4 v[236:237], off
	v_lshl_add_u64 v[238:239], s[50:51], 0, v[130:131]
	s_mov_b32 m0, s54
	v_lshl_add_u64 v[240:241], s[38:39], 0, v[132:133]
	global_load_lds_dwordx4 v[238:239], off
	v_lshl_add_u64 v[238:239], s[50:51], 0, v[134:135]
	s_add_i32 m0, s54, 0x2000
	s_nop 0
	global_load_lds_dwordx4 v[238:239], off
	v_lshl_add_u64 v[238:239], s[38:39], 0, v[128:129]
	s_mov_b32 m0, s31
	s_nop 0
	global_load_lds_dwordx4 v[238:239], off
	s_mov_b32 m0, s59
	s_nop 0
	global_load_lds_dwordx4 v[240:241], off
	s_waitcnt vmcnt(8)
	s_waitcnt lgkmcnt(0)
	s_barrier
; #define PG8_STAGE(bufoff, gbase, voff) do { _Pragma("unroll") for (int _i = 0; _i < 2; ++_i) \
;         __builtin_amdgcn_global_load_lds((const unsigned*)((const char*)(gbase) + (voff)[_i]), (PG8_LAS unsigned*)(lds + (bufoff) + ldsw + _i * 8192), 16, 0, 0); } while (0)
; #define PG8_LDA(dst, b, h) do { _Pragma("unroll") for (int m = 0; m < 4; ++m) _Pragma("unroll") for (int k = 0; k < 2; ++k) dst[m][k] = *(const PG8_LAS bf16x8*)(lds + PG8_SA(b, h) + aoff + m * 2048 + k * 1024); } while (0)
; #define PG8_LDB(dst, b, h) do { _Pragma("unroll") for (int n = 0; n < 2; ++n) _Pragma("unroll") for (int k = 0; k < 2; ++k) dst[n][k] = *(const PG8_LAS bf16x8*)(lds + PG8_SB(b, h) + boff + n * 2048 + k * 1024); } while (0)
; #define PG8_MMA(ai, bj, At, Bt) do { __builtin_amdgcn_s_setprio(1); _Pragma("unroll") for (int m = 0; m < 4; ++m) _Pragma("unroll") for (int n = 0; n < 2; ++n) _Pragma("unroll") for (int k = 0; k < 2; ++k) \
;         acc[ai][bj][m][n] = __builtin_amdgcn_mfma_f32_16x16x32_bf16(Bt[n][k], At[m][k], acc[ai][bj][m][n], 0, 0, 0); __builtin_amdgcn_s_setprio(0); } while (0)
; #define PG8_WAIT_V(n) asm volatile("s_waitcnt vmcnt(" #n ")" ::: "memory")
; #define PG8_WAIT_L(n) asm volatile("s_waitcnt lgkmcnt(" #n ")" ::: "memory")
; #define PG8_BAR __builtin_amdgcn_s_barrier()
; #define PG8_SCHED __builtin_amdgcn_sched_barrier(0)
; template <class Epi, class Sched, bool ALIGN_EPI = false, bool SP2 = false>
; __device__ __forceinline__ void gemm_phase(PG8_LAS unsigned char* lds, const Gemm g, const Sched& S, const Epi& E) {
;     ...
;             PG8_WAIT_V(8); PG8_WAIT_L(0); PG8_BAR; PG8_MMA(1, 0, At, B0); PG8_MMA(1, 1, At, B1); PG8_BAR; PG8_SCHED;
;             PG8_LDB(B0, 1, 0); PG8_LDB(B1, 1, 1); PG8_SCHED; PG8_LDA(At, 1, 0); PG8_STAGE(PG8_SA(0, 1), a2 + hstep, voffA);
;             PG8_WAIT_V(8); PG8_WAIT_L(0); PG8_BAR; PG8_MMA(0, 0, At, B0); PG8_MMA(0, 1, At, B1); PG8_BAR; PG8_SCHED;
	s_setprio 1
	s_waitcnt lgkmcnt(0)
	v_mfma_f32_16x16x32_bf16 v[60:63], v[154:157], v[202:205], v[60:63]
	v_mfma_f32_16x16x32_bf16 v[56:59], v[176:179], v[202:205], v[56:59]
	v_mfma_f32_16x16x32_bf16 v[40:43], v[176:179], v[210:213], v[40:43]
	v_mfma_f32_16x16x32_bf16 v[44:47], v[154:157], v[210:213], v[44:47]
	v_mfma_f32_16x16x32_bf16 v[28:31], v[154:157], v[218:221], v[28:31]
	v_mfma_f32_16x16x32_bf16 v[24:27], v[176:179], v[218:221], v[24:27]
	v_mfma_f32_16x16x32_bf16 v[8:11], v[176:179], v[226:229], v[8:11]
	v_mfma_f32_16x16x32_bf16 v[12:15], v[154:157], v[226:229], v[12:15]
	v_mfma_f32_16x16x32_bf16 v[60:63], v[166:169], v[206:209], v[60:63]
	v_mfma_f32_16x16x32_bf16 v[56:59], v[180:183], v[206:209], v[56:59]
	v_mfma_f32_16x16x32_bf16 v[40:43], v[180:183], v[214:217], v[40:43]
	v_mfma_f32_16x16x32_bf16 v[44:47], v[166:169], v[214:217], v[44:47]
	v_mfma_f32_16x16x32_bf16 v[28:31], v[166:169], v[222:225], v[28:31]
	v_mfma_f32_16x16x32_bf16 v[24:27], v[180:183], v[222:225], v[24:27]
	v_mfma_f32_16x16x32_bf16 v[8:11], v[180:183], v[230:233], v[8:11]
	v_mfma_f32_16x16x32_bf16 v[12:15], v[166:169], v[230:233], v[12:15]
	s_setprio 0
	s_setprio 1
	v_mfma_f32_16x16x32_bf16 v[52:55], v[184:187], v[202:205], v[52:55]
	v_mfma_f32_16x16x32_bf16 v[48:51], v[192:195], v[202:205], v[48:51]
	v_mfma_f32_16x16x32_bf16 v[32:35], v[192:195], v[210:213], v[32:35]
	v_mfma_f32_16x16x32_bf16 v[36:39], v[184:187], v[210:213], v[36:39]
	v_mfma_f32_16x16x32_bf16 v[20:23], v[184:187], v[218:221], v[20:23]
	v_mfma_f32_16x16x32_bf16 v[16:19], v[192:195], v[218:221], v[16:19]
	v_mfma_f32_16x16x32_bf16 v[0:3], v[192:195], v[226:229], v[0:3]
	v_mfma_f32_16x16x32_bf16 v[4:7], v[184:187], v[226:229], v[4:7]
	v_mfma_f32_16x16x32_bf16 v[52:55], v[188:191], v[206:209], v[52:55]
	v_mfma_f32_16x16x32_bf16 v[48:51], v[196:199], v[206:209], v[48:51]
	v_mfma_f32_16x16x32_bf16 v[32:35], v[196:199], v[214:217], v[32:35]
	v_mfma_f32_16x16x32_bf16 v[36:39], v[188:191], v[214:217], v[36:39]
	v_mfma_f32_16x16x32_bf16 v[20:23], v[188:191], v[222:225], v[20:23]
	v_mfma_f32_16x16x32_bf16 v[16:19], v[196:199], v[222:225], v[16:19]
	v_mfma_f32_16x16x32_bf16 v[0:3], v[196:199], v[230:233], v[0:3]
	v_mfma_f32_16x16x32_bf16 v[4:7], v[188:191], v[230:233], v[4:7]
	s_setprio 0
	s_barrier
	s_add_i32 s50, 0, 0x18000
	v_add_u32_e32 v171, s50, v159
	s_add_i32 s51, 0, 0x1c000
	ds_read_b128 v[154:157], v171
	ds_read_b128 v[166:169], v171 offset:1024
	ds_read_b128 v[176:179], v171 offset:2048
	ds_read_b128 v[180:183], v171 offset:3072
	v_add_u32_e32 v171, s51, v159
	ds_read_b128 v[184:187], v171
	ds_read_b128 v[188:191], v171 offset:1024
	ds_read_b128 v[192:195], v171 offset:2048
	ds_read_b128 v[196:199], v171 offset:3072
	s_add_u32 s38, s38, 0x20000
	s_addc_u32 s39, s39, 0
	s_mov_b32 m0, s60
	v_lshl_add_u64 v[242:243], s[38:39], 0, v[128:129]
	ds_read_b128 v[202:205], v165 offset:32768
	ds_read_b128 v[206:209], v165 offset:33792
	ds_read_b128 v[210:213], v165 offset:34816
	ds_read_b128 v[214:217], v165 offset:35840
	ds_read_b128 v[218:221], v165 offset:36864
	ds_read_b128 v[222:225], v165 offset:37888
	ds_read_b128 v[226:229], v165 offset:38912
	ds_read_b128 v[230:233], v165 offset:39936
	global_load_lds_dwordx4 v[242:243], off
	v_lshl_add_u64 v[242:243], s[38:39], 0, v[132:133]
	s_mov_b32 m0, s61
	s_nop 0
	global_load_lds_dwordx4 v[242:243], off
	s_waitcnt vmcnt(8)
	s_waitcnt lgkmcnt(0)
	s_barrier
	s_setprio 1
	s_waitcnt lgkmcnt(0)
	v_mfma_f32_16x16x32_bf16 v[124:127], v[154:157], v[202:205], v[124:127]
	v_mfma_f32_16x16x32_bf16 v[120:123], v[176:179], v[202:205], v[120:123]
	v_mfma_f32_16x16x32_bf16 v[104:107], v[176:179], v[210:213], v[104:107]
	v_mfma_f32_16x16x32_bf16 v[108:111], v[154:157], v[210:213], v[108:111]
	v_mfma_f32_16x16x32_bf16 v[92:95], v[154:157], v[218:221], v[92:95]
	v_mfma_f32_16x16x32_bf16 v[88:91], v[176:179], v[218:221], v[88:91]
	v_mfma_f32_16x16x32_bf16 v[72:75], v[176:179], v[226:229], v[72:75]
	v_mfma_f32_16x16x32_bf16 v[76:79], v[154:157], v[226:229], v[76:79]
	v_mfma_f32_16x16x32_bf16 v[124:127], v[166:169], v[206:209], v[124:127]
	v_mfma_f32_16x16x32_bf16 v[120:123], v[180:183], v[206:209], v[120:123]
	v_mfma_f32_16x16x32_bf16 v[104:107], v[180:183], v[214:217], v[104:107]
	v_mfma_f32_16x16x32_bf16 v[108:111], v[166:169], v[214:217], v[108:111]
	v_mfma_f32_16x16x32_bf16 v[92:95], v[166:169], v[222:225], v[92:95]
	v_mfma_f32_16x16x32_bf16 v[88:91], v[180:183], v[222:225], v[88:91]
	v_mfma_f32_16x16x32_bf16 v[72:75], v[180:183], v[230:233], v[72:75]
	v_mfma_f32_16x16x32_bf16 v[76:79], v[166:169], v[230:233], v[76:79]
	s_setprio 0
	s_setprio 1
	v_mfma_f32_16x16x32_bf16 v[116:119], v[184:187], v[202:205], v[116:119]
	v_mfma_f32_16x16x32_bf16 v[112:115], v[192:195], v[202:205], v[112:115]
	v_mfma_f32_16x16x32_bf16 v[96:99], v[192:195], v[210:213], v[96:99]
	v_mfma_f32_16x16x32_bf16 v[100:103], v[184:187], v[210:213], v[100:103]
	v_mfma_f32_16x16x32_bf16 v[84:87], v[184:187], v[218:221], v[84:87]
	v_mfma_f32_16x16x32_bf16 v[80:83], v[192:195], v[218:221], v[80:83]
	v_mfma_f32_16x16x32_bf16 v[64:67], v[192:195], v[226:229], v[64:67]
	v_mfma_f32_16x16x32_bf16 v[68:71], v[184:187], v[226:229], v[68:71]
	v_mfma_f32_16x16x32_bf16 v[116:119], v[188:191], v[206:209], v[116:119]
	v_mfma_f32_16x16x32_bf16 v[112:115], v[196:199], v[206:209], v[112:115]
	v_mfma_f32_16x16x32_bf16 v[96:99], v[196:199], v[214:217], v[96:99]
	v_mfma_f32_16x16x32_bf16 v[100:103], v[188:191], v[214:217], v[100:103]
	v_mfma_f32_16x16x32_bf16 v[84:87], v[188:191], v[222:225], v[84:87]
	v_mfma_f32_16x16x32_bf16 v[80:83], v[196:199], v[222:225], v[80:83]
	v_mfma_f32_16x16x32_bf16 v[64:67], v[196:199], v[230:233], v[64:67]
	v_mfma_f32_16x16x32_bf16 v[68:71], v[188:191], v[230:233], v[68:71]
	s_setprio 0
	s_barrier
; #define PG8_STAGE(bufoff, gbase, voff) do { _Pragma("unroll") for (int _i = 0; _i < 2; ++_i) \
;         __builtin_amdgcn_global_load_lds((const unsigned*)((const char*)(gbase) + (voff)[_i]), (PG8_LAS unsigned*)(lds + (bufoff) + ldsw + _i * 8192), 16, 0, 0); } while (0)
; #define PG8_LDA(dst, b, h) do { _Pragma("unroll") for (int m = 0; m < 4; ++m) _Pragma("unroll") for (int k = 0; k < 2; ++k) dst[m][k] = *(const PG8_LAS bf16x8*)(lds + PG8_SA(b, h) + aoff + m * 2048 + k * 1024); } while (0)
; #define PG8_MMA(ai, bj, At, Bt) do { __builtin_amdgcn_s_setprio(1); _Pragma("unroll") for (int m = 0; m < 4; ++m) _Pragma("unroll") for (int n = 0; n < 2; ++n) _Pragma("unroll") for (int k = 0; k < 2; ++k) \
;         acc[ai][bj][m][n] = __builtin_amdgcn_mfma_f32_16x16x32_bf16(Bt[n][k], At[m][k], acc[ai][bj][m][n], 0, 0, 0); __builtin_amdgcn_s_setprio(0); } while (0)
; #define PG8_WAIT_V(n) asm volatile("s_waitcnt vmcnt(" #n ")" ::: "memory")
; #define PG8_WAIT_L(n) asm volatile("s_waitcnt lgkmcnt(" #n ")" ::: "memory")
; #define PG8_BAR __builtin_amdgcn_s_barrier()
; #define PG8_SCHED __builtin_amdgcn_sched_barrier(0)
; template <class Epi, class Sched, bool ALIGN_EPI = false, bool SP2 = false>
; __device__ __forceinline__ void gemm_phase(PG8_LAS unsigned char* lds, const Gemm g, const Sched& S, const Epi& E) {
;     ...
;             PG8_LDA(At, 1, 1); PG8_STAGE(PG8_SB(1, 0), b3, voffB); PG8_STAGE(PG8_SB(1, 1), b3 + hstepB, voffB); PG8_STAGE(PG8_SA(1, 0), a3, voffA);
;             PG8_WAIT_V(8); PG8_WAIT_L(0); PG8_BAR; PG8_MMA(1, 0, At, B0); PG8_MMA(1, 1, At, B1); PG8_BAR; PG8_SCHED;
	s_add_i32 s38, s50, s58
	v_lshl_add_u64 v[234:235], v[234:235], 0, s[16:17]
	s_mov_b32 m0, s38
	ds_read_b128 v[202:205], v165 offset:49152
	ds_read_b128 v[206:209], v165 offset:50176
	ds_read_b128 v[210:213], v165 offset:51200
	ds_read_b128 v[214:217], v165 offset:52224
	ds_read_b128 v[218:221], v165 offset:53248
	ds_read_b128 v[222:225], v165 offset:54272
	ds_read_b128 v[226:229], v165 offset:55296
	ds_read_b128 v[230:233], v165 offset:56320
	global_load_lds_dwordx4 v[234:235], off
	s_add_i32 m0, s38, 0x2000
	s_add_u32 s36, s36, 0x8080
	v_lshl_add_u64 v[234:235], v[236:237], 0, s[16:17]
	s_addc_u32 s37, s37, 0
	s_add_i32 s38, s51, s58
	global_load_lds_dwordx4 v[234:235], off
	v_lshl_add_u64 v[234:235], s[36:37], 0, v[130:131]
	s_mov_b32 m0, s38
	s_nop 0
	global_load_lds_dwordx4 v[234:235], off
	v_lshl_add_u64 v[234:235], s[36:37], 0, v[134:135]
	s_add_i32 m0, s38, 0x2000
	s_nop 0
	global_load_lds_dwordx4 v[234:235], off
	v_lshl_add_u64 v[234:235], v[238:239], 0, s[16:17]
	s_mov_b32 m0, s63
	s_nop 0
	global_load_lds_dwordx4 v[234:235], off
	v_lshl_add_u64 v[234:235], v[240:241], 0, s[16:17]
	s_mov_b32 m0, s64
	s_nop 0
	global_load_lds_dwordx4 v[234:235], off
	s_waitcnt vmcnt(8)
	s_waitcnt lgkmcnt(0)
	s_barrier
	s_setprio 1
	s_waitcnt lgkmcnt(0)
	v_mfma_f32_16x16x32_bf16 v[60:63], v[154:157], v[202:205], v[60:63]
	v_mfma_f32_16x16x32_bf16 v[56:59], v[176:179], v[202:205], v[56:59]
	v_mfma_f32_16x16x32_bf16 v[40:43], v[176:179], v[210:213], v[40:43]
	v_mfma_f32_16x16x32_bf16 v[44:47], v[154:157], v[210:213], v[44:47]
	v_mfma_f32_16x16x32_bf16 v[28:31], v[154:157], v[218:221], v[28:31]
	v_mfma_f32_16x16x32_bf16 v[24:27], v[176:179], v[218:221], v[24:27]
	v_mfma_f32_16x16x32_bf16 v[8:11], v[176:179], v[226:229], v[8:11]
	v_mfma_f32_16x16x32_bf16 v[12:15], v[154:157], v[226:229], v[12:15]
	v_mfma_f32_16x16x32_bf16 v[60:63], v[166:169], v[206:209], v[60:63]
	v_mfma_f32_16x16x32_bf16 v[56:59], v[180:183], v[206:209], v[56:59]
	v_mfma_f32_16x16x32_bf16 v[40:43], v[180:183], v[214:217], v[40:43]
	v_mfma_f32_16x16x32_bf16 v[44:47], v[166:169], v[214:217], v[44:47]
	v_mfma_f32_16x16x32_bf16 v[28:31], v[166:169], v[222:225], v[28:31]
	v_mfma_f32_16x16x32_bf16 v[24:27], v[180:183], v[222:225], v[24:27]
	v_mfma_f32_16x16x32_bf16 v[8:11], v[180:183], v[230:233], v[8:11]
	v_mfma_f32_16x16x32_bf16 v[12:15], v[166:169], v[230:233], v[12:15]
	s_setprio 0
	s_setprio 1
	v_mfma_f32_16x16x32_bf16 v[52:55], v[184:187], v[202:205], v[52:55]
	v_mfma_f32_16x16x32_bf16 v[48:51], v[192:195], v[202:205], v[48:51]
	v_mfma_f32_16x16x32_bf16 v[32:35], v[192:195], v[210:213], v[32:35]
	v_mfma_f32_16x16x32_bf16 v[36:39], v[184:187], v[210:213], v[36:39]
	v_mfma_f32_16x16x32_bf16 v[20:23], v[184:187], v[218:221], v[20:23]
	v_mfma_f32_16x16x32_bf16 v[16:19], v[192:195], v[218:221], v[16:19]
	v_mfma_f32_16x16x32_bf16 v[0:3], v[192:195], v[226:229], v[0:3]
	v_mfma_f32_16x16x32_bf16 v[4:7], v[184:187], v[226:229], v[4:7]
	v_mfma_f32_16x16x32_bf16 v[52:55], v[188:191], v[206:209], v[52:55]
	v_mfma_f32_16x16x32_bf16 v[48:51], v[196:199], v[206:209], v[48:51]
	v_mfma_f32_16x16x32_bf16 v[32:35], v[196:199], v[214:217], v[32:35]
	v_mfma_f32_16x16x32_bf16 v[36:39], v[188:191], v[214:217], v[36:39]
	v_mfma_f32_16x16x32_bf16 v[20:23], v[188:191], v[222:225], v[20:23]
	v_mfma_f32_16x16x32_bf16 v[16:19], v[196:199], v[222:225], v[16:19]
	v_mfma_f32_16x16x32_bf16 v[0:3], v[196:199], v[230:233], v[0:3]
	v_mfma_f32_16x16x32_bf16 v[4:7], v[188:191], v[230:233], v[4:7]
	s_setprio 0
	s_barrier
	s_add_i32 s49, s49, 2
	s_add_u32 s41, s41, 0x100
	s_addc_u32 s48, s48, 0
	s_add_u32 s34, s34, 0x100
	s_addc_u32 s35, s35, 0
	s_cmp_gt_u32 s49, 5
	s_cbranch_scc0 .LBB0_956
	s_and_b64 vcc, exec, s[20:21]
	s_cbranch_vccz .LBB0_959
	s_barrier

; #define PG8_STAGE(bufoff, gbase, voff) do { _Pragma("unroll") for (int _i = 0; _i < 2; ++_i) \
;         __builtin_amdgcn_global_load_lds((const unsigned*)((const char*)(gbase) + (voff)[_i]), (PG8_LAS unsigned*)(lds + (bufoff) + ldsw + _i * 8192), 16, 0, 0); } while (0)
; #define PG8_LDA(dst, b, h) do { _Pragma("unroll") for (int m = 0; m < 4; ++m) _Pragma("unroll") for (int k = 0; k < 2; ++k) dst[m][k] = *(const PG8_LAS bf16x8*)(lds + PG8_SA(b, h) + aoff + m * 2048 + k * 1024); } while (0)
; #define PG8_LDB(dst, b, h) do { _Pragma("unroll") for (int n = 0; n < 2; ++n) _Pragma("unroll") for (int k = 0; k < 2; ++k) dst[n][k] = *(const PG8_LAS bf16x8*)(lds + PG8_SB(b, h) + boff + n * 2048 + k * 1024); } while (0)
; #define PG8_WAIT_V(n) asm volatile("s_waitcnt vmcnt(" #n ")" ::: "memory")
; #define PG8_WAIT_L(n) asm volatile("s_waitcnt lgkmcnt(" #n ")" ::: "memory")
; #define PG8_BAR __builtin_amdgcn_s_barrier()
; #define PG8_SCHED __builtin_amdgcn_sched_barrier(0)
; template <class Epi, class Sched, bool ALIGN_EPI = false, bool SP2 = false>
; __device__ __forceinline__ void gemm_phase(PG8_LAS unsigned char* lds, const Gemm g, const Sched& S, const Epi& E) {
;     ...
;         const char* nA = has_next ? (const char*)g.A + (size_t)nxt.pm * tstep : cA; const char* nB = has_next ? (const char*)g.Bt + (size_t)nxt.pn * tstep : cB;
;         for (int t = 0; t < nt; t += 2) {
;             const bool last = (t == nt - 2);
;             const char* a1 = cA + (size_t)(t + 1) * kstep;
;             const char* a2 = last ? nA : cA + (size_t)(t + 2) * kstep; const char* b2 = last ? nB : cB + (size_t)(t + 2) * kstep;
;             const char* a3 = a2 + kstep; const char* b3 = b2 + kstep;
;             if (last && has_next) S.a_ready(nxt);
;             if constexpr (SP2) {
;             PG8_LDB(B0, 0, 0); PG8_LDB(B1, 0, 1); PG8_SCHED; PG8_LDA(At, 0, 0); PG8_STAGE(PG8_SA(1, 1), a1 + hstep, voffA);
;             PG8_WAIT_V(8); PG8_WAIT_L(0); PG8_BAR; PG8_MMA(0, 0, At, B0); PG8_MMA(0, 1, At, B1); PG8_BAR; PG8_SCHED;
;             PG8_LDA(At, 0, 1); PG8_STAGE(PG8_SB(0, 0), b2, voffB); PG8_STAGE(PG8_SB(0, 1), b2 + hstepB, voffB); PG8_STAGE(PG8_SA(0, 0), a2, voffA);
;             PG8_WAIT_V(8); PG8_WAIT_L(0); PG8_BAR; PG8_MMA(1, 0, At, B0); PG8_MMA(1, 1, At, B1); PG8_BAR; PG8_SCHED;
.LBB0_1012:
	s_add_u32 s43, s34, s42
	s_addc_u32 s50, s35, 0
	s_add_u32 s51, s43, 0x100
	s_addc_u32 s54, s50, 0
	s_and_b64 s[48:49], s[38:39], exec
	s_cselect_b32 s59, s23, s54
	s_cselect_b32 s58, s40, s51
	s_add_u32 s42, s30, s42
	s_addc_u32 s48, s31, 0
	s_add_u32 s42, s42, 0x100
	s_addc_u32 s48, s48, 0
	s_and_b64 s[38:39], s[38:39], exec
	s_cselect_b32 s61, s21, s48
	s_cselect_b32 s60, s41, s42
	s_add_u32 s64, s43, 0x10080
	ds_read_b128 v[152:155], v148
	ds_read_b128 v[156:159], v148 offset:1024
	ds_read_b128 v[160:163], v148 offset:2048
	ds_read_b128 v[164:167], v148 offset:3072
	ds_read_b128 v[176:179], v149
	ds_read_b128 v[180:183], v149 offset:1024
	ds_read_b128 v[184:187], v149 offset:2048
	ds_read_b128 v[188:191], v149 offset:3072
	s_addc_u32 s65, s50, 0
	s_add_i32 s90, s79, s67
	s_add_i32 m0, s29, 0xc000
	s_add_i32 s91, s29, 0xe000
	s_add_i32 s56, s90, 0x2000
	s_add_u32 s62, s60, 0x4000
	s_addc_u32 s63, s61, 0
	s_add_i32 s78, s80, s67
	s_add_i32 s57, s78, 0x2000
	s_add_i32 s55, 0, 0x18000
	s_add_i32 s54, 0, 0x1c000
	s_add_u32 s42, s58, 0x10000
	s_addc_u32 s43, s59, 0
	s_add_i32 s51, s55, s67
	s_add_i32 s49, s51, 0x2000
	s_add_u32 s38, s60, 0x4080
	s_addc_u32 s39, s61, 0
	s_add_i32 s50, s54, s67
	s_add_i32 s48, s50, 0x2000
	v_lshl_add_u64 v[142:143], s[64:65], 0, v[128:129]
	ds_read_b128 v[192:195], v150
	ds_read_b128 v[196:199], v150 offset:1024
	ds_read_b128 v[202:205], v150 offset:2048
	ds_read_b128 v[206:209], v150 offset:3072
	ds_read_b128 v[210:213], v150 offset:4096
	ds_read_b128 v[214:217], v150 offset:5120
	ds_read_b128 v[218:221], v150 offset:6144
	ds_read_b128 v[222:225], v150 offset:7168
	global_load_lds_dwordx4 v[142:143], off
	v_lshl_add_u64 v[142:143], s[64:65], 0, v[132:133]
	s_mov_b32 m0, s91
	s_nop 0
	global_load_lds_dwordx4 v[142:143], off
	s_waitcnt vmcnt(8)
	s_waitcnt lgkmcnt(0)
	s_barrier
	s_setprio 1
	s_waitcnt lgkmcnt(0)
	v_mfma_f32_16x16x32_bf16 v[124:127], v[152:155], v[192:195], v[124:127]
	v_mfma_f32_16x16x32_bf16 v[120:123], v[160:163], v[192:195], v[120:123]
	v_mfma_f32_16x16x32_bf16 v[108:111], v[160:163], v[202:205], v[108:111]
	v_mfma_f32_16x16x32_bf16 v[116:119], v[152:155], v[202:205], v[116:119]
	v_mfma_f32_16x16x32_bf16 v[96:99], v[152:155], v[210:213], v[96:99]
	v_mfma_f32_16x16x32_bf16 v[88:91], v[160:163], v[210:213], v[88:91]
	v_mfma_f32_16x16x32_bf16 v[72:75], v[160:163], v[218:221], v[72:75]
	v_mfma_f32_16x16x32_bf16 v[80:83], v[152:155], v[218:221], v[80:83]
	v_mfma_f32_16x16x32_bf16 v[124:127], v[156:159], v[196:199], v[124:127]
	v_mfma_f32_16x16x32_bf16 v[120:123], v[164:167], v[196:199], v[120:123]
	v_mfma_f32_16x16x32_bf16 v[108:111], v[164:167], v[206:209], v[108:111]
	v_mfma_f32_16x16x32_bf16 v[116:119], v[156:159], v[206:209], v[116:119]
	v_mfma_f32_16x16x32_bf16 v[96:99], v[156:159], v[214:217], v[96:99]
	v_mfma_f32_16x16x32_bf16 v[88:91], v[164:167], v[214:217], v[88:91]
	v_mfma_f32_16x16x32_bf16 v[72:75], v[164:167], v[222:225], v[72:75]
	v_mfma_f32_16x16x32_bf16 v[80:83], v[156:159], v[222:225], v[80:83]
	s_setprio 0
	s_setprio 1
	v_mfma_f32_16x16x32_bf16 v[112:115], v[176:179], v[192:195], v[112:115]
	v_mfma_f32_16x16x32_bf16 v[104:107], v[184:187], v[192:195], v[104:107]
	v_mfma_f32_16x16x32_bf16 v[92:95], v[184:187], v[202:205], v[92:95]
	v_mfma_f32_16x16x32_bf16 v[100:103], v[176:179], v[202:205], v[100:103]
	v_mfma_f32_16x16x32_bf16 v[84:87], v[176:179], v[210:213], v[84:87]
	v_mfma_f32_16x16x32_bf16 v[76:79], v[184:187], v[210:213], v[76:79]
	v_mfma_f32_16x16x32_bf16 v[64:67], v[184:187], v[218:221], v[64:67]
	v_mfma_f32_16x16x32_bf16 v[68:71], v[176:179], v[218:221], v[68:71]
	v_mfma_f32_16x16x32_bf16 v[112:115], v[180:183], v[196:199], v[112:115]
	v_mfma_f32_16x16x32_bf16 v[104:107], v[188:191], v[196:199], v[104:107]
	v_mfma_f32_16x16x32_bf16 v[92:95], v[188:191], v[206:209], v[92:95]
	v_mfma_f32_16x16x32_bf16 v[100:103], v[180:183], v[206:209], v[100:103]
	v_mfma_f32_16x16x32_bf16 v[84:87], v[180:183], v[214:217], v[84:87]
	v_mfma_f32_16x16x32_bf16 v[76:79], v[188:191], v[214:217], v[76:79]
	v_mfma_f32_16x16x32_bf16 v[64:67], v[188:191], v[222:225], v[64:67]
	v_mfma_f32_16x16x32_bf16 v[68:71], v[180:183], v[222:225], v[68:71]
	s_setprio 0
	s_barrier
	s_mov_b32 m0, s90
	v_lshl_add_u64 v[142:143], s[60:61], 0, v[130:131]
	ds_read_b128 v[192:195], v150 offset:16384
	ds_read_b128 v[196:199], v150 offset:17408
	ds_read_b128 v[202:205], v150 offset:18432
	ds_read_b128 v[206:209], v150 offset:19456
	ds_read_b128 v[210:213], v150 offset:20480
	ds_read_b128 v[214:217], v150 offset:21504
	ds_read_b128 v[218:221], v150 offset:22528
	ds_read_b128 v[222:225], v150 offset:23552
	global_load_lds_dwordx4 v[142:143], off
	v_lshl_add_u64 v[168:169], s[60:61], 0, v[134:135]
	s_mov_b32 m0, s56
	v_lshl_add_u64 v[226:227], s[62:63], 0, v[130:131]
	global_load_lds_dwordx4 v[168:169], off
	s_mov_b32 m0, s78
	v_lshl_add_u64 v[228:229], s[58:59], 0, v[132:133]
	global_load_lds_dwordx4 v[226:227], off
	v_lshl_add_u64 v[226:227], s[62:63], 0, v[134:135]
	s_mov_b32 m0, s57
	s_nop 0
	global_load_lds_dwordx4 v[226:227], off
	v_lshl_add_u64 v[226:227], s[58:59], 0, v[128:129]
	s_mov_b32 m0, s29
	s_nop 0
	global_load_lds_dwordx4 v[226:227], off
	s_mov_b32 m0, s70
	s_nop 0
	global_load_lds_dwordx4 v[228:229], off
	s_waitcnt vmcnt(8)
	s_waitcnt lgkmcnt(0)
	s_barrier
; #define PG8_STAGE(bufoff, gbase, voff) do { _Pragma("unroll") for (int _i = 0; _i < 2; ++_i) \
;         __builtin_amdgcn_global_load_lds((const unsigned*)((const char*)(gbase) + (voff)[_i]), (PG8_LAS unsigned*)(lds + (bufoff) + ldsw + _i * 8192), 16, 0, 0); } while (0)
; #define PG8_LDA(dst, b, h) do { _Pragma("unroll") for (int m = 0; m < 4; ++m) _Pragma("unroll") for (int k = 0; k < 2; ++k) dst[m][k] = *(const PG8_LAS bf16x8*)(lds + PG8_SA(b, h) + aoff + m * 2048 + k * 1024); } while (0)
; #define PG8_LDB(dst, b, h) do { _Pragma("unroll") for (int n = 0; n < 2; ++n) _Pragma("unroll") for (int k = 0; k < 2; ++k) dst[n][k] = *(const PG8_LAS bf16x8*)(lds + PG8_SB(b, h) + boff + n * 2048 + k * 1024); } while (0)
; #define PG8_MMA(ai, bj, At, Bt) do { __builtin_amdgcn_s_setprio(1); _Pragma("unroll") for (int m = 0; m < 4; ++m) _Pragma("unroll") for (int n = 0; n < 2; ++n) _Pragma("unroll") for (int k = 0; k < 2; ++k) \
;         acc[ai][bj][m][n] = __builtin_amdgcn_mfma_f32_16x16x32_bf16(Bt[n][k], At[m][k], acc[ai][bj][m][n], 0, 0, 0); __builtin_amdgcn_s_setprio(0); } while (0)
; #define PG8_WAIT_V(n) asm volatile("s_waitcnt vmcnt(" #n ")" ::: "memory")
; #define PG8_WAIT_L(n) asm volatile("s_waitcnt lgkmcnt(" #n ")" ::: "memory")
; #define PG8_BAR __builtin_amdgcn_s_barrier()
; #define PG8_SCHED __builtin_amdgcn_sched_barrier(0)
; template <class Epi, class Sched, bool ALIGN_EPI = false, bool SP2 = false>
; __device__ __forceinline__ void gemm_phase(PG8_LAS unsigned char* lds, const Gemm g, const Sched& S, const Epi& E) {
;     ...
;             PG8_WAIT_V(8); PG8_WAIT_L(0); PG8_BAR; PG8_MMA(1, 0, At, B0); PG8_MMA(1, 1, At, B1); PG8_BAR; PG8_SCHED;
;             PG8_LDB(B0, 1, 0); PG8_LDB(B1, 1, 1); PG8_SCHED; PG8_LDA(At, 1, 0); PG8_STAGE(PG8_SA(0, 1), a2 + hstep, voffA);
;             PG8_WAIT_V(8); PG8_WAIT_L(0); PG8_BAR; PG8_MMA(0, 0, At, B0); PG8_MMA(0, 1, At, B1); PG8_BAR; PG8_SCHED;
	s_setprio 1
	s_waitcnt lgkmcnt(0)
	v_mfma_f32_16x16x32_bf16 v[60:63], v[152:155], v[192:195], v[60:63]
	v_mfma_f32_16x16x32_bf16 v[56:59], v[160:163], v[192:195], v[56:59]
	v_mfma_f32_16x16x32_bf16 v[40:43], v[160:163], v[202:205], v[40:43]
	v_mfma_f32_16x16x32_bf16 v[48:51], v[152:155], v[202:205], v[48:51]
	v_mfma_f32_16x16x32_bf16 v[32:35], v[152:155], v[210:213], v[32:35]
	v_mfma_f32_16x16x32_bf16 v[24:27], v[160:163], v[210:213], v[24:27]
	v_mfma_f32_16x16x32_bf16 v[8:11], v[160:163], v[218:221], v[8:11]
	v_mfma_f32_16x16x32_bf16 v[16:19], v[152:155], v[218:221], v[16:19]
	v_mfma_f32_16x16x32_bf16 v[60:63], v[156:159], v[196:199], v[60:63]
	v_mfma_f32_16x16x32_bf16 v[56:59], v[164:167], v[196:199], v[56:59]
	v_mfma_f32_16x16x32_bf16 v[40:43], v[164:167], v[206:209], v[40:43]
	v_mfma_f32_16x16x32_bf16 v[48:51], v[156:159], v[206:209], v[48:51]
	v_mfma_f32_16x16x32_bf16 v[32:35], v[156:159], v[214:217], v[32:35]
	v_mfma_f32_16x16x32_bf16 v[24:27], v[164:167], v[214:217], v[24:27]
	v_mfma_f32_16x16x32_bf16 v[8:11], v[164:167], v[222:225], v[8:11]
	v_mfma_f32_16x16x32_bf16 v[16:19], v[156:159], v[222:225], v[16:19]
	s_setprio 0
	s_setprio 1
	v_mfma_f32_16x16x32_bf16 v[52:55], v[176:179], v[192:195], v[52:55]
	v_mfma_f32_16x16x32_bf16 v[44:47], v[184:187], v[192:195], v[44:47]
	v_mfma_f32_16x16x32_bf16 v[28:31], v[184:187], v[202:205], v[28:31]
	v_mfma_f32_16x16x32_bf16 v[36:39], v[176:179], v[202:205], v[36:39]
	v_mfma_f32_16x16x32_bf16 v[20:23], v[176:179], v[210:213], v[20:23]
	v_mfma_f32_16x16x32_bf16 v[12:15], v[184:187], v[210:213], v[12:15]
	v_mfma_f32_16x16x32_bf16 v[0:3], v[184:187], v[218:221], v[0:3]
	v_mfma_f32_16x16x32_bf16 v[4:7], v[176:179], v[218:221], v[4:7]
	v_mfma_f32_16x16x32_bf16 v[52:55], v[180:183], v[196:199], v[52:55]
	v_mfma_f32_16x16x32_bf16 v[44:47], v[188:191], v[196:199], v[44:47]
	v_mfma_f32_16x16x32_bf16 v[28:31], v[188:191], v[206:209], v[28:31]
	v_mfma_f32_16x16x32_bf16 v[36:39], v[180:183], v[206:209], v[36:39]
	v_mfma_f32_16x16x32_bf16 v[20:23], v[180:183], v[214:217], v[20:23]
	v_mfma_f32_16x16x32_bf16 v[12:15], v[188:191], v[214:217], v[12:15]
	v_mfma_f32_16x16x32_bf16 v[0:3], v[188:191], v[222:225], v[0:3]
	v_mfma_f32_16x16x32_bf16 v[4:7], v[180:183], v[222:225], v[4:7]
	s_setprio 0
	s_barrier
	v_add_u32_e32 v151, s55, v144
	ds_read_b128 v[152:155], v151
	ds_read_b128 v[156:159], v151 offset:1024
	ds_read_b128 v[160:163], v151 offset:2048
	ds_read_b128 v[164:167], v151 offset:3072
	v_add_u32_e32 v151, s54, v144
	ds_read_b128 v[176:179], v151
	ds_read_b128 v[180:183], v151 offset:1024
	ds_read_b128 v[184:187], v151 offset:2048
	ds_read_b128 v[188:191], v151 offset:3072
	s_mov_b32 m0, s71
	v_lshl_add_u64 v[230:231], s[42:43], 0, v[128:129]
	ds_read_b128 v[192:195], v150 offset:32768
	ds_read_b128 v[196:199], v150 offset:33792
	ds_read_b128 v[202:205], v150 offset:34816
	ds_read_b128 v[206:209], v150 offset:35840
	ds_read_b128 v[210:213], v150 offset:36864
	ds_read_b128 v[214:217], v150 offset:37888
	ds_read_b128 v[218:221], v150 offset:38912
	ds_read_b128 v[222:225], v150 offset:39936
	global_load_lds_dwordx4 v[230:231], off
	v_lshl_add_u64 v[230:231], s[42:43], 0, v[132:133]
	s_mov_b32 m0, s72
	s_nop 0
	global_load_lds_dwordx4 v[230:231], off
	s_waitcnt vmcnt(8)
	s_waitcnt lgkmcnt(0)
	s_barrier
	s_setprio 1
	s_waitcnt lgkmcnt(0)
	v_mfma_f32_16x16x32_bf16 v[124:127], v[152:155], v[192:195], v[124:127]
	v_mfma_f32_16x16x32_bf16 v[120:123], v[160:163], v[192:195], v[120:123]
	v_mfma_f32_16x16x32_bf16 v[108:111], v[160:163], v[202:205], v[108:111]
	v_mfma_f32_16x16x32_bf16 v[116:119], v[152:155], v[202:205], v[116:119]
	v_mfma_f32_16x16x32_bf16 v[96:99], v[152:155], v[210:213], v[96:99]
	v_mfma_f32_16x16x32_bf16 v[88:91], v[160:163], v[210:213], v[88:91]
	v_mfma_f32_16x16x32_bf16 v[72:75], v[160:163], v[218:221], v[72:75]
	v_mfma_f32_16x16x32_bf16 v[80:83], v[152:155], v[218:221], v[80:83]
	v_mfma_f32_16x16x32_bf16 v[124:127], v[156:159], v[196:199], v[124:127]
	v_mfma_f32_16x16x32_bf16 v[120:123], v[164:167], v[196:199], v[120:123]
	v_mfma_f32_16x16x32_bf16 v[108:111], v[164:167], v[206:209], v[108:111]
	v_mfma_f32_16x16x32_bf16 v[116:119], v[156:159], v[206:209], v[116:119]
	v_mfma_f32_16x16x32_bf16 v[96:99], v[156:159], v[214:217], v[96:99]
	v_mfma_f32_16x16x32_bf16 v[88:91], v[164:167], v[214:217], v[88:91]
	v_mfma_f32_16x16x32_bf16 v[72:75], v[164:167], v[222:225], v[72:75]
	v_mfma_f32_16x16x32_bf16 v[80:83], v[156:159], v[222:225], v[80:83]
	s_setprio 0
	s_setprio 1
	v_mfma_f32_16x16x32_bf16 v[112:115], v[176:179], v[192:195], v[112:115]
	v_mfma_f32_16x16x32_bf16 v[104:107], v[184:187], v[192:195], v[104:107]
	v_mfma_f32_16x16x32_bf16 v[92:95], v[184:187], v[202:205], v[92:95]
	v_mfma_f32_16x16x32_bf16 v[100:103], v[176:179], v[202:205], v[100:103]
	v_mfma_f32_16x16x32_bf16 v[84:87], v[176:179], v[210:213], v[84:87]
	v_mfma_f32_16x16x32_bf16 v[76:79], v[184:187], v[210:213], v[76:79]
	v_mfma_f32_16x16x32_bf16 v[64:67], v[184:187], v[218:221], v[64:67]
	v_mfma_f32_16x16x32_bf16 v[68:71], v[176:179], v[218:221], v[68:71]
	v_mfma_f32_16x16x32_bf16 v[112:115], v[180:183], v[196:199], v[112:115]
	v_mfma_f32_16x16x32_bf16 v[104:107], v[188:191], v[196:199], v[104:107]
	v_mfma_f32_16x16x32_bf16 v[92:95], v[188:191], v[206:209], v[92:95]
	v_mfma_f32_16x16x32_bf16 v[100:103], v[180:183], v[206:209], v[100:103]
	v_mfma_f32_16x16x32_bf16 v[84:87], v[180:183], v[214:217], v[84:87]
	v_mfma_f32_16x16x32_bf16 v[76:79], v[188:191], v[214:217], v[76:79]
	v_mfma_f32_16x16x32_bf16 v[64:67], v[188:191], v[222:225], v[64:67]
	v_mfma_f32_16x16x32_bf16 v[68:71], v[180:183], v[222:225], v[68:71]
	s_setprio 0
	s_barrier
; #define PG8_STAGE(bufoff, gbase, voff) do { _Pragma("unroll") for (int _i = 0; _i < 2; ++_i) \
;         __builtin_amdgcn_global_load_lds((const unsigned*)((const char*)(gbase) + (voff)[_i]), (PG8_LAS unsigned*)(lds + (bufoff) + ldsw + _i * 8192), 16, 0, 0); } while (0)
; #define PG8_LDA(dst, b, h) do { _Pragma("unroll") for (int m = 0; m < 4; ++m) _Pragma("unroll") for (int k = 0; k < 2; ++k) dst[m][k] = *(const PG8_LAS bf16x8*)(lds + PG8_SA(b, h) + aoff + m * 2048 + k * 1024); } while (0)
; #define PG8_MMA(ai, bj, At, Bt) do { __builtin_amdgcn_s_setprio(1); _Pragma("unroll") for (int m = 0; m < 4; ++m) _Pragma("unroll") for (int n = 0; n < 2; ++n) _Pragma("unroll") for (int k = 0; k < 2; ++k) \
;         acc[ai][bj][m][n] = __builtin_amdgcn_mfma_f32_16x16x32_bf16(Bt[n][k], At[m][k], acc[ai][bj][m][n], 0, 0, 0); __builtin_amdgcn_s_setprio(0); } while (0)
; #define PG8_WAIT_V(n) asm volatile("s_waitcnt vmcnt(" #n ")" ::: "memory")
; #define PG8_WAIT_L(n) asm volatile("s_waitcnt lgkmcnt(" #n ")" ::: "memory")
; #define PG8_BAR __builtin_amdgcn_s_barrier()
; #define PG8_SCHED __builtin_amdgcn_sched_barrier(0)
; template <class Epi, class Sched, bool ALIGN_EPI = false, bool SP2 = false>
; __device__ __forceinline__ void gemm_phase(PG8_LAS unsigned char* lds, const Gemm g, const Sched& S, const Epi& E) {
;     ...
;             PG8_LDA(At, 1, 1); PG8_STAGE(PG8_SB(1, 0), b3, voffB); PG8_STAGE(PG8_SB(1, 1), b3 + hstepB, voffB); PG8_STAGE(PG8_SA(1, 0), a3, voffA);
;             PG8_WAIT_V(8); PG8_WAIT_L(0); PG8_BAR; PG8_MMA(1, 0, At, B0); PG8_MMA(1, 1, At, B1); PG8_BAR; PG8_SCHED;
	s_mov_b32 m0, s51
	v_lshl_add_u64 v[142:143], v[142:143], 0, s[16:17]
	ds_read_b128 v[192:195], v150 offset:49152
	ds_read_b128 v[196:199], v150 offset:50176
	ds_read_b128 v[202:205], v150 offset:51200
	ds_read_b128 v[206:209], v150 offset:52224
	ds_read_b128 v[210:213], v150 offset:53248
	ds_read_b128 v[214:217], v150 offset:54272
	ds_read_b128 v[218:221], v150 offset:55296
	ds_read_b128 v[222:225], v150 offset:56320
	global_load_lds_dwordx4 v[142:143], off
	v_lshl_add_u64 v[142:143], v[168:169], 0, s[16:17]
	s_mov_b32 m0, s49
	s_nop 0
	global_load_lds_dwordx4 v[142:143], off
	v_lshl_add_u64 v[142:143], s[38:39], 0, v[130:131]
	s_mov_b32 m0, s50
	s_nop 0
	global_load_lds_dwordx4 v[142:143], off
	v_lshl_add_u64 v[142:143], s[38:39], 0, v[134:135]
	s_mov_b32 m0, s48
	s_nop 0
	global_load_lds_dwordx4 v[142:143], off
	v_lshl_add_u64 v[142:143], v[226:227], 0, s[16:17]
	s_mov_b32 m0, s73
	s_nop 0
	global_load_lds_dwordx4 v[142:143], off
	v_lshl_add_u64 v[142:143], v[228:229], 0, s[16:17]
	s_mov_b32 m0, s74
	s_nop 0
	global_load_lds_dwordx4 v[142:143], off
	s_waitcnt vmcnt(8)
	s_waitcnt lgkmcnt(0)
	s_barrier
	s_setprio 1
	s_waitcnt lgkmcnt(0)
	v_mfma_f32_16x16x32_bf16 v[60:63], v[152:155], v[192:195], v[60:63]
	v_mfma_f32_16x16x32_bf16 v[56:59], v[160:163], v[192:195], v[56:59]
	v_mfma_f32_16x16x32_bf16 v[40:43], v[160:163], v[202:205], v[40:43]
	v_mfma_f32_16x16x32_bf16 v[48:51], v[152:155], v[202:205], v[48:51]
	v_mfma_f32_16x16x32_bf16 v[32:35], v[152:155], v[210:213], v[32:35]
	v_mfma_f32_16x16x32_bf16 v[24:27], v[160:163], v[210:213], v[24:27]
	v_mfma_f32_16x16x32_bf16 v[8:11], v[160:163], v[218:221], v[8:11]
	v_mfma_f32_16x16x32_bf16 v[16:19], v[152:155], v[218:221], v[16:19]
	v_mfma_f32_16x16x32_bf16 v[60:63], v[156:159], v[196:199], v[60:63]
	v_mfma_f32_16x16x32_bf16 v[56:59], v[164:167], v[196:199], v[56:59]
	v_mfma_f32_16x16x32_bf16 v[40:43], v[164:167], v[206:209], v[40:43]
	v_mfma_f32_16x16x32_bf16 v[48:51], v[156:159], v[206:209], v[48:51]
	v_mfma_f32_16x16x32_bf16 v[32:35], v[156:159], v[214:217], v[32:35]
	v_mfma_f32_16x16x32_bf16 v[24:27], v[164:167], v[214:217], v[24:27]
	v_mfma_f32_16x16x32_bf16 v[8:11], v[164:167], v[222:225], v[8:11]
	v_mfma_f32_16x16x32_bf16 v[16:19], v[156:159], v[222:225], v[16:19]
	s_setprio 0
	s_setprio 1
	v_mfma_f32_16x16x32_bf16 v[52:55], v[176:179], v[192:195], v[52:55]
	v_mfma_f32_16x16x32_bf16 v[44:47], v[184:187], v[192:195], v[44:47]
	v_mfma_f32_16x16x32_bf16 v[28:31], v[184:187], v[202:205], v[28:31]
	v_mfma_f32_16x16x32_bf16 v[36:39], v[176:179], v[202:205], v[36:39]
	v_mfma_f32_16x16x32_bf16 v[20:23], v[176:179], v[210:213], v[20:23]
	v_mfma_f32_16x16x32_bf16 v[12:15], v[184:187], v[210:213], v[12:15]
	v_mfma_f32_16x16x32_bf16 v[0:3], v[184:187], v[218:221], v[0:3]
	v_mfma_f32_16x16x32_bf16 v[4:7], v[176:179], v[218:221], v[4:7]
	v_mfma_f32_16x16x32_bf16 v[52:55], v[180:183], v[196:199], v[52:55]
	v_mfma_f32_16x16x32_bf16 v[44:47], v[188:191], v[196:199], v[44:47]
	v_mfma_f32_16x16x32_bf16 v[28:31], v[188:191], v[206:209], v[28:31]
	v_mfma_f32_16x16x32_bf16 v[36:39], v[180:183], v[206:209], v[36:39]
	v_mfma_f32_16x16x32_bf16 v[20:23], v[180:183], v[214:217], v[20:23]
	v_mfma_f32_16x16x32_bf16 v[12:15], v[188:191], v[214:217], v[12:15]
	v_mfma_f32_16x16x32_bf16 v[0:3], v[188:191], v[222:225], v[0:3]
	v_mfma_f32_16x16x32_bf16 v[4:7], v[180:183], v[222:225], v[4:7]
	s_setprio 0
	s_barrier
	s_movk_i32 s42, 0x100
	s_andn2_b64 vcc, exec, s[36:37]
	s_mov_b64 s[38:39], -1
	s_mov_b64 s[36:37], 0
	s_cbranch_vccz .LBB0_1012
	s_and_b64 vcc, exec, s[18:19]
	s_cbranch_vccz .LBB0_1015
	s_barrier

; #define PG8_STAGE(bufoff, gbase, voff) do { _Pragma("unroll") for (int _i = 0; _i < 2; ++_i) \
;         __builtin_amdgcn_global_load_lds((const unsigned*)((const char*)(gbase) + (voff)[_i]), (PG8_LAS unsigned*)(lds + (bufoff) + ldsw + _i * 8192), 16, 0, 0); } while (0)
; #define PG8_LDA(dst, b, h) do { _Pragma("unroll") for (int m = 0; m < 4; ++m) _Pragma("unroll") for (int k = 0; k < 2; ++k) dst[m][k] = *(const PG8_LAS bf16x8*)(lds + PG8_SA(b, h) + aoff + m * 2048 + k * 1024); } while (0)
; #define PG8_LDB(dst, b, h) do { _Pragma("unroll") for (int n = 0; n < 2; ++n) _Pragma("unroll") for (int k = 0; k < 2; ++k) dst[n][k] = *(const PG8_LAS bf16x8*)(lds + PG8_SB(b, h) + boff + n * 2048 + k * 1024); } while (0)
; #define PG8_WAIT_V(n) asm volatile("s_waitcnt vmcnt(" #n ")" ::: "memory")
; #define PG8_WAIT_L(n) asm volatile("s_waitcnt lgkmcnt(" #n ")" ::: "memory")
; #define PG8_BAR __builtin_amdgcn_s_barrier()
; #define PG8_SCHED __builtin_amdgcn_sched_barrier(0)
; template <class Epi, class Sched, bool ALIGN_EPI = false, bool SP2 = false>
; __device__ __forceinline__ void gemm_phase(PG8_LAS unsigned char* lds, const Gemm g, const Sched& S, const Epi& E) {
;     ...
;         const char* nA = has_next ? (const char*)g.A + (size_t)nxt.pm * tstep : cA; const char* nB = has_next ? (const char*)g.Bt + (size_t)nxt.pn * tstep : cB;
;         for (int t = 0; t < nt; t += 2) {
;             const bool last = (t == nt - 2);
;             const char* a1 = cA + (size_t)(t + 1) * kstep;
;             const char* a2 = last ? nA : cA + (size_t)(t + 2) * kstep; const char* b2 = last ? nB : cB + (size_t)(t + 2) * kstep;
;             const char* a3 = a2 + kstep; const char* b3 = b2 + kstep;
;             if (last && has_next) S.a_ready(nxt);
;             if constexpr (SP2) {
;             PG8_LDB(B0, 0, 0); PG8_LDB(B1, 0, 1); PG8_SCHED; PG8_LDA(At, 0, 0); PG8_STAGE(PG8_SA(1, 1), a1 + hstep, voffA);
;             PG8_WAIT_V(8); PG8_WAIT_L(0); PG8_BAR; PG8_MMA(0, 0, At, B0); PG8_MMA(0, 1, At, B1); PG8_BAR; PG8_SCHED;
;             PG8_LDA(At, 0, 1); PG8_STAGE(PG8_SB(0, 0), b2, voffB); PG8_STAGE(PG8_SB(0, 1), b2 + hstepB, voffB); PG8_STAGE(PG8_SA(0, 0), a2, voffA);
;             PG8_WAIT_V(8); PG8_WAIT_L(0); PG8_BAR; PG8_MMA(1, 0, At, B0); PG8_MMA(1, 1, At, B1); PG8_BAR; PG8_SCHED;
.LBB0_1036:
	s_add_u32 s37, s28, s36
	s_addc_u32 s48, s29, 0
	s_add_u32 s42, s37, 0x100
	s_addc_u32 s43, s48, 0
	s_and_b64 s[38:39], s[34:35], exec
	s_cselect_b32 s39, s19, s43
	s_cselect_b32 s38, s40, s42
	s_add_u32 s36, s26, s36
	s_addc_u32 s42, s27, 0
	s_add_u32 s36, s36, 0x100
	s_addc_u32 s42, s42, 0
	s_and_b64 s[34:35], s[34:35], exec
	s_cselect_b32 s43, s17, s42
	s_cselect_b32 s42, s41, s36
	s_add_u32 s60, s37, 0x10080
	ds_read_b128 v[152:155], v148
	ds_read_b128 v[156:159], v148 offset:1024
	ds_read_b128 v[160:163], v148 offset:2048
	ds_read_b128 v[164:167], v148 offset:3072
	ds_read_b128 v[176:179], v149
	ds_read_b128 v[180:183], v149 offset:1024
	ds_read_b128 v[184:187], v149 offset:2048
	ds_read_b128 v[188:191], v149 offset:3072
	s_addc_u32 s61, s48, 0
	s_add_i32 s90, s73, s63
	s_add_i32 m0, s25, 0xc000
	s_add_i32 s91, s25, 0xe000
	s_add_i32 s56, s90, 0x2000
	s_add_u32 s58, s42, 0x4000
	s_addc_u32 s59, s43, 0
	s_add_i32 s78, s74, s63
	s_add_i32 s57, s78, 0x2000
	s_add_i32 s55, 0, 0x18000
	s_add_i32 s54, 0, 0x1c000
	s_add_u32 s36, s38, 0x10000
	s_addc_u32 s37, s39, 0
	s_add_i32 s51, s55, s63
	s_add_i32 s49, s51, 0x2000
	s_add_u32 s34, s42, 0x4080
	s_addc_u32 s35, s43, 0
	s_add_i32 s50, s54, s63
	s_add_i32 s48, s50, 0x2000
	v_lshl_add_u64 v[142:143], s[60:61], 0, v[128:129]
	ds_read_b128 v[192:195], v150
	ds_read_b128 v[196:199], v150 offset:1024
	ds_read_b128 v[202:205], v150 offset:2048
	ds_read_b128 v[206:209], v150 offset:3072
	ds_read_b128 v[210:213], v150 offset:4096
	ds_read_b128 v[214:217], v150 offset:5120
	ds_read_b128 v[218:221], v150 offset:6144
	ds_read_b128 v[222:225], v150 offset:7168
	global_load_lds_dwordx4 v[142:143], off
	v_lshl_add_u64 v[142:143], s[60:61], 0, v[132:133]
	s_mov_b32 m0, s91
	s_nop 0
	global_load_lds_dwordx4 v[142:143], off
	s_waitcnt vmcnt(8)
	s_waitcnt lgkmcnt(0)
	s_barrier
	s_setprio 1
	s_waitcnt lgkmcnt(0)
	v_mfma_f32_16x16x32_bf16 v[124:127], v[152:155], v[192:195], v[124:127]
	v_mfma_f32_16x16x32_bf16 v[120:123], v[160:163], v[192:195], v[120:123]
	v_mfma_f32_16x16x32_bf16 v[108:111], v[160:163], v[202:205], v[108:111]
	v_mfma_f32_16x16x32_bf16 v[116:119], v[152:155], v[202:205], v[116:119]
	v_mfma_f32_16x16x32_bf16 v[96:99], v[152:155], v[210:213], v[96:99]
	v_mfma_f32_16x16x32_bf16 v[88:91], v[160:163], v[210:213], v[88:91]
	v_mfma_f32_16x16x32_bf16 v[72:75], v[160:163], v[218:221], v[72:75]
	v_mfma_f32_16x16x32_bf16 v[80:83], v[152:155], v[218:221], v[80:83]
	v_mfma_f32_16x16x32_bf16 v[124:127], v[156:159], v[196:199], v[124:127]
	v_mfma_f32_16x16x32_bf16 v[120:123], v[164:167], v[196:199], v[120:123]
	v_mfma_f32_16x16x32_bf16 v[108:111], v[164:167], v[206:209], v[108:111]
	v_mfma_f32_16x16x32_bf16 v[116:119], v[156:159], v[206:209], v[116:119]
	v_mfma_f32_16x16x32_bf16 v[96:99], v[156:159], v[214:217], v[96:99]
	v_mfma_f32_16x16x32_bf16 v[88:91], v[164:167], v[214:217], v[88:91]
	v_mfma_f32_16x16x32_bf16 v[72:75], v[164:167], v[222:225], v[72:75]
	v_mfma_f32_16x16x32_bf16 v[80:83], v[156:159], v[222:225], v[80:83]
	s_setprio 0
	s_setprio 1
	v_mfma_f32_16x16x32_bf16 v[112:115], v[176:179], v[192:195], v[112:115]
	v_mfma_f32_16x16x32_bf16 v[104:107], v[184:187], v[192:195], v[104:107]
	v_mfma_f32_16x16x32_bf16 v[92:95], v[184:187], v[202:205], v[92:95]
	v_mfma_f32_16x16x32_bf16 v[100:103], v[176:179], v[202:205], v[100:103]
	v_mfma_f32_16x16x32_bf16 v[84:87], v[176:179], v[210:213], v[84:87]
	v_mfma_f32_16x16x32_bf16 v[76:79], v[184:187], v[210:213], v[76:79]
	v_mfma_f32_16x16x32_bf16 v[64:67], v[184:187], v[218:221], v[64:67]
	v_mfma_f32_16x16x32_bf16 v[68:71], v[176:179], v[218:221], v[68:71]
	v_mfma_f32_16x16x32_bf16 v[112:115], v[180:183], v[196:199], v[112:115]
	v_mfma_f32_16x16x32_bf16 v[104:107], v[188:191], v[196:199], v[104:107]
	v_mfma_f32_16x16x32_bf16 v[92:95], v[188:191], v[206:209], v[92:95]
	v_mfma_f32_16x16x32_bf16 v[100:103], v[180:183], v[206:209], v[100:103]
	v_mfma_f32_16x16x32_bf16 v[84:87], v[180:183], v[214:217], v[84:87]
	v_mfma_f32_16x16x32_bf16 v[76:79], v[188:191], v[214:217], v[76:79]
	v_mfma_f32_16x16x32_bf16 v[64:67], v[188:191], v[222:225], v[64:67]
	v_mfma_f32_16x16x32_bf16 v[68:71], v[180:183], v[222:225], v[68:71]
	s_setprio 0
	s_barrier
	s_mov_b32 m0, s90
	v_lshl_add_u64 v[142:143], s[42:43], 0, v[130:131]
	ds_read_b128 v[192:195], v150 offset:16384
	ds_read_b128 v[196:199], v150 offset:17408
	ds_read_b128 v[202:205], v150 offset:18432
	ds_read_b128 v[206:209], v150 offset:19456
	ds_read_b128 v[210:213], v150 offset:20480
	ds_read_b128 v[214:217], v150 offset:21504
	ds_read_b128 v[218:221], v150 offset:22528
	ds_read_b128 v[222:225], v150 offset:23552
	global_load_lds_dwordx4 v[142:143], off
	v_lshl_add_u64 v[168:169], s[42:43], 0, v[134:135]
	s_mov_b32 m0, s56
	v_lshl_add_u64 v[226:227], s[58:59], 0, v[130:131]
	global_load_lds_dwordx4 v[168:169], off
	s_mov_b32 m0, s78
	v_lshl_add_u64 v[228:229], s[38:39], 0, v[132:133]
	global_load_lds_dwordx4 v[226:227], off
	v_lshl_add_u64 v[226:227], s[58:59], 0, v[134:135]
	s_mov_b32 m0, s57
	s_nop 0
	global_load_lds_dwordx4 v[226:227], off
	v_lshl_add_u64 v[226:227], s[38:39], 0, v[128:129]
	s_mov_b32 m0, s25
	s_nop 0
	global_load_lds_dwordx4 v[226:227], off
	s_mov_b32 m0, s66
	s_nop 0
	global_load_lds_dwordx4 v[228:229], off
	s_waitcnt vmcnt(8)
	s_waitcnt lgkmcnt(0)
	s_barrier
; #define PG8_STAGE(bufoff, gbase, voff) do { _Pragma("unroll") for (int _i = 0; _i < 2; ++_i) \
;         __builtin_amdgcn_global_load_lds((const unsigned*)((const char*)(gbase) + (voff)[_i]), (PG8_LAS unsigned*)(lds + (bufoff) + ldsw + _i * 8192), 16, 0, 0); } while (0)
; #define PG8_LDA(dst, b, h) do { _Pragma("unroll") for (int m = 0; m < 4; ++m) _Pragma("unroll") for (int k = 0; k < 2; ++k) dst[m][k] = *(const PG8_LAS bf16x8*)(lds + PG8_SA(b, h) + aoff + m * 2048 + k * 1024); } while (0)
; #define PG8_LDB(dst, b, h) do { _Pragma("unroll") for (int n = 0; n < 2; ++n) _Pragma("unroll") for (int k = 0; k < 2; ++k) dst[n][k] = *(const PG8_LAS bf16x8*)(lds + PG8_SB(b, h) + boff + n * 2048 + k * 1024); } while (0)
; #define PG8_MMA(ai, bj, At, Bt) do { __builtin_amdgcn_s_setprio(1); _Pragma("unroll") for (int m = 0; m < 4; ++m) _Pragma("unroll") for (int n = 0; n < 2; ++n) _Pragma("unroll") for (int k = 0; k < 2; ++k) \
;         acc[ai][bj][m][n] = __builtin_amdgcn_mfma_f32_16x16x32_bf16(Bt[n][k], At[m][k], acc[ai][bj][m][n], 0, 0, 0); __builtin_amdgcn_s_setprio(0); } while (0)
; #define PG8_WAIT_V(n) asm volatile("s_waitcnt vmcnt(" #n ")" ::: "memory")
; #define PG8_WAIT_L(n) asm volatile("s_waitcnt lgkmcnt(" #n ")" ::: "memory")
; #define PG8_BAR __builtin_amdgcn_s_barrier()
; #define PG8_SCHED __builtin_amdgcn_sched_barrier(0)
; template <class Epi, class Sched, bool ALIGN_EPI = false, bool SP2 = false>
; __device__ __forceinline__ void gemm_phase(PG8_LAS unsigned char* lds, const Gemm g, const Sched& S, const Epi& E) {
;     ...
;             PG8_WAIT_V(8); PG8_WAIT_L(0); PG8_BAR; PG8_MMA(1, 0, At, B0); PG8_MMA(1, 1, At, B1); PG8_BAR; PG8_SCHED;
;             PG8_LDB(B0, 1, 0); PG8_LDB(B1, 1, 1); PG8_SCHED; PG8_LDA(At, 1, 0); PG8_STAGE(PG8_SA(0, 1), a2 + hstep, voffA);
;             PG8_WAIT_V(8); PG8_WAIT_L(0); PG8_BAR; PG8_MMA(0, 0, At, B0); PG8_MMA(0, 1, At, B1); PG8_BAR; PG8_SCHED;
	s_setprio 1
	s_waitcnt lgkmcnt(0)
	v_mfma_f32_16x16x32_bf16 v[60:63], v[152:155], v[192:195], v[60:63]
	v_mfma_f32_16x16x32_bf16 v[56:59], v[160:163], v[192:195], v[56:59]
	v_mfma_f32_16x16x32_bf16 v[40:43], v[160:163], v[202:205], v[40:43]
	v_mfma_f32_16x16x32_bf16 v[48:51], v[152:155], v[202:205], v[48:51]
	v_mfma_f32_16x16x32_bf16 v[32:35], v[152:155], v[210:213], v[32:35]
	v_mfma_f32_16x16x32_bf16 v[24:27], v[160:163], v[210:213], v[24:27]
	v_mfma_f32_16x16x32_bf16 v[8:11], v[160:163], v[218:221], v[8:11]
	v_mfma_f32_16x16x32_bf16 v[16:19], v[152:155], v[218:221], v[16:19]
	v_mfma_f32_16x16x32_bf16 v[60:63], v[156:159], v[196:199], v[60:63]
	v_mfma_f32_16x16x32_bf16 v[56:59], v[164:167], v[196:199], v[56:59]
	v_mfma_f32_16x16x32_bf16 v[40:43], v[164:167], v[206:209], v[40:43]
	v_mfma_f32_16x16x32_bf16 v[48:51], v[156:159], v[206:209], v[48:51]
	v_mfma_f32_16x16x32_bf16 v[32:35], v[156:159], v[214:217], v[32:35]
	v_mfma_f32_16x16x32_bf16 v[24:27], v[164:167], v[214:217], v[24:27]
	v_mfma_f32_16x16x32_bf16 v[8:11], v[164:167], v[222:225], v[8:11]
	v_mfma_f32_16x16x32_bf16 v[16:19], v[156:159], v[222:225], v[16:19]
	s_setprio 0
	s_setprio 1
	v_mfma_f32_16x16x32_bf16 v[52:55], v[176:179], v[192:195], v[52:55]
	v_mfma_f32_16x16x32_bf16 v[44:47], v[184:187], v[192:195], v[44:47]
	v_mfma_f32_16x16x32_bf16 v[28:31], v[184:187], v[202:205], v[28:31]
	v_mfma_f32_16x16x32_bf16 v[36:39], v[176:179], v[202:205], v[36:39]
	v_mfma_f32_16x16x32_bf16 v[20:23], v[176:179], v[210:213], v[20:23]
	v_mfma_f32_16x16x32_bf16 v[12:15], v[184:187], v[210:213], v[12:15]
	v_mfma_f32_16x16x32_bf16 v[0:3], v[184:187], v[218:221], v[0:3]
	v_mfma_f32_16x16x32_bf16 v[4:7], v[176:179], v[218:221], v[4:7]
	v_mfma_f32_16x16x32_bf16 v[52:55], v[180:183], v[196:199], v[52:55]
	v_mfma_f32_16x16x32_bf16 v[44:47], v[188:191], v[196:199], v[44:47]
	v_mfma_f32_16x16x32_bf16 v[28:31], v[188:191], v[206:209], v[28:31]
	v_mfma_f32_16x16x32_bf16 v[36:39], v[180:183], v[206:209], v[36:39]
	v_mfma_f32_16x16x32_bf16 v[20:23], v[180:183], v[214:217], v[20:23]
	v_mfma_f32_16x16x32_bf16 v[12:15], v[188:191], v[214:217], v[12:15]
	v_mfma_f32_16x16x32_bf16 v[0:3], v[188:191], v[222:225], v[0:3]
	v_mfma_f32_16x16x32_bf16 v[4:7], v[180:183], v[222:225], v[4:7]
	s_setprio 0
	s_barrier
	v_add_u32_e32 v151, s55, v144
	ds_read_b128 v[152:155], v151
	ds_read_b128 v[156:159], v151 offset:1024
	ds_read_b128 v[160:163], v151 offset:2048
	ds_read_b128 v[164:167], v151 offset:3072
	v_add_u32_e32 v151, s54, v144
	ds_read_b128 v[176:179], v151
	ds_read_b128 v[180:183], v151 offset:1024
	ds_read_b128 v[184:187], v151 offset:2048
	ds_read_b128 v[188:191], v151 offset:3072
	s_mov_b32 m0, s67
	v_lshl_add_u64 v[230:231], s[36:37], 0, v[128:129]
	ds_read_b128 v[192:195], v150 offset:32768
	ds_read_b128 v[196:199], v150 offset:33792
	ds_read_b128 v[202:205], v150 offset:34816
	ds_read_b128 v[206:209], v150 offset:35840
	ds_read_b128 v[210:213], v150 offset:36864
	ds_read_b128 v[214:217], v150 offset:37888
	ds_read_b128 v[218:221], v150 offset:38912
	ds_read_b128 v[222:225], v150 offset:39936
	global_load_lds_dwordx4 v[230:231], off
	v_lshl_add_u64 v[230:231], s[36:37], 0, v[132:133]
	s_mov_b32 m0, s68
	s_nop 0
	global_load_lds_dwordx4 v[230:231], off
	s_waitcnt vmcnt(8)
	s_waitcnt lgkmcnt(0)
	s_barrier
	s_setprio 1
	s_waitcnt lgkmcnt(0)
	v_mfma_f32_16x16x32_bf16 v[124:127], v[152:155], v[192:195], v[124:127]
	v_mfma_f32_16x16x32_bf16 v[120:123], v[160:163], v[192:195], v[120:123]
	v_mfma_f32_16x16x32_bf16 v[108:111], v[160:163], v[202:205], v[108:111]
	v_mfma_f32_16x16x32_bf16 v[116:119], v[152:155], v[202:205], v[116:119]
	v_mfma_f32_16x16x32_bf16 v[96:99], v[152:155], v[210:213], v[96:99]
	v_mfma_f32_16x16x32_bf16 v[88:91], v[160:163], v[210:213], v[88:91]
	v_mfma_f32_16x16x32_bf16 v[72:75], v[160:163], v[218:221], v[72:75]
	v_mfma_f32_16x16x32_bf16 v[80:83], v[152:155], v[218:221], v[80:83]
	v_mfma_f32_16x16x32_bf16 v[124:127], v[156:159], v[196:199], v[124:127]
	v_mfma_f32_16x16x32_bf16 v[120:123], v[164:167], v[196:199], v[120:123]
	v_mfma_f32_16x16x32_bf16 v[108:111], v[164:167], v[206:209], v[108:111]
	v_mfma_f32_16x16x32_bf16 v[116:119], v[156:159], v[206:209], v[116:119]
	v_mfma_f32_16x16x32_bf16 v[96:99], v[156:159], v[214:217], v[96:99]
	v_mfma_f32_16x16x32_bf16 v[88:91], v[164:167], v[214:217], v[88:91]
	v_mfma_f32_16x16x32_bf16 v[72:75], v[164:167], v[222:225], v[72:75]
	v_mfma_f32_16x16x32_bf16 v[80:83], v[156:159], v[222:225], v[80:83]
	s_setprio 0
	s_setprio 1
	v_mfma_f32_16x16x32_bf16 v[112:115], v[176:179], v[192:195], v[112:115]
	v_mfma_f32_16x16x32_bf16 v[104:107], v[184:187], v[192:195], v[104:107]
	v_mfma_f32_16x16x32_bf16 v[92:95], v[184:187], v[202:205], v[92:95]
	v_mfma_f32_16x16x32_bf16 v[100:103], v[176:179], v[202:205], v[100:103]
	v_mfma_f32_16x16x32_bf16 v[84:87], v[176:179], v[210:213], v[84:87]
	v_mfma_f32_16x16x32_bf16 v[76:79], v[184:187], v[210:213], v[76:79]
	v_mfma_f32_16x16x32_bf16 v[64:67], v[184:187], v[218:221], v[64:67]
	v_mfma_f32_16x16x32_bf16 v[68:71], v[176:179], v[218:221], v[68:71]
	v_mfma_f32_16x16x32_bf16 v[112:115], v[180:183], v[196:199], v[112:115]
	v_mfma_f32_16x16x32_bf16 v[104:107], v[188:191], v[196:199], v[104:107]
	v_mfma_f32_16x16x32_bf16 v[92:95], v[188:191], v[206:209], v[92:95]
	v_mfma_f32_16x16x32_bf16 v[100:103], v[180:183], v[206:209], v[100:103]
	v_mfma_f32_16x16x32_bf16 v[84:87], v[180:183], v[214:217], v[84:87]
	v_mfma_f32_16x16x32_bf16 v[76:79], v[188:191], v[214:217], v[76:79]
	v_mfma_f32_16x16x32_bf16 v[64:67], v[188:191], v[222:225], v[64:67]
	v_mfma_f32_16x16x32_bf16 v[68:71], v[180:183], v[222:225], v[68:71]
	s_setprio 0
	s_barrier
; #define PG8_STAGE(bufoff, gbase, voff) do { _Pragma("unroll") for (int _i = 0; _i < 2; ++_i) \
;         __builtin_amdgcn_global_load_lds((const unsigned*)((const char*)(gbase) + (voff)[_i]), (PG8_LAS unsigned*)(lds + (bufoff) + ldsw + _i * 8192), 16, 0, 0); } while (0)
; #define PG8_LDA(dst, b, h) do { _Pragma("unroll") for (int m = 0; m < 4; ++m) _Pragma("unroll") for (int k = 0; k < 2; ++k) dst[m][k] = *(const PG8_LAS bf16x8*)(lds + PG8_SA(b, h) + aoff + m * 2048 + k * 1024); } while (0)
; #define PG8_MMA(ai, bj, At, Bt) do { __builtin_amdgcn_s_setprio(1); _Pragma("unroll") for (int m = 0; m < 4; ++m) _Pragma("unroll") for (int n = 0; n < 2; ++n) _Pragma("unroll") for (int k = 0; k < 2; ++k) \
;         acc[ai][bj][m][n] = __builtin_amdgcn_mfma_f32_16x16x32_bf16(Bt[n][k], At[m][k], acc[ai][bj][m][n], 0, 0, 0); __builtin_amdgcn_s_setprio(0); } while (0)
; #define PG8_WAIT_V(n) asm volatile("s_waitcnt vmcnt(" #n ")" ::: "memory")
; #define PG8_WAIT_L(n) asm volatile("s_waitcnt lgkmcnt(" #n ")" ::: "memory")
; #define PG8_BAR __builtin_amdgcn_s_barrier()
; #define PG8_SCHED __builtin_amdgcn_sched_barrier(0)
; template <class Epi, class Sched, bool ALIGN_EPI = false, bool SP2 = false>
; __device__ __forceinline__ void gemm_phase(PG8_LAS unsigned char* lds, const Gemm g, const Sched& S, const Epi& E) {
;     ...
;             PG8_LDA(At, 1, 1); PG8_STAGE(PG8_SB(1, 0), b3, voffB); PG8_STAGE(PG8_SB(1, 1), b3 + hstepB, voffB); PG8_STAGE(PG8_SA(1, 0), a3, voffA);
;             PG8_WAIT_V(8); PG8_WAIT_L(0); PG8_BAR; PG8_MMA(1, 0, At, B0); PG8_MMA(1, 1, At, B1); PG8_BAR; PG8_SCHED;
	s_mov_b32 m0, s51
	v_lshl_add_u64 v[142:143], v[142:143], 0, s[12:13]
	ds_read_b128 v[192:195], v150 offset:49152
	ds_read_b128 v[196:199], v150 offset:50176
	ds_read_b128 v[202:205], v150 offset:51200
	ds_read_b128 v[206:209], v150 offset:52224
	ds_read_b128 v[210:213], v150 offset:53248
	ds_read_b128 v[214:217], v150 offset:54272
	ds_read_b128 v[218:221], v150 offset:55296
	ds_read_b128 v[222:225], v150 offset:56320
	global_load_lds_dwordx4 v[142:143], off
	v_lshl_add_u64 v[142:143], v[168:169], 0, s[12:13]
	s_mov_b32 m0, s49
	s_nop 0
	global_load_lds_dwordx4 v[142:143], off
	v_lshl_add_u64 v[142:143], s[34:35], 0, v[130:131]
	s_mov_b32 m0, s50
	s_nop 0
	global_load_lds_dwordx4 v[142:143], off
	v_lshl_add_u64 v[142:143], s[34:35], 0, v[134:135]
	s_mov_b32 m0, s48
	s_nop 0
	global_load_lds_dwordx4 v[142:143], off
	v_lshl_add_u64 v[142:143], v[226:227], 0, s[12:13]
	s_mov_b32 m0, s69
	s_nop 0
	global_load_lds_dwordx4 v[142:143], off
	v_lshl_add_u64 v[142:143], v[228:229], 0, s[12:13]
	s_mov_b32 m0, s70
	s_nop 0
	global_load_lds_dwordx4 v[142:143], off
	s_waitcnt vmcnt(8)
	s_waitcnt lgkmcnt(0)
	s_barrier
	s_setprio 1
	s_waitcnt lgkmcnt(0)
	v_mfma_f32_16x16x32_bf16 v[60:63], v[152:155], v[192:195], v[60:63]
	v_mfma_f32_16x16x32_bf16 v[56:59], v[160:163], v[192:195], v[56:59]
	v_mfma_f32_16x16x32_bf16 v[40:43], v[160:163], v[202:205], v[40:43]
	v_mfma_f32_16x16x32_bf16 v[48:51], v[152:155], v[202:205], v[48:51]
	v_mfma_f32_16x16x32_bf16 v[32:35], v[152:155], v[210:213], v[32:35]
	v_mfma_f32_16x16x32_bf16 v[24:27], v[160:163], v[210:213], v[24:27]
	v_mfma_f32_16x16x32_bf16 v[8:11], v[160:163], v[218:221], v[8:11]
	v_mfma_f32_16x16x32_bf16 v[16:19], v[152:155], v[218:221], v[16:19]
	v_mfma_f32_16x16x32_bf16 v[60:63], v[156:159], v[196:199], v[60:63]
	v_mfma_f32_16x16x32_bf16 v[56:59], v[164:167], v[196:199], v[56:59]
	v_mfma_f32_16x16x32_bf16 v[40:43], v[164:167], v[206:209], v[40:43]
	v_mfma_f32_16x16x32_bf16 v[48:51], v[156:159], v[206:209], v[48:51]
	v_mfma_f32_16x16x32_bf16 v[32:35], v[156:159], v[214:217], v[32:35]
	v_mfma_f32_16x16x32_bf16 v[24:27], v[164:167], v[214:217], v[24:27]
	v_mfma_f32_16x16x32_bf16 v[8:11], v[164:167], v[222:225], v[8:11]
	v_mfma_f32_16x16x32_bf16 v[16:19], v[156:159], v[222:225], v[16:19]
	s_setprio 0
	s_setprio 1
	v_mfma_f32_16x16x32_bf16 v[52:55], v[176:179], v[192:195], v[52:55]
	v_mfma_f32_16x16x32_bf16 v[44:47], v[184:187], v[192:195], v[44:47]
	v_mfma_f32_16x16x32_bf16 v[28:31], v[184:187], v[202:205], v[28:31]
	v_mfma_f32_16x16x32_bf16 v[36:39], v[176:179], v[202:205], v[36:39]
	v_mfma_f32_16x16x32_bf16 v[20:23], v[176:179], v[210:213], v[20:23]
	v_mfma_f32_16x16x32_bf16 v[12:15], v[184:187], v[210:213], v[12:15]
	v_mfma_f32_16x16x32_bf16 v[0:3], v[184:187], v[218:221], v[0:3]
	v_mfma_f32_16x16x32_bf16 v[4:7], v[176:179], v[218:221], v[4:7]
	v_mfma_f32_16x16x32_bf16 v[52:55], v[180:183], v[196:199], v[52:55]
	v_mfma_f32_16x16x32_bf16 v[44:47], v[188:191], v[196:199], v[44:47]
	v_mfma_f32_16x16x32_bf16 v[28:31], v[188:191], v[206:209], v[28:31]
	v_mfma_f32_16x16x32_bf16 v[36:39], v[180:183], v[206:209], v[36:39]
	v_mfma_f32_16x16x32_bf16 v[20:23], v[180:183], v[214:217], v[20:23]
	v_mfma_f32_16x16x32_bf16 v[12:15], v[188:191], v[214:217], v[12:15]
	v_mfma_f32_16x16x32_bf16 v[0:3], v[188:191], v[222:225], v[0:3]
	v_mfma_f32_16x16x32_bf16 v[4:7], v[180:183], v[222:225], v[4:7]
	s_setprio 0
	s_barrier
	s_movk_i32 s36, 0x100
	s_andn2_b64 vcc, exec, s[30:31]
	s_mov_b64 s[34:35], -1
	s_mov_b64 s[30:31], 0
	s_cbranch_vccz .LBB0_1036
	s_and_b64 vcc, exec, s[14:15]
	s_cbranch_vccz .LBB0_1039
	s_barrier

; #define PG8_STAGE(bufoff, gbase, voff) do { _Pragma("unroll") for (int _i = 0; _i < 2; ++_i) \
;         __builtin_amdgcn_global_load_lds((const unsigned*)((const char*)(gbase) + (voff)[_i]), (PG8_LAS unsigned*)(lds + (bufoff) + ldsw + _i * 8192), 16, 0, 0); } while (0)
; #define PG8_LDA(dst, b, h) do { _Pragma("unroll") for (int m = 0; m < 4; ++m) _Pragma("unroll") for (int k = 0; k < 2; ++k) dst[m][k] = *(const PG8_LAS bf16x8*)(lds + PG8_SA(b, h) + aoff + m * 2048 + k * 1024); } while (0)
; #define PG8_LDB(dst, b, h) do { _Pragma("unroll") for (int n = 0; n < 2; ++n) _Pragma("unroll") for (int k = 0; k < 2; ++k) dst[n][k] = *(const PG8_LAS bf16x8*)(lds + PG8_SB(b, h) + boff + n * 2048 + k * 1024); } while (0)
; #define PG8_MMA(ai, bj, At, Bt) do { __builtin_amdgcn_s_setprio(1); _Pragma("unroll") for (int m = 0; m < 4; ++m) _Pragma("unroll") for (int n = 0; n < 2; ++n) _Pragma("unroll") for (int k = 0; k < 2; ++k) \
;         acc[ai][bj][m][n] = __builtin_amdgcn_mfma_f32_16x16x32_bf16(Bt[n][k], At[m][k], acc[ai][bj][m][n], 0, 0, 0); __builtin_amdgcn_s_setprio(0); } while (0)
; #define PG8_WAIT_V(n) asm volatile("s_waitcnt vmcnt(" #n ")" ::: "memory")
; #define PG8_WAIT_L(n) asm volatile("s_waitcnt lgkmcnt(" #n ")" ::: "memory")
; template <class Epi, class Sched, bool ALIGN_EPI = false, bool SP2 = false>
; __device__ __forceinline__ void gemm_phase(PG8_LAS unsigned char* lds, const Gemm g, const Sched& S, const Epi& E) {
;     ...
;             const bool last = (t == nt - 2);
;             const char* a1 = cA + (size_t)(t + 1) * kstep;
;             const char* a2 = last ? nA : cA + (size_t)(t + 2) * kstep; const char* b2 = last ? nB : cB + (size_t)(t + 2) * kstep;
;             const char* a3 = a2 + kstep; const char* b3 = b2 + kstep;
;             if (last && has_next) S.a_ready(nxt);
;             if constexpr (SP2) {
;             PG8_LDB(B0, 0, 0); PG8_LDB(B1, 0, 1); PG8_SCHED; PG8_LDA(At, 0, 0); PG8_STAGE(PG8_SA(1, 1), a1 + hstep, voffA);
;             PG8_WAIT_V(8); PG8_WAIT_L(0); PG8_BAR; PG8_MMA(0, 0, At, B0); PG8_MMA(0, 1, At, B1); PG8_BAR; PG8_SCHED;
;             PG8_LDA(At, 0, 1); PG8_STAGE(PG8_SB(0, 0), b2, voffB); PG8_STAGE(PG8_SB(0, 1), b2 + hstepB, voffB); PG8_STAGE(PG8_SA(0, 0), a2, voffA);
;             PG8_WAIT_V(8); PG8_WAIT_L(0); PG8_BAR; PG8_MMA(1, 0, At, B0); PG8_MMA(1, 1, At, B1); PG8_BAR; PG8_SCHED;
.LBB0_1407:
	ds_read_b128 v[146:149], v156
	ds_read_b128 v[160:163], v156 offset:1024
	ds_read_b128 v[164:167], v156 offset:2048
	ds_read_b128 v[176:179], v156 offset:3072
	ds_read_b128 v[180:183], v157
	ds_read_b128 v[184:187], v157 offset:1024
	ds_read_b128 v[188:191], v157 offset:2048
	ds_read_b128 v[192:195], v157 offset:3072
	s_add_u32 s38, s36, 0xfffc0080
	s_addc_u32 s39, s37, -1
	s_cmp_eq_u32 s50, 12
	s_cselect_b32 s43, s27, s39
	s_cselect_b32 s42, s40, s38
	s_cselect_b32 s39, s25, s49
	s_cselect_b32 s38, s41, s48
	v_lshl_add_u64 v[168:169], s[36:37], 0, v[140:141]
	s_add_i32 m0, s60, 0xc000
	ds_read_b128 v[196:199], v158
	ds_read_b128 v[202:205], v158 offset:1024
	ds_read_b128 v[206:209], v158 offset:2048
	ds_read_b128 v[210:213], v158 offset:3072
	ds_read_b128 v[214:217], v158 offset:4096
	ds_read_b128 v[218:221], v158 offset:5120
	ds_read_b128 v[222:225], v158 offset:6144
	ds_read_b128 v[226:229], v158 offset:7168
	global_load_lds_dwordx4 v[168:169], off
	v_lshl_add_u64 v[168:169], s[36:37], 0, v[138:139]
	s_add_i32 m0, s60, 0xe000
	s_nop 0
	global_load_lds_dwordx4 v[168:169], off
	s_waitcnt vmcnt(8)
	s_waitcnt lgkmcnt(0)
	s_barrier
	s_setprio 1
	s_waitcnt lgkmcnt(0)
	v_mfma_f32_16x16x32_bf16 v[124:127], v[146:149], v[196:199], v[124:127]
	v_mfma_f32_16x16x32_bf16 v[120:123], v[164:167], v[196:199], v[120:123]
	v_mfma_f32_16x16x32_bf16 v[104:107], v[164:167], v[206:209], v[104:107]
	v_mfma_f32_16x16x32_bf16 v[112:115], v[146:149], v[206:209], v[112:115]
	v_mfma_f32_16x16x32_bf16 v[96:99], v[146:149], v[214:217], v[96:99]
	v_mfma_f32_16x16x32_bf16 v[88:91], v[164:167], v[214:217], v[88:91]
	v_mfma_f32_16x16x32_bf16 v[72:75], v[164:167], v[222:225], v[72:75]
	v_mfma_f32_16x16x32_bf16 v[80:83], v[146:149], v[222:225], v[80:83]
	v_mfma_f32_16x16x32_bf16 v[124:127], v[160:163], v[202:205], v[124:127]
	v_mfma_f32_16x16x32_bf16 v[120:123], v[176:179], v[202:205], v[120:123]
	v_mfma_f32_16x16x32_bf16 v[104:107], v[176:179], v[210:213], v[104:107]
	v_mfma_f32_16x16x32_bf16 v[112:115], v[160:163], v[210:213], v[112:115]
	v_mfma_f32_16x16x32_bf16 v[96:99], v[160:163], v[218:221], v[96:99]
	v_mfma_f32_16x16x32_bf16 v[88:91], v[176:179], v[218:221], v[88:91]
	v_mfma_f32_16x16x32_bf16 v[72:75], v[176:179], v[226:229], v[72:75]
	v_mfma_f32_16x16x32_bf16 v[80:83], v[160:163], v[226:229], v[80:83]
	s_setprio 0
	s_setprio 1
	v_mfma_f32_16x16x32_bf16 v[116:119], v[180:183], v[196:199], v[116:119]
	v_mfma_f32_16x16x32_bf16 v[108:111], v[188:191], v[196:199], v[108:111]
	v_mfma_f32_16x16x32_bf16 v[92:95], v[188:191], v[206:209], v[92:95]
	v_mfma_f32_16x16x32_bf16 v[100:103], v[180:183], v[206:209], v[100:103]
	v_mfma_f32_16x16x32_bf16 v[84:87], v[180:183], v[214:217], v[84:87]
	v_mfma_f32_16x16x32_bf16 v[76:79], v[188:191], v[214:217], v[76:79]
	v_mfma_f32_16x16x32_bf16 v[64:67], v[188:191], v[222:225], v[64:67]
	v_mfma_f32_16x16x32_bf16 v[68:71], v[180:183], v[222:225], v[68:71]
	v_mfma_f32_16x16x32_bf16 v[116:119], v[184:187], v[202:205], v[116:119]
	v_mfma_f32_16x16x32_bf16 v[108:111], v[192:195], v[202:205], v[108:111]
	v_mfma_f32_16x16x32_bf16 v[92:95], v[192:195], v[210:213], v[92:95]
	v_mfma_f32_16x16x32_bf16 v[100:103], v[184:187], v[210:213], v[100:103]
	v_mfma_f32_16x16x32_bf16 v[84:87], v[184:187], v[218:221], v[84:87]
	v_mfma_f32_16x16x32_bf16 v[76:79], v[192:195], v[218:221], v[76:79]
	v_mfma_f32_16x16x32_bf16 v[64:67], v[192:195], v[226:229], v[64:67]
	v_mfma_f32_16x16x32_bf16 v[68:71], v[184:187], v[226:229], v[68:71]
	s_setprio 0
	s_barrier
	s_add_i32 s51, s72, s59
	v_lshl_add_u64 v[168:169], s[38:39], 0, v[130:131]
	s_mov_b32 m0, s51
	ds_read_b128 v[196:199], v158 offset:16384
	ds_read_b128 v[202:205], v158 offset:17408
	ds_read_b128 v[206:209], v158 offset:18432
	ds_read_b128 v[210:213], v158 offset:19456
	ds_read_b128 v[214:217], v158 offset:20480
	ds_read_b128 v[218:221], v158 offset:21504
	ds_read_b128 v[222:225], v158 offset:22528
	ds_read_b128 v[226:229], v158 offset:23552
	global_load_lds_dwordx4 v[168:169], off
	s_add_i32 m0, s51, 0x2000
	s_add_u32 s54, s38, 0x10000
	v_lshl_add_u64 v[230:231], s[38:39], 0, v[134:135]
	s_addc_u32 s55, s39, 0
	s_add_i32 s51, s73, s59
	global_load_lds_dwordx4 v[230:231], off
	v_lshl_add_u64 v[232:233], s[54:55], 0, v[130:131]
	s_mov_b32 m0, s51
	v_lshl_add_u64 v[234:235], s[42:43], 0, v[132:133]
	global_load_lds_dwordx4 v[232:233], off
	v_lshl_add_u64 v[232:233], s[54:55], 0, v[134:135]
	s_add_i32 m0, s51, 0x2000
	s_nop 0
	global_load_lds_dwordx4 v[232:233], off
	v_lshl_add_u64 v[232:233], s[42:43], 0, v[128:129]
	s_mov_b32 m0, s60
	s_nop 0
	global_load_lds_dwordx4 v[232:233], off
	s_mov_b32 m0, s61
	s_nop 0
	global_load_lds_dwordx4 v[234:235], off
	s_waitcnt vmcnt(8)
	s_waitcnt lgkmcnt(0)
	s_barrier
; #define PG8_STAGE(bufoff, gbase, voff) do { _Pragma("unroll") for (int _i = 0; _i < 2; ++_i) \
;         __builtin_amdgcn_global_load_lds((const unsigned*)((const char*)(gbase) + (voff)[_i]), (PG8_LAS unsigned*)(lds + (bufoff) + ldsw + _i * 8192), 16, 0, 0); } while (0)
; #define PG8_LDA(dst, b, h) do { _Pragma("unroll") for (int m = 0; m < 4; ++m) _Pragma("unroll") for (int k = 0; k < 2; ++k) dst[m][k] = *(const PG8_LAS bf16x8*)(lds + PG8_SA(b, h) + aoff + m * 2048 + k * 1024); } while (0)
; #define PG8_LDB(dst, b, h) do { _Pragma("unroll") for (int n = 0; n < 2; ++n) _Pragma("unroll") for (int k = 0; k < 2; ++k) dst[n][k] = *(const PG8_LAS bf16x8*)(lds + PG8_SB(b, h) + boff + n * 2048 + k * 1024); } while (0)
; #define PG8_MMA(ai, bj, At, Bt) do { __builtin_amdgcn_s_setprio(1); _Pragma("unroll") for (int m = 0; m < 4; ++m) _Pragma("unroll") for (int n = 0; n < 2; ++n) _Pragma("unroll") for (int k = 0; k < 2; ++k) \
;         acc[ai][bj][m][n] = __builtin_amdgcn_mfma_f32_16x16x32_bf16(Bt[n][k], At[m][k], acc[ai][bj][m][n], 0, 0, 0); __builtin_amdgcn_s_setprio(0); } while (0)
; #define PG8_WAIT_V(n) asm volatile("s_waitcnt vmcnt(" #n ")" ::: "memory")
; #define PG8_WAIT_L(n) asm volatile("s_waitcnt lgkmcnt(" #n ")" ::: "memory")
; #define PG8_BAR __builtin_amdgcn_s_barrier()
; #define PG8_SCHED __builtin_amdgcn_sched_barrier(0)
; template <class Epi, class Sched, bool ALIGN_EPI = false, bool SP2 = false>
; __device__ __forceinline__ void gemm_phase(PG8_LAS unsigned char* lds, const Gemm g, const Sched& S, const Epi& E) {
;     ...
;             PG8_WAIT_V(8); PG8_WAIT_L(0); PG8_BAR; PG8_MMA(1, 0, At, B0); PG8_MMA(1, 1, At, B1); PG8_BAR; PG8_SCHED;
;             PG8_LDB(B0, 1, 0); PG8_LDB(B1, 1, 1); PG8_SCHED; PG8_LDA(At, 1, 0); PG8_STAGE(PG8_SA(0, 1), a2 + hstep, voffA);
;             PG8_WAIT_V(8); PG8_WAIT_L(0); PG8_BAR; PG8_MMA(0, 0, At, B0); PG8_MMA(0, 1, At, B1); PG8_BAR; PG8_SCHED;
	s_setprio 1
	s_waitcnt lgkmcnt(0)
	v_mfma_f32_16x16x32_bf16 v[60:63], v[146:149], v[196:199], v[60:63]
	v_mfma_f32_16x16x32_bf16 v[56:59], v[164:167], v[196:199], v[56:59]
	v_mfma_f32_16x16x32_bf16 v[40:43], v[164:167], v[206:209], v[40:43]
	v_mfma_f32_16x16x32_bf16 v[48:51], v[146:149], v[206:209], v[48:51]
	v_mfma_f32_16x16x32_bf16 v[32:35], v[146:149], v[214:217], v[32:35]
	v_mfma_f32_16x16x32_bf16 v[24:27], v[164:167], v[214:217], v[24:27]
	v_mfma_f32_16x16x32_bf16 v[8:11], v[164:167], v[222:225], v[8:11]
	v_mfma_f32_16x16x32_bf16 v[16:19], v[146:149], v[222:225], v[16:19]
	v_mfma_f32_16x16x32_bf16 v[60:63], v[160:163], v[202:205], v[60:63]
	v_mfma_f32_16x16x32_bf16 v[56:59], v[176:179], v[202:205], v[56:59]
	v_mfma_f32_16x16x32_bf16 v[40:43], v[176:179], v[210:213], v[40:43]
	v_mfma_f32_16x16x32_bf16 v[48:51], v[160:163], v[210:213], v[48:51]
	v_mfma_f32_16x16x32_bf16 v[32:35], v[160:163], v[218:221], v[32:35]
	v_mfma_f32_16x16x32_bf16 v[24:27], v[176:179], v[218:221], v[24:27]
	v_mfma_f32_16x16x32_bf16 v[8:11], v[176:179], v[226:229], v[8:11]
	v_mfma_f32_16x16x32_bf16 v[16:19], v[160:163], v[226:229], v[16:19]
	s_setprio 0
	s_setprio 1
	v_mfma_f32_16x16x32_bf16 v[52:55], v[180:183], v[196:199], v[52:55]
	v_mfma_f32_16x16x32_bf16 v[44:47], v[188:191], v[196:199], v[44:47]
	v_mfma_f32_16x16x32_bf16 v[28:31], v[188:191], v[206:209], v[28:31]
	v_mfma_f32_16x16x32_bf16 v[36:39], v[180:183], v[206:209], v[36:39]
	v_mfma_f32_16x16x32_bf16 v[20:23], v[180:183], v[214:217], v[20:23]
	v_mfma_f32_16x16x32_bf16 v[12:15], v[188:191], v[214:217], v[12:15]
	v_mfma_f32_16x16x32_bf16 v[0:3], v[188:191], v[222:225], v[0:3]
	v_mfma_f32_16x16x32_bf16 v[4:7], v[180:183], v[222:225], v[4:7]
	v_mfma_f32_16x16x32_bf16 v[52:55], v[184:187], v[202:205], v[52:55]
	v_mfma_f32_16x16x32_bf16 v[44:47], v[192:195], v[202:205], v[44:47]
	v_mfma_f32_16x16x32_bf16 v[28:31], v[192:195], v[210:213], v[28:31]
	v_mfma_f32_16x16x32_bf16 v[36:39], v[184:187], v[210:213], v[36:39]
	v_mfma_f32_16x16x32_bf16 v[20:23], v[184:187], v[218:221], v[20:23]
	v_mfma_f32_16x16x32_bf16 v[12:15], v[192:195], v[218:221], v[12:15]
	v_mfma_f32_16x16x32_bf16 v[0:3], v[192:195], v[226:229], v[0:3]
	v_mfma_f32_16x16x32_bf16 v[4:7], v[184:187], v[226:229], v[4:7]
	s_setprio 0
	s_barrier
	s_add_i32 s51, 0, 0x18000
	v_add_u32_e32 v159, s51, v151
	s_add_i32 s54, 0, 0x1c000
	ds_read_b128 v[146:149], v159
	ds_read_b128 v[160:163], v159 offset:1024
	ds_read_b128 v[164:167], v159 offset:2048
	ds_read_b128 v[176:179], v159 offset:3072
	v_add_u32_e32 v159, s54, v151
	ds_read_b128 v[180:183], v159
	ds_read_b128 v[184:187], v159 offset:1024
	ds_read_b128 v[188:191], v159 offset:2048
	ds_read_b128 v[192:195], v159 offset:3072
	s_add_u32 s42, s42, 0x40000
	s_addc_u32 s43, s43, 0
	s_mov_b32 m0, s62
	v_lshl_add_u64 v[236:237], s[42:43], 0, v[128:129]
	ds_read_b128 v[196:199], v158 offset:32768
	ds_read_b128 v[202:205], v158 offset:33792
	ds_read_b128 v[206:209], v158 offset:34816
	ds_read_b128 v[210:213], v158 offset:35840
	ds_read_b128 v[214:217], v158 offset:36864
	ds_read_b128 v[218:221], v158 offset:37888
	ds_read_b128 v[222:225], v158 offset:38912
	ds_read_b128 v[226:229], v158 offset:39936
	global_load_lds_dwordx4 v[236:237], off
	v_lshl_add_u64 v[236:237], s[42:43], 0, v[132:133]
	s_mov_b32 m0, s63
	s_nop 0
	global_load_lds_dwordx4 v[236:237], off
	s_waitcnt vmcnt(8)
	s_waitcnt lgkmcnt(0)
	s_barrier
	s_setprio 1
	s_waitcnt lgkmcnt(0)
	v_mfma_f32_16x16x32_bf16 v[124:127], v[146:149], v[196:199], v[124:127]
	v_mfma_f32_16x16x32_bf16 v[120:123], v[164:167], v[196:199], v[120:123]
	v_mfma_f32_16x16x32_bf16 v[104:107], v[164:167], v[206:209], v[104:107]
	v_mfma_f32_16x16x32_bf16 v[112:115], v[146:149], v[206:209], v[112:115]
	v_mfma_f32_16x16x32_bf16 v[96:99], v[146:149], v[214:217], v[96:99]
	v_mfma_f32_16x16x32_bf16 v[88:91], v[164:167], v[214:217], v[88:91]
	v_mfma_f32_16x16x32_bf16 v[72:75], v[164:167], v[222:225], v[72:75]
	v_mfma_f32_16x16x32_bf16 v[80:83], v[146:149], v[222:225], v[80:83]
	v_mfma_f32_16x16x32_bf16 v[124:127], v[160:163], v[202:205], v[124:127]
	v_mfma_f32_16x16x32_bf16 v[120:123], v[176:179], v[202:205], v[120:123]
	v_mfma_f32_16x16x32_bf16 v[104:107], v[176:179], v[210:213], v[104:107]
	v_mfma_f32_16x16x32_bf16 v[112:115], v[160:163], v[210:213], v[112:115]
	v_mfma_f32_16x16x32_bf16 v[96:99], v[160:163], v[218:221], v[96:99]
	v_mfma_f32_16x16x32_bf16 v[88:91], v[176:179], v[218:221], v[88:91]
	v_mfma_f32_16x16x32_bf16 v[72:75], v[176:179], v[226:229], v[72:75]
	v_mfma_f32_16x16x32_bf16 v[80:83], v[160:163], v[226:229], v[80:83]
	s_setprio 0
	s_setprio 1
	v_mfma_f32_16x16x32_bf16 v[116:119], v[180:183], v[196:199], v[116:119]
	v_mfma_f32_16x16x32_bf16 v[108:111], v[188:191], v[196:199], v[108:111]
	v_mfma_f32_16x16x32_bf16 v[92:95], v[188:191], v[206:209], v[92:95]
	v_mfma_f32_16x16x32_bf16 v[100:103], v[180:183], v[206:209], v[100:103]
	v_mfma_f32_16x16x32_bf16 v[84:87], v[180:183], v[214:217], v[84:87]
	v_mfma_f32_16x16x32_bf16 v[76:79], v[188:191], v[214:217], v[76:79]
	v_mfma_f32_16x16x32_bf16 v[64:67], v[188:191], v[222:225], v[64:67]
	v_mfma_f32_16x16x32_bf16 v[68:71], v[180:183], v[222:225], v[68:71]
	v_mfma_f32_16x16x32_bf16 v[116:119], v[184:187], v[202:205], v[116:119]
	v_mfma_f32_16x16x32_bf16 v[108:111], v[192:195], v[202:205], v[108:111]
	v_mfma_f32_16x16x32_bf16 v[92:95], v[192:195], v[210:213], v[92:95]
	v_mfma_f32_16x16x32_bf16 v[100:103], v[184:187], v[210:213], v[100:103]
	v_mfma_f32_16x16x32_bf16 v[84:87], v[184:187], v[218:221], v[84:87]
	v_mfma_f32_16x16x32_bf16 v[76:79], v[192:195], v[218:221], v[76:79]
	v_mfma_f32_16x16x32_bf16 v[64:67], v[192:195], v[226:229], v[64:67]
	v_mfma_f32_16x16x32_bf16 v[68:71], v[184:187], v[226:229], v[68:71]
	s_setprio 0
	s_barrier
; #define PG8_STAGE(bufoff, gbase, voff) do { _Pragma("unroll") for (int _i = 0; _i < 2; ++_i) \
;         __builtin_amdgcn_global_load_lds((const unsigned*)((const char*)(gbase) + (voff)[_i]), (PG8_LAS unsigned*)(lds + (bufoff) + ldsw + _i * 8192), 16, 0, 0); } while (0)
; #define PG8_LDA(dst, b, h) do { _Pragma("unroll") for (int m = 0; m < 4; ++m) _Pragma("unroll") for (int k = 0; k < 2; ++k) dst[m][k] = *(const PG8_LAS bf16x8*)(lds + PG8_SA(b, h) + aoff + m * 2048 + k * 1024); } while (0)
; #define PG8_MMA(ai, bj, At, Bt) do { __builtin_amdgcn_s_setprio(1); _Pragma("unroll") for (int m = 0; m < 4; ++m) _Pragma("unroll") for (int n = 0; n < 2; ++n) _Pragma("unroll") for (int k = 0; k < 2; ++k) \
;         acc[ai][bj][m][n] = __builtin_amdgcn_mfma_f32_16x16x32_bf16(Bt[n][k], At[m][k], acc[ai][bj][m][n], 0, 0, 0); __builtin_amdgcn_s_setprio(0); } while (0)
; #define PG8_WAIT_V(n) asm volatile("s_waitcnt vmcnt(" #n ")" ::: "memory")
; #define PG8_WAIT_L(n) asm volatile("s_waitcnt lgkmcnt(" #n ")" ::: "memory")
; #define PG8_BAR __builtin_amdgcn_s_barrier()
; #define PG8_SCHED __builtin_amdgcn_sched_barrier(0)
; template <class Epi, class Sched, bool ALIGN_EPI = false, bool SP2 = false>
; __device__ __forceinline__ void gemm_phase(PG8_LAS unsigned char* lds, const Gemm g, const Sched& S, const Epi& E) {
;     ...
;             PG8_LDA(At, 1, 1); PG8_STAGE(PG8_SB(1, 0), b3, voffB); PG8_STAGE(PG8_SB(1, 1), b3 + hstepB, voffB); PG8_STAGE(PG8_SA(1, 0), a3, voffA);
;             PG8_WAIT_V(8); PG8_WAIT_L(0); PG8_BAR; PG8_MMA(1, 0, At, B0); PG8_MMA(1, 1, At, B1); PG8_BAR; PG8_SCHED;
	s_add_i32 s42, s51, s59
	v_lshl_add_u64 v[168:169], v[168:169], 0, s[20:21]
	s_mov_b32 m0, s42
	ds_read_b128 v[196:199], v158 offset:49152
	ds_read_b128 v[202:205], v158 offset:50176
	ds_read_b128 v[206:209], v158 offset:51200
	ds_read_b128 v[210:213], v158 offset:52224
	ds_read_b128 v[214:217], v158 offset:53248
	ds_read_b128 v[218:221], v158 offset:54272
	ds_read_b128 v[222:225], v158 offset:55296
	ds_read_b128 v[226:229], v158 offset:56320
	global_load_lds_dwordx4 v[168:169], off
	s_add_i32 m0, s42, 0x2000
	s_add_u32 s38, s38, 0x10080
	v_lshl_add_u64 v[168:169], v[230:231], 0, s[20:21]
	s_addc_u32 s39, s39, 0
	s_add_i32 s42, s54, s59
	global_load_lds_dwordx4 v[168:169], off
	v_lshl_add_u64 v[168:169], s[38:39], 0, v[130:131]
	s_mov_b32 m0, s42
	s_nop 0
	global_load_lds_dwordx4 v[168:169], off
	v_lshl_add_u64 v[168:169], s[38:39], 0, v[134:135]
	s_add_i32 m0, s42, 0x2000
	s_nop 0
	global_load_lds_dwordx4 v[168:169], off
	v_lshl_add_u64 v[168:169], v[232:233], 0, s[20:21]
	s_mov_b32 m0, s66
	s_nop 0
	global_load_lds_dwordx4 v[168:169], off
	v_lshl_add_u64 v[168:169], v[234:235], 0, s[20:21]
	s_mov_b32 m0, s67
	s_nop 0
	global_load_lds_dwordx4 v[168:169], off
	s_waitcnt vmcnt(8)
	s_waitcnt lgkmcnt(0)
	s_barrier
	s_setprio 1
	s_waitcnt lgkmcnt(0)
	v_mfma_f32_16x16x32_bf16 v[60:63], v[146:149], v[196:199], v[60:63]
	v_mfma_f32_16x16x32_bf16 v[56:59], v[164:167], v[196:199], v[56:59]
	v_mfma_f32_16x16x32_bf16 v[40:43], v[164:167], v[206:209], v[40:43]
	v_mfma_f32_16x16x32_bf16 v[48:51], v[146:149], v[206:209], v[48:51]
	v_mfma_f32_16x16x32_bf16 v[32:35], v[146:149], v[214:217], v[32:35]
	v_mfma_f32_16x16x32_bf16 v[24:27], v[164:167], v[214:217], v[24:27]
	v_mfma_f32_16x16x32_bf16 v[8:11], v[164:167], v[222:225], v[8:11]
	v_mfma_f32_16x16x32_bf16 v[16:19], v[146:149], v[222:225], v[16:19]
	v_mfma_f32_16x16x32_bf16 v[60:63], v[160:163], v[202:205], v[60:63]
	v_mfma_f32_16x16x32_bf16 v[56:59], v[176:179], v[202:205], v[56:59]
	v_mfma_f32_16x16x32_bf16 v[40:43], v[176:179], v[210:213], v[40:43]
	v_mfma_f32_16x16x32_bf16 v[48:51], v[160:163], v[210:213], v[48:51]
	v_mfma_f32_16x16x32_bf16 v[32:35], v[160:163], v[218:221], v[32:35]
	v_mfma_f32_16x16x32_bf16 v[24:27], v[176:179], v[218:221], v[24:27]
	v_mfma_f32_16x16x32_bf16 v[8:11], v[176:179], v[226:229], v[8:11]
	v_mfma_f32_16x16x32_bf16 v[16:19], v[160:163], v[226:229], v[16:19]
	s_setprio 0
	s_setprio 1
	v_mfma_f32_16x16x32_bf16 v[52:55], v[180:183], v[196:199], v[52:55]
	v_mfma_f32_16x16x32_bf16 v[44:47], v[188:191], v[196:199], v[44:47]
	v_mfma_f32_16x16x32_bf16 v[28:31], v[188:191], v[206:209], v[28:31]
	v_mfma_f32_16x16x32_bf16 v[36:39], v[180:183], v[206:209], v[36:39]
	v_mfma_f32_16x16x32_bf16 v[20:23], v[180:183], v[214:217], v[20:23]
	v_mfma_f32_16x16x32_bf16 v[12:15], v[188:191], v[214:217], v[12:15]
	v_mfma_f32_16x16x32_bf16 v[0:3], v[188:191], v[222:225], v[0:3]
	v_mfma_f32_16x16x32_bf16 v[4:7], v[180:183], v[222:225], v[4:7]
	v_mfma_f32_16x16x32_bf16 v[52:55], v[184:187], v[202:205], v[52:55]
	v_mfma_f32_16x16x32_bf16 v[44:47], v[192:195], v[202:205], v[44:47]
	v_mfma_f32_16x16x32_bf16 v[28:31], v[192:195], v[210:213], v[28:31]
	v_mfma_f32_16x16x32_bf16 v[36:39], v[184:187], v[210:213], v[36:39]
	v_mfma_f32_16x16x32_bf16 v[20:23], v[184:187], v[218:221], v[20:23]
	v_mfma_f32_16x16x32_bf16 v[12:15], v[192:195], v[218:221], v[12:15]
	v_mfma_f32_16x16x32_bf16 v[0:3], v[192:195], v[226:229], v[0:3]
	v_mfma_f32_16x16x32_bf16 v[4:7], v[184:187], v[226:229], v[4:7]
	s_setprio 0
	s_barrier
	s_add_i32 s50, s50, 2
	s_add_u32 s48, s48, 0x100
	s_addc_u32 s49, s49, 0
	s_add_u32 s36, s36, 0x100
	s_addc_u32 s37, s37, 0
	s_cmp_gt_u32 s50, 13
	s_cbranch_scc0 .LBB0_1407
	s_and_b64 vcc, exec, s[22:23]
	s_cbranch_vccz .LBB0_1410
	s_barrier

; #define PG8_STAGE(bufoff, gbase, voff) do { _Pragma("unroll") for (int _i = 0; _i < 2; ++_i) \
;         __builtin_amdgcn_global_load_lds((const unsigned*)((const char*)(gbase) + (voff)[_i]), (PG8_LAS unsigned*)(lds + (bufoff) + ldsw + _i * 8192), 16, 0, 0); } while (0)
; #define PG8_LDA(dst, b, h) do { _Pragma("unroll") for (int m = 0; m < 4; ++m) _Pragma("unroll") for (int k = 0; k < 2; ++k) dst[m][k] = *(const PG8_LAS bf16x8*)(lds + PG8_SA(b, h) + aoff + m * 2048 + k * 1024); } while (0)
; #define PG8_LDB(dst, b, h) do { _Pragma("unroll") for (int n = 0; n < 2; ++n) _Pragma("unroll") for (int k = 0; k < 2; ++k) dst[n][k] = *(const PG8_LAS bf16x8*)(lds + PG8_SB(b, h) + boff + n * 2048 + k * 1024); } while (0)
; #define PG8_MMA(ai, bj, At, Bt) do { __builtin_amdgcn_s_setprio(1); _Pragma("unroll") for (int m = 0; m < 4; ++m) _Pragma("unroll") for (int n = 0; n < 2; ++n) _Pragma("unroll") for (int k = 0; k < 2; ++k) \
;         acc[ai][bj][m][n] = __builtin_amdgcn_mfma_f32_16x16x32_bf16(Bt[n][k], At[m][k], acc[ai][bj][m][n], 0, 0, 0); __builtin_amdgcn_s_setprio(0); } while (0)
; #define PG8_WAIT_V(n) asm volatile("s_waitcnt vmcnt(" #n ")" ::: "memory")
; #define PG8_WAIT_L(n) asm volatile("s_waitcnt lgkmcnt(" #n ")" ::: "memory")
; template <class Epi, class Sched, bool ALIGN_EPI = false, bool SP2 = false>
; __device__ __forceinline__ void gemm_phase(PG8_LAS unsigned char* lds, const Gemm g, const Sched& S, const Epi& E) {
;     ...
;             const bool last = (t == nt - 2);
;             const char* a1 = cA + (size_t)(t + 1) * kstep;
;             const char* a2 = last ? nA : cA + (size_t)(t + 2) * kstep; const char* b2 = last ? nB : cB + (size_t)(t + 2) * kstep;
;             const char* a3 = a2 + kstep; const char* b3 = b2 + kstep;
;             if (last && has_next) S.a_ready(nxt);
;             if constexpr (SP2) {
;             PG8_LDB(B0, 0, 0); PG8_LDB(B1, 0, 1); PG8_SCHED; PG8_LDA(At, 0, 0); PG8_STAGE(PG8_SA(1, 1), a1 + hstep, voffA);
;             PG8_WAIT_V(8); PG8_WAIT_L(0); PG8_BAR; PG8_MMA(0, 0, At, B0); PG8_MMA(0, 1, At, B1); PG8_BAR; PG8_SCHED;
;             PG8_LDA(At, 0, 1); PG8_STAGE(PG8_SB(0, 0), b2, voffB); PG8_STAGE(PG8_SB(0, 1), b2 + hstepB, voffB); PG8_STAGE(PG8_SA(0, 0), a2, voffA);
;             PG8_WAIT_V(8); PG8_WAIT_L(0); PG8_BAR; PG8_MMA(1, 0, At, B0); PG8_MMA(1, 1, At, B1); PG8_BAR; PG8_SCHED;
.LBB0_1431:
	ds_read_b128 v[146:149], v158
	ds_read_b128 v[162:165], v158 offset:1024
	ds_read_b128 v[166:169], v158 offset:2048
	ds_read_b128 v[176:179], v158 offset:3072
	ds_read_b128 v[180:183], v159
	ds_read_b128 v[184:187], v159 offset:1024
	ds_read_b128 v[188:191], v159 offset:2048
	ds_read_b128 v[192:195], v159 offset:3072
	s_add_u32 s34, s30, 0xfffc0080
	s_addc_u32 s35, s31, -1
	s_cmp_eq_u32 s50, 12
	s_cselect_b32 s37, s23, s35
	s_cselect_b32 s36, s40, s34
	s_cselect_b32 s35, s21, s49
	s_cselect_b32 s34, s41, s48
	v_lshl_add_u64 v[150:151], s[30:31], 0, v[140:141]
	s_add_i32 m0, s58, 0xc000
	ds_read_b128 v[196:199], v160
	ds_read_b128 v[202:205], v160 offset:1024
	ds_read_b128 v[206:209], v160 offset:2048
	ds_read_b128 v[210:213], v160 offset:3072
	ds_read_b128 v[214:217], v160 offset:4096
	ds_read_b128 v[218:221], v160 offset:5120
	ds_read_b128 v[222:225], v160 offset:6144
	ds_read_b128 v[226:229], v160 offset:7168
	global_load_lds_dwordx4 v[150:151], off
	v_lshl_add_u64 v[150:151], s[30:31], 0, v[138:139]
	s_add_i32 m0, s58, 0xe000
	s_nop 0
	global_load_lds_dwordx4 v[150:151], off
	s_waitcnt vmcnt(8)
	s_waitcnt lgkmcnt(0)
	s_barrier
	s_setprio 1
	s_waitcnt lgkmcnt(0)
	v_mfma_f32_16x16x32_bf16 v[124:127], v[146:149], v[196:199], v[124:127]
	v_mfma_f32_16x16x32_bf16 v[120:123], v[166:169], v[196:199], v[120:123]
	v_mfma_f32_16x16x32_bf16 v[104:107], v[166:169], v[206:209], v[104:107]
	v_mfma_f32_16x16x32_bf16 v[108:111], v[146:149], v[206:209], v[108:111]
	v_mfma_f32_16x16x32_bf16 v[92:95], v[146:149], v[214:217], v[92:95]
	v_mfma_f32_16x16x32_bf16 v[88:91], v[166:169], v[214:217], v[88:91]
	v_mfma_f32_16x16x32_bf16 v[72:75], v[166:169], v[222:225], v[72:75]
	v_mfma_f32_16x16x32_bf16 v[76:79], v[146:149], v[222:225], v[76:79]
	v_mfma_f32_16x16x32_bf16 v[124:127], v[162:165], v[202:205], v[124:127]
	v_mfma_f32_16x16x32_bf16 v[120:123], v[176:179], v[202:205], v[120:123]
	v_mfma_f32_16x16x32_bf16 v[104:107], v[176:179], v[210:213], v[104:107]
	v_mfma_f32_16x16x32_bf16 v[108:111], v[162:165], v[210:213], v[108:111]
	v_mfma_f32_16x16x32_bf16 v[92:95], v[162:165], v[218:221], v[92:95]
	v_mfma_f32_16x16x32_bf16 v[88:91], v[176:179], v[218:221], v[88:91]
	v_mfma_f32_16x16x32_bf16 v[72:75], v[176:179], v[226:229], v[72:75]
	v_mfma_f32_16x16x32_bf16 v[76:79], v[162:165], v[226:229], v[76:79]
	s_setprio 0
	s_setprio 1
	v_mfma_f32_16x16x32_bf16 v[116:119], v[180:183], v[196:199], v[116:119]
	v_mfma_f32_16x16x32_bf16 v[112:115], v[188:191], v[196:199], v[112:115]
	v_mfma_f32_16x16x32_bf16 v[96:99], v[188:191], v[206:209], v[96:99]
	v_mfma_f32_16x16x32_bf16 v[100:103], v[180:183], v[206:209], v[100:103]
	v_mfma_f32_16x16x32_bf16 v[84:87], v[180:183], v[214:217], v[84:87]
	v_mfma_f32_16x16x32_bf16 v[80:83], v[188:191], v[214:217], v[80:83]
	v_mfma_f32_16x16x32_bf16 v[64:67], v[188:191], v[222:225], v[64:67]
	v_mfma_f32_16x16x32_bf16 v[68:71], v[180:183], v[222:225], v[68:71]
	v_mfma_f32_16x16x32_bf16 v[116:119], v[184:187], v[202:205], v[116:119]
	v_mfma_f32_16x16x32_bf16 v[112:115], v[192:195], v[202:205], v[112:115]
	v_mfma_f32_16x16x32_bf16 v[96:99], v[192:195], v[210:213], v[96:99]
	v_mfma_f32_16x16x32_bf16 v[100:103], v[184:187], v[210:213], v[100:103]
	v_mfma_f32_16x16x32_bf16 v[84:87], v[184:187], v[218:221], v[84:87]
	v_mfma_f32_16x16x32_bf16 v[80:83], v[192:195], v[218:221], v[80:83]
	v_mfma_f32_16x16x32_bf16 v[64:67], v[192:195], v[226:229], v[64:67]
	v_mfma_f32_16x16x32_bf16 v[68:71], v[184:187], v[226:229], v[68:71]
	s_setprio 0
	s_barrier
	s_add_i32 s51, s70, s38
	v_lshl_add_u64 v[150:151], s[34:35], 0, v[130:131]
	s_mov_b32 m0, s51
	ds_read_b128 v[196:199], v160 offset:16384
	ds_read_b128 v[202:205], v160 offset:17408
	ds_read_b128 v[206:209], v160 offset:18432
	ds_read_b128 v[210:213], v160 offset:19456
	ds_read_b128 v[214:217], v160 offset:20480
	ds_read_b128 v[218:221], v160 offset:21504
	ds_read_b128 v[222:225], v160 offset:22528
	ds_read_b128 v[226:229], v160 offset:23552
	global_load_lds_dwordx4 v[150:151], off
	s_add_i32 m0, s51, 0x2000
	s_add_u32 s54, s34, 0x10000
	v_lshl_add_u64 v[230:231], s[34:35], 0, v[134:135]
	s_addc_u32 s55, s35, 0
	s_add_i32 s51, s71, s38
	global_load_lds_dwordx4 v[230:231], off
	v_lshl_add_u64 v[232:233], s[54:55], 0, v[130:131]
	s_mov_b32 m0, s51
	v_lshl_add_u64 v[234:235], s[36:37], 0, v[132:133]
	global_load_lds_dwordx4 v[232:233], off
	v_lshl_add_u64 v[232:233], s[54:55], 0, v[134:135]
	s_add_i32 m0, s51, 0x2000
	s_nop 0
	global_load_lds_dwordx4 v[232:233], off
	v_lshl_add_u64 v[232:233], s[36:37], 0, v[128:129]
	s_mov_b32 m0, s58
	s_nop 0
	global_load_lds_dwordx4 v[232:233], off
	s_mov_b32 m0, s59
	s_nop 0
	global_load_lds_dwordx4 v[234:235], off
	s_waitcnt vmcnt(8)
	s_waitcnt lgkmcnt(0)
	s_barrier
; #define PG8_STAGE(bufoff, gbase, voff) do { _Pragma("unroll") for (int _i = 0; _i < 2; ++_i) \
;         __builtin_amdgcn_global_load_lds((const unsigned*)((const char*)(gbase) + (voff)[_i]), (PG8_LAS unsigned*)(lds + (bufoff) + ldsw + _i * 8192), 16, 0, 0); } while (0)
; #define PG8_LDA(dst, b, h) do { _Pragma("unroll") for (int m = 0; m < 4; ++m) _Pragma("unroll") for (int k = 0; k < 2; ++k) dst[m][k] = *(const PG8_LAS bf16x8*)(lds + PG8_SA(b, h) + aoff + m * 2048 + k * 1024); } while (0)
; #define PG8_LDB(dst, b, h) do { _Pragma("unroll") for (int n = 0; n < 2; ++n) _Pragma("unroll") for (int k = 0; k < 2; ++k) dst[n][k] = *(const PG8_LAS bf16x8*)(lds + PG8_SB(b, h) + boff + n * 2048 + k * 1024); } while (0)
; #define PG8_MMA(ai, bj, At, Bt) do { __builtin_amdgcn_s_setprio(1); _Pragma("unroll") for (int m = 0; m < 4; ++m) _Pragma("unroll") for (int n = 0; n < 2; ++n) _Pragma("unroll") for (int k = 0; k < 2; ++k) \
;         acc[ai][bj][m][n] = __builtin_amdgcn_mfma_f32_16x16x32_bf16(Bt[n][k], At[m][k], acc[ai][bj][m][n], 0, 0, 0); __builtin_amdgcn_s_setprio(0); } while (0)
; #define PG8_WAIT_V(n) asm volatile("s_waitcnt vmcnt(" #n ")" ::: "memory")
; #define PG8_WAIT_L(n) asm volatile("s_waitcnt lgkmcnt(" #n ")" ::: "memory")
; #define PG8_BAR __builtin_amdgcn_s_barrier()
; #define PG8_SCHED __builtin_amdgcn_sched_barrier(0)
; template <class Epi, class Sched, bool ALIGN_EPI = false, bool SP2 = false>
; __device__ __forceinline__ void gemm_phase(PG8_LAS unsigned char* lds, const Gemm g, const Sched& S, const Epi& E) {
;     ...
;             PG8_WAIT_V(8); PG8_WAIT_L(0); PG8_BAR; PG8_MMA(1, 0, At, B0); PG8_MMA(1, 1, At, B1); PG8_BAR; PG8_SCHED;
;             PG8_LDB(B0, 1, 0); PG8_LDB(B1, 1, 1); PG8_SCHED; PG8_LDA(At, 1, 0); PG8_STAGE(PG8_SA(0, 1), a2 + hstep, voffA);
;             PG8_WAIT_V(8); PG8_WAIT_L(0); PG8_BAR; PG8_MMA(0, 0, At, B0); PG8_MMA(0, 1, At, B1); PG8_BAR; PG8_SCHED;
	s_setprio 1
	s_waitcnt lgkmcnt(0)
	v_mfma_f32_16x16x32_bf16 v[60:63], v[146:149], v[196:199], v[60:63]
	v_mfma_f32_16x16x32_bf16 v[56:59], v[166:169], v[196:199], v[56:59]
	v_mfma_f32_16x16x32_bf16 v[40:43], v[166:169], v[206:209], v[40:43]
	v_mfma_f32_16x16x32_bf16 v[44:47], v[146:149], v[206:209], v[44:47]
	v_mfma_f32_16x16x32_bf16 v[28:31], v[146:149], v[214:217], v[28:31]
	v_mfma_f32_16x16x32_bf16 v[24:27], v[166:169], v[214:217], v[24:27]
	v_mfma_f32_16x16x32_bf16 v[8:11], v[166:169], v[222:225], v[8:11]
	v_mfma_f32_16x16x32_bf16 v[12:15], v[146:149], v[222:225], v[12:15]
	v_mfma_f32_16x16x32_bf16 v[60:63], v[162:165], v[202:205], v[60:63]
	v_mfma_f32_16x16x32_bf16 v[56:59], v[176:179], v[202:205], v[56:59]
	v_mfma_f32_16x16x32_bf16 v[40:43], v[176:179], v[210:213], v[40:43]
	v_mfma_f32_16x16x32_bf16 v[44:47], v[162:165], v[210:213], v[44:47]
	v_mfma_f32_16x16x32_bf16 v[28:31], v[162:165], v[218:221], v[28:31]
	v_mfma_f32_16x16x32_bf16 v[24:27], v[176:179], v[218:221], v[24:27]
	v_mfma_f32_16x16x32_bf16 v[8:11], v[176:179], v[226:229], v[8:11]
	v_mfma_f32_16x16x32_bf16 v[12:15], v[162:165], v[226:229], v[12:15]
	s_setprio 0
	s_setprio 1
	v_mfma_f32_16x16x32_bf16 v[52:55], v[180:183], v[196:199], v[52:55]
	v_mfma_f32_16x16x32_bf16 v[48:51], v[188:191], v[196:199], v[48:51]
	v_mfma_f32_16x16x32_bf16 v[32:35], v[188:191], v[206:209], v[32:35]
	v_mfma_f32_16x16x32_bf16 v[36:39], v[180:183], v[206:209], v[36:39]
	v_mfma_f32_16x16x32_bf16 v[20:23], v[180:183], v[214:217], v[20:23]
	v_mfma_f32_16x16x32_bf16 v[16:19], v[188:191], v[214:217], v[16:19]
	v_mfma_f32_16x16x32_bf16 v[0:3], v[188:191], v[222:225], v[0:3]
	v_mfma_f32_16x16x32_bf16 v[4:7], v[180:183], v[222:225], v[4:7]
	v_mfma_f32_16x16x32_bf16 v[52:55], v[184:187], v[202:205], v[52:55]
	v_mfma_f32_16x16x32_bf16 v[48:51], v[192:195], v[202:205], v[48:51]
	v_mfma_f32_16x16x32_bf16 v[32:35], v[192:195], v[210:213], v[32:35]
	v_mfma_f32_16x16x32_bf16 v[36:39], v[184:187], v[210:213], v[36:39]
	v_mfma_f32_16x16x32_bf16 v[20:23], v[184:187], v[218:221], v[20:23]
	v_mfma_f32_16x16x32_bf16 v[16:19], v[192:195], v[218:221], v[16:19]
	v_mfma_f32_16x16x32_bf16 v[0:3], v[192:195], v[226:229], v[0:3]
	v_mfma_f32_16x16x32_bf16 v[4:7], v[184:187], v[226:229], v[4:7]
	s_setprio 0
	s_barrier
	s_add_i32 s51, 0, 0x18000
	v_add_u32_e32 v161, s51, v153
	s_add_i32 s54, 0, 0x1c000
	ds_read_b128 v[146:149], v161
	ds_read_b128 v[162:165], v161 offset:1024
	ds_read_b128 v[166:169], v161 offset:2048
	ds_read_b128 v[176:179], v161 offset:3072
	v_add_u32_e32 v161, s54, v153
	ds_read_b128 v[180:183], v161
	ds_read_b128 v[184:187], v161 offset:1024
	ds_read_b128 v[188:191], v161 offset:2048
	ds_read_b128 v[192:195], v161 offset:3072
	s_add_u32 s36, s36, 0x40000
	s_addc_u32 s37, s37, 0
	s_mov_b32 m0, s60
	v_lshl_add_u64 v[236:237], s[36:37], 0, v[128:129]
	ds_read_b128 v[196:199], v160 offset:32768
	ds_read_b128 v[202:205], v160 offset:33792
	ds_read_b128 v[206:209], v160 offset:34816
	ds_read_b128 v[210:213], v160 offset:35840
	ds_read_b128 v[214:217], v160 offset:36864
	ds_read_b128 v[218:221], v160 offset:37888
	ds_read_b128 v[222:225], v160 offset:38912
	ds_read_b128 v[226:229], v160 offset:39936
	global_load_lds_dwordx4 v[236:237], off
	v_lshl_add_u64 v[236:237], s[36:37], 0, v[132:133]
	s_mov_b32 m0, s61
	s_nop 0
	global_load_lds_dwordx4 v[236:237], off
	s_waitcnt vmcnt(8)
	s_waitcnt lgkmcnt(0)
	s_barrier
	s_setprio 1
	s_waitcnt lgkmcnt(0)
	v_mfma_f32_16x16x32_bf16 v[124:127], v[146:149], v[196:199], v[124:127]
	v_mfma_f32_16x16x32_bf16 v[120:123], v[166:169], v[196:199], v[120:123]
	v_mfma_f32_16x16x32_bf16 v[104:107], v[166:169], v[206:209], v[104:107]
	v_mfma_f32_16x16x32_bf16 v[108:111], v[146:149], v[206:209], v[108:111]
	v_mfma_f32_16x16x32_bf16 v[92:95], v[146:149], v[214:217], v[92:95]
	v_mfma_f32_16x16x32_bf16 v[88:91], v[166:169], v[214:217], v[88:91]
	v_mfma_f32_16x16x32_bf16 v[72:75], v[166:169], v[222:225], v[72:75]
	v_mfma_f32_16x16x32_bf16 v[76:79], v[146:149], v[222:225], v[76:79]
	v_mfma_f32_16x16x32_bf16 v[124:127], v[162:165], v[202:205], v[124:127]
	v_mfma_f32_16x16x32_bf16 v[120:123], v[176:179], v[202:205], v[120:123]
	v_mfma_f32_16x16x32_bf16 v[104:107], v[176:179], v[210:213], v[104:107]
	v_mfma_f32_16x16x32_bf16 v[108:111], v[162:165], v[210:213], v[108:111]
	v_mfma_f32_16x16x32_bf16 v[92:95], v[162:165], v[218:221], v[92:95]
	v_mfma_f32_16x16x32_bf16 v[88:91], v[176:179], v[218:221], v[88:91]
	v_mfma_f32_16x16x32_bf16 v[72:75], v[176:179], v[226:229], v[72:75]
	v_mfma_f32_16x16x32_bf16 v[76:79], v[162:165], v[226:229], v[76:79]
	s_setprio 0
	s_setprio 1
	v_mfma_f32_16x16x32_bf16 v[116:119], v[180:183], v[196:199], v[116:119]
	v_mfma_f32_16x16x32_bf16 v[112:115], v[188:191], v[196:199], v[112:115]
	v_mfma_f32_16x16x32_bf16 v[96:99], v[188:191], v[206:209], v[96:99]
	v_mfma_f32_16x16x32_bf16 v[100:103], v[180:183], v[206:209], v[100:103]
	v_mfma_f32_16x16x32_bf16 v[84:87], v[180:183], v[214:217], v[84:87]
	v_mfma_f32_16x16x32_bf16 v[80:83], v[188:191], v[214:217], v[80:83]
	v_mfma_f32_16x16x32_bf16 v[64:67], v[188:191], v[222:225], v[64:67]
	v_mfma_f32_16x16x32_bf16 v[68:71], v[180:183], v[222:225], v[68:71]
	v_mfma_f32_16x16x32_bf16 v[116:119], v[184:187], v[202:205], v[116:119]
	v_mfma_f32_16x16x32_bf16 v[112:115], v[192:195], v[202:205], v[112:115]
	v_mfma_f32_16x16x32_bf16 v[96:99], v[192:195], v[210:213], v[96:99]
	v_mfma_f32_16x16x32_bf16 v[100:103], v[184:187], v[210:213], v[100:103]
	v_mfma_f32_16x16x32_bf16 v[84:87], v[184:187], v[218:221], v[84:87]
	v_mfma_f32_16x16x32_bf16 v[80:83], v[192:195], v[218:221], v[80:83]
	v_mfma_f32_16x16x32_bf16 v[64:67], v[192:195], v[226:229], v[64:67]
	v_mfma_f32_16x16x32_bf16 v[68:71], v[184:187], v[226:229], v[68:71]
	s_setprio 0
	s_barrier
; #define PG8_STAGE(bufoff, gbase, voff) do { _Pragma("unroll") for (int _i = 0; _i < 2; ++_i) \
;         __builtin_amdgcn_global_load_lds((const unsigned*)((const char*)(gbase) + (voff)[_i]), (PG8_LAS unsigned*)(lds + (bufoff) + ldsw + _i * 8192), 16, 0, 0); } while (0)
; #define PG8_LDA(dst, b, h) do { _Pragma("unroll") for (int m = 0; m < 4; ++m) _Pragma("unroll") for (int k = 0; k < 2; ++k) dst[m][k] = *(const PG8_LAS bf16x8*)(lds + PG8_SA(b, h) + aoff + m * 2048 + k * 1024); } while (0)
; #define PG8_MMA(ai, bj, At, Bt) do { __builtin_amdgcn_s_setprio(1); _Pragma("unroll") for (int m = 0; m < 4; ++m) _Pragma("unroll") for (int n = 0; n < 2; ++n) _Pragma("unroll") for (int k = 0; k < 2; ++k) \
;         acc[ai][bj][m][n] = __builtin_amdgcn_mfma_f32_16x16x32_bf16(Bt[n][k], At[m][k], acc[ai][bj][m][n], 0, 0, 0); __builtin_amdgcn_s_setprio(0); } while (0)
; #define PG8_WAIT_V(n) asm volatile("s_waitcnt vmcnt(" #n ")" ::: "memory")
; #define PG8_WAIT_L(n) asm volatile("s_waitcnt lgkmcnt(" #n ")" ::: "memory")
; #define PG8_BAR __builtin_amdgcn_s_barrier()
; #define PG8_SCHED __builtin_amdgcn_sched_barrier(0)
; template <class Epi, class Sched, bool ALIGN_EPI = false, bool SP2 = false>
; __device__ __forceinline__ void gemm_phase(PG8_LAS unsigned char* lds, const Gemm g, const Sched& S, const Epi& E) {
;     ...
;             PG8_LDA(At, 1, 1); PG8_STAGE(PG8_SB(1, 0), b3, voffB); PG8_STAGE(PG8_SB(1, 1), b3 + hstepB, voffB); PG8_STAGE(PG8_SA(1, 0), a3, voffA);
;             PG8_WAIT_V(8); PG8_WAIT_L(0); PG8_BAR; PG8_MMA(1, 0, At, B0); PG8_MMA(1, 1, At, B1); PG8_BAR; PG8_SCHED;
;     ...
;         if constexpr (ALIGN_EPI) { if (wr == 0) PG8_BAR; }
	s_add_i32 s36, s51, s38
	v_lshl_add_u64 v[150:151], v[150:151], 0, s[16:17]
	s_mov_b32 m0, s36
	ds_read_b128 v[196:199], v160 offset:49152
	ds_read_b128 v[202:205], v160 offset:50176
	ds_read_b128 v[206:209], v160 offset:51200
	ds_read_b128 v[210:213], v160 offset:52224
	ds_read_b128 v[214:217], v160 offset:53248
	ds_read_b128 v[218:221], v160 offset:54272
	ds_read_b128 v[222:225], v160 offset:55296
	ds_read_b128 v[226:229], v160 offset:56320
	global_load_lds_dwordx4 v[150:151], off
	s_add_i32 m0, s36, 0x2000
	s_add_u32 s34, s34, 0x10080
	v_lshl_add_u64 v[150:151], v[230:231], 0, s[16:17]
	s_addc_u32 s35, s35, 0
	s_add_i32 s36, s54, s38
	global_load_lds_dwordx4 v[150:151], off
	v_lshl_add_u64 v[150:151], s[34:35], 0, v[130:131]
	s_mov_b32 m0, s36
	s_nop 0
	global_load_lds_dwordx4 v[150:151], off
	v_lshl_add_u64 v[150:151], s[34:35], 0, v[134:135]
	s_add_i32 m0, s36, 0x2000
	s_nop 0
	global_load_lds_dwordx4 v[150:151], off
	v_lshl_add_u64 v[150:151], v[232:233], 0, s[16:17]
	s_mov_b32 m0, s64
	s_nop 0
	global_load_lds_dwordx4 v[150:151], off
	v_lshl_add_u64 v[150:151], v[234:235], 0, s[16:17]
	s_mov_b32 m0, s65
	s_nop 0
	global_load_lds_dwordx4 v[150:151], off
	s_waitcnt vmcnt(8)
	s_waitcnt lgkmcnt(0)
	s_barrier
	s_setprio 1
	s_waitcnt lgkmcnt(0)
	v_mfma_f32_16x16x32_bf16 v[60:63], v[146:149], v[196:199], v[60:63]
	v_mfma_f32_16x16x32_bf16 v[56:59], v[166:169], v[196:199], v[56:59]
	v_mfma_f32_16x16x32_bf16 v[40:43], v[166:169], v[206:209], v[40:43]
	v_mfma_f32_16x16x32_bf16 v[44:47], v[146:149], v[206:209], v[44:47]
	v_mfma_f32_16x16x32_bf16 v[28:31], v[146:149], v[214:217], v[28:31]
	v_mfma_f32_16x16x32_bf16 v[24:27], v[166:169], v[214:217], v[24:27]
	v_mfma_f32_16x16x32_bf16 v[8:11], v[166:169], v[222:225], v[8:11]
	v_mfma_f32_16x16x32_bf16 v[12:15], v[146:149], v[222:225], v[12:15]
	v_mfma_f32_16x16x32_bf16 v[60:63], v[162:165], v[202:205], v[60:63]
	v_mfma_f32_16x16x32_bf16 v[56:59], v[176:179], v[202:205], v[56:59]
	v_mfma_f32_16x16x32_bf16 v[40:43], v[176:179], v[210:213], v[40:43]
	v_mfma_f32_16x16x32_bf16 v[44:47], v[162:165], v[210:213], v[44:47]
	v_mfma_f32_16x16x32_bf16 v[28:31], v[162:165], v[218:221], v[28:31]
	v_mfma_f32_16x16x32_bf16 v[24:27], v[176:179], v[218:221], v[24:27]
	v_mfma_f32_16x16x32_bf16 v[8:11], v[176:179], v[226:229], v[8:11]
	v_mfma_f32_16x16x32_bf16 v[12:15], v[162:165], v[226:229], v[12:15]
	s_setprio 0
	s_setprio 1
	v_mfma_f32_16x16x32_bf16 v[52:55], v[180:183], v[196:199], v[52:55]
	v_mfma_f32_16x16x32_bf16 v[48:51], v[188:191], v[196:199], v[48:51]
	v_mfma_f32_16x16x32_bf16 v[32:35], v[188:191], v[206:209], v[32:35]
	v_mfma_f32_16x16x32_bf16 v[36:39], v[180:183], v[206:209], v[36:39]
	v_mfma_f32_16x16x32_bf16 v[20:23], v[180:183], v[214:217], v[20:23]
	v_mfma_f32_16x16x32_bf16 v[16:19], v[188:191], v[214:217], v[16:19]
	v_mfma_f32_16x16x32_bf16 v[0:3], v[188:191], v[222:225], v[0:3]
	v_mfma_f32_16x16x32_bf16 v[4:7], v[180:183], v[222:225], v[4:7]
	v_mfma_f32_16x16x32_bf16 v[52:55], v[184:187], v[202:205], v[52:55]
	v_mfma_f32_16x16x32_bf16 v[48:51], v[192:195], v[202:205], v[48:51]
	v_mfma_f32_16x16x32_bf16 v[32:35], v[192:195], v[210:213], v[32:35]
	v_mfma_f32_16x16x32_bf16 v[36:39], v[184:187], v[210:213], v[36:39]
	v_mfma_f32_16x16x32_bf16 v[20:23], v[184:187], v[218:221], v[20:23]
	v_mfma_f32_16x16x32_bf16 v[16:19], v[192:195], v[218:221], v[16:19]
	v_mfma_f32_16x16x32_bf16 v[0:3], v[192:195], v[226:229], v[0:3]
	v_mfma_f32_16x16x32_bf16 v[4:7], v[184:187], v[226:229], v[4:7]
	s_setprio 0
	s_barrier
	s_add_i32 s50, s50, 2
	s_add_u32 s48, s48, 0x100
	s_addc_u32 s49, s49, 0
	s_add_u32 s30, s30, 0x100
	s_addc_u32 s31, s31, 0
	s_cmp_gt_u32 s50, 13
	s_cbranch_scc0 .LBB0_1431
	s_and_b64 vcc, exec, s[18:19]
	s_cbranch_vccz .LBB0_1434
	s_barrier

; #define PG8_STAGE(bufoff, gbase, voff) do { _Pragma("unroll") for (int _i = 0; _i < 2; ++_i) \
;         __builtin_amdgcn_global_load_lds((const unsigned*)((const char*)(gbase) + (voff)[_i]), (PG8_LAS unsigned*)(lds + (bufoff) + ldsw + _i * 8192), 16, 0, 0); } while (0)
; #define PG8_LDA(dst, b, h) do { _Pragma("unroll") for (int m = 0; m < 4; ++m) _Pragma("unroll") for (int k = 0; k < 2; ++k) dst[m][k] = *(const PG8_LAS bf16x8*)(lds + PG8_SA(b, h) + aoff + m * 2048 + k * 1024); } while (0)
; #define PG8_LDB(dst, b, h) do { _Pragma("unroll") for (int n = 0; n < 2; ++n) _Pragma("unroll") for (int k = 0; k < 2; ++k) dst[n][k] = *(const PG8_LAS bf16x8*)(lds + PG8_SB(b, h) + boff + n * 2048 + k * 1024); } while (0)
; #define PG8_MMA(ai, bj, At, Bt) do { __builtin_amdgcn_s_setprio(1); _Pragma("unroll") for (int m = 0; m < 4; ++m) _Pragma("unroll") for (int n = 0; n < 2; ++n) _Pragma("unroll") for (int k = 0; k < 2; ++k) \
;         acc[ai][bj][m][n] = __builtin_amdgcn_mfma_f32_16x16x32_bf16(Bt[n][k], At[m][k], acc[ai][bj][m][n], 0, 0, 0); __builtin_amdgcn_s_setprio(0); } while (0)
; #define PG8_WAIT_V(n) asm volatile("s_waitcnt vmcnt(" #n ")" ::: "memory")
; #define PG8_WAIT_L(n) asm volatile("s_waitcnt lgkmcnt(" #n ")" ::: "memory")
; #define PG8_BAR __builtin_amdgcn_s_barrier()
; #define PG8_SCHED __builtin_amdgcn_sched_barrier(0)
; template <class Epi, class Sched, bool ALIGN_EPI = false, bool SP2 = false>
; __device__ __forceinline__ void gemm_phase(PG8_LAS unsigned char* lds, const Gemm g, const Sched& S, const Epi& E) {
;     ...
;             const bool last = (t == nt - 2);
;             const char* a1 = cA + (size_t)(t + 1) * kstep;
;             const char* a2 = last ? nA : cA + (size_t)(t + 2) * kstep; const char* b2 = last ? nB : cB + (size_t)(t + 2) * kstep;
;             const char* a3 = a2 + kstep; const char* b3 = b2 + kstep;
;             if (last && has_next) S.a_ready(nxt);
;             if constexpr (SP2) {
;             PG8_LDB(B0, 0, 0); PG8_LDB(B1, 0, 1); PG8_SCHED; PG8_LDA(At, 0, 0); PG8_STAGE(PG8_SA(1, 1), a1 + hstep, voffA);
;             PG8_WAIT_V(8); PG8_WAIT_L(0); PG8_BAR; PG8_MMA(0, 0, At, B0); PG8_MMA(0, 1, At, B1); PG8_BAR; PG8_SCHED;
;             PG8_LDA(At, 0, 1); PG8_STAGE(PG8_SB(0, 0), b2, voffB); PG8_STAGE(PG8_SB(0, 1), b2 + hstepB, voffB); PG8_STAGE(PG8_SA(0, 0), a2, voffA);
.LBB0_1507:
	ds_read_b128 v[156:159], v152
	ds_read_b128 v[160:163], v152 offset:1024
	ds_read_b128 v[164:167], v152 offset:2048
	ds_read_b128 v[176:179], v152 offset:3072
	ds_read_b128 v[180:183], v153
	ds_read_b128 v[184:187], v153 offset:1024
	ds_read_b128 v[188:191], v153 offset:2048
	ds_read_b128 v[192:195], v153 offset:3072
	s_add_u32 s30, s28, 0xfff80080
	s_addc_u32 s31, s29, -1
	s_cmp_eq_u32 s50, 28
	s_cselect_b32 s35, s21, s31
	s_cselect_b32 s34, s40, s30
	s_cselect_b32 s31, s19, s49
	s_cselect_b32 s30, s41, s48
	v_lshl_add_u64 v[146:147], s[28:29], 0, v[140:141]
	s_add_i32 m0, s27, 0xc000
	ds_read_b128 v[196:199], v154
	ds_read_b128 v[202:205], v154 offset:1024
	ds_read_b128 v[206:209], v154 offset:2048
	ds_read_b128 v[210:213], v154 offset:3072
	ds_read_b128 v[214:217], v154 offset:4096
	ds_read_b128 v[218:221], v154 offset:5120
	ds_read_b128 v[222:225], v154 offset:6144
	ds_read_b128 v[226:229], v154 offset:7168
	global_load_lds_dwordx4 v[146:147], off
	v_lshl_add_u64 v[146:147], s[28:29], 0, v[138:139]
	s_add_i32 m0, s27, 0xe000
	s_nop 0
	global_load_lds_dwordx4 v[146:147], off
	s_waitcnt vmcnt(8)
	s_waitcnt lgkmcnt(0)
	s_barrier
	s_setprio 1
	s_waitcnt lgkmcnt(0)
	v_mfma_f32_16x16x32_bf16 v[124:127], v[156:159], v[196:199], v[124:127]
	v_mfma_f32_16x16x32_bf16 v[120:123], v[164:167], v[196:199], v[120:123]
	v_mfma_f32_16x16x32_bf16 v[108:111], v[164:167], v[206:209], v[108:111]
	v_mfma_f32_16x16x32_bf16 v[116:119], v[156:159], v[206:209], v[116:119]
	v_mfma_f32_16x16x32_bf16 v[96:99], v[156:159], v[214:217], v[96:99]
	v_mfma_f32_16x16x32_bf16 v[88:91], v[164:167], v[214:217], v[88:91]
	v_mfma_f32_16x16x32_bf16 v[72:75], v[164:167], v[222:225], v[72:75]
	v_mfma_f32_16x16x32_bf16 v[80:83], v[156:159], v[222:225], v[80:83]
	v_mfma_f32_16x16x32_bf16 v[124:127], v[160:163], v[202:205], v[124:127]
	v_mfma_f32_16x16x32_bf16 v[120:123], v[176:179], v[202:205], v[120:123]
	v_mfma_f32_16x16x32_bf16 v[108:111], v[176:179], v[210:213], v[108:111]
	v_mfma_f32_16x16x32_bf16 v[116:119], v[160:163], v[210:213], v[116:119]
	v_mfma_f32_16x16x32_bf16 v[96:99], v[160:163], v[218:221], v[96:99]
	v_mfma_f32_16x16x32_bf16 v[88:91], v[176:179], v[218:221], v[88:91]
	v_mfma_f32_16x16x32_bf16 v[72:75], v[176:179], v[226:229], v[72:75]
	v_mfma_f32_16x16x32_bf16 v[80:83], v[160:163], v[226:229], v[80:83]
	s_setprio 0
	s_setprio 1
	v_mfma_f32_16x16x32_bf16 v[112:115], v[180:183], v[196:199], v[112:115]
	v_mfma_f32_16x16x32_bf16 v[104:107], v[188:191], v[196:199], v[104:107]
	v_mfma_f32_16x16x32_bf16 v[92:95], v[188:191], v[206:209], v[92:95]
	v_mfma_f32_16x16x32_bf16 v[100:103], v[180:183], v[206:209], v[100:103]
	v_mfma_f32_16x16x32_bf16 v[84:87], v[180:183], v[214:217], v[84:87]
	v_mfma_f32_16x16x32_bf16 v[76:79], v[188:191], v[214:217], v[76:79]
	v_mfma_f32_16x16x32_bf16 v[64:67], v[188:191], v[222:225], v[64:67]
	v_mfma_f32_16x16x32_bf16 v[68:71], v[180:183], v[222:225], v[68:71]
	v_mfma_f32_16x16x32_bf16 v[112:115], v[184:187], v[202:205], v[112:115]
	v_mfma_f32_16x16x32_bf16 v[104:107], v[192:195], v[202:205], v[104:107]
	v_mfma_f32_16x16x32_bf16 v[92:95], v[192:195], v[210:213], v[92:95]
	v_mfma_f32_16x16x32_bf16 v[100:103], v[184:187], v[210:213], v[100:103]
	v_mfma_f32_16x16x32_bf16 v[84:87], v[184:187], v[218:221], v[84:87]
	v_mfma_f32_16x16x32_bf16 v[76:79], v[192:195], v[218:221], v[76:79]
	v_mfma_f32_16x16x32_bf16 v[64:67], v[192:195], v[226:229], v[64:67]
	v_mfma_f32_16x16x32_bf16 v[68:71], v[184:187], v[226:229], v[68:71]
	s_setprio 0
	s_barrier
	s_add_i32 s51, s66, s42
	v_lshl_add_u64 v[146:147], s[30:31], 0, v[130:131]
	s_mov_b32 m0, s51
	ds_read_b128 v[196:199], v154 offset:16384
	ds_read_b128 v[202:205], v154 offset:17408
	ds_read_b128 v[206:209], v154 offset:18432
	ds_read_b128 v[210:213], v154 offset:19456
	ds_read_b128 v[214:217], v154 offset:20480
	ds_read_b128 v[218:221], v154 offset:21504
	ds_read_b128 v[222:225], v154 offset:22528
	ds_read_b128 v[226:229], v154 offset:23552
	global_load_lds_dwordx4 v[146:147], off
	s_add_i32 m0, s51, 0x2000
	s_add_u32 s54, s30, 0x20000
	v_lshl_add_u64 v[168:169], s[30:31], 0, v[134:135]
	s_addc_u32 s55, s31, 0
	s_add_i32 s51, s67, s42
	global_load_lds_dwordx4 v[168:169], off
	v_lshl_add_u64 v[230:231], s[54:55], 0, v[130:131]
	s_mov_b32 m0, s51
	v_lshl_add_u64 v[232:233], s[34:35], 0, v[132:133]
	global_load_lds_dwordx4 v[230:231], off
	v_lshl_add_u64 v[230:231], s[54:55], 0, v[134:135]
	s_add_i32 m0, s51, 0x2000
	s_nop 0
	global_load_lds_dwordx4 v[230:231], off
	v_lshl_add_u64 v[230:231], s[34:35], 0, v[128:129]
	s_mov_b32 m0, s27
	s_nop 0
	global_load_lds_dwordx4 v[230:231], off
	s_mov_b32 m0, s43
	s_nop 0
	global_load_lds_dwordx4 v[232:233], off
	s_waitcnt vmcnt(8)
	s_waitcnt lgkmcnt(0)
	s_barrier
; #define PG8_STAGE(bufoff, gbase, voff) do { _Pragma("unroll") for (int _i = 0; _i < 2; ++_i) \
;         __builtin_amdgcn_global_load_lds((const unsigned*)((const char*)(gbase) + (voff)[_i]), (PG8_LAS unsigned*)(lds + (bufoff) + ldsw + _i * 8192), 16, 0, 0); } while (0)
; #define PG8_LDA(dst, b, h) do { _Pragma("unroll") for (int m = 0; m < 4; ++m) _Pragma("unroll") for (int k = 0; k < 2; ++k) dst[m][k] = *(const PG8_LAS bf16x8*)(lds + PG8_SA(b, h) + aoff + m * 2048 + k * 1024); } while (0)
; #define PG8_LDB(dst, b, h) do { _Pragma("unroll") for (int n = 0; n < 2; ++n) _Pragma("unroll") for (int k = 0; k < 2; ++k) dst[n][k] = *(const PG8_LAS bf16x8*)(lds + PG8_SB(b, h) + boff + n * 2048 + k * 1024); } while (0)
; #define PG8_MMA(ai, bj, At, Bt) do { __builtin_amdgcn_s_setprio(1); _Pragma("unroll") for (int m = 0; m < 4; ++m) _Pragma("unroll") for (int n = 0; n < 2; ++n) _Pragma("unroll") for (int k = 0; k < 2; ++k) \
;         acc[ai][bj][m][n] = __builtin_amdgcn_mfma_f32_16x16x32_bf16(Bt[n][k], At[m][k], acc[ai][bj][m][n], 0, 0, 0); __builtin_amdgcn_s_setprio(0); } while (0)
; #define PG8_WAIT_V(n) asm volatile("s_waitcnt vmcnt(" #n ")" ::: "memory")
; #define PG8_WAIT_L(n) asm volatile("s_waitcnt lgkmcnt(" #n ")" ::: "memory")
; #define PG8_BAR __builtin_amdgcn_s_barrier()
; #define PG8_SCHED __builtin_amdgcn_sched_barrier(0)
; template <class Epi, class Sched, bool ALIGN_EPI = false, bool SP2 = false>
; __device__ __forceinline__ void gemm_phase(PG8_LAS unsigned char* lds, const Gemm g, const Sched& S, const Epi& E) {
;     ...
;             PG8_WAIT_V(8); PG8_WAIT_L(0); PG8_BAR; PG8_MMA(1, 0, At, B0); PG8_MMA(1, 1, At, B1); PG8_BAR; PG8_SCHED;
;             PG8_LDB(B0, 1, 0); PG8_LDB(B1, 1, 1); PG8_SCHED; PG8_LDA(At, 1, 0); PG8_STAGE(PG8_SA(0, 1), a2 + hstep, voffA);
;             PG8_WAIT_V(8); PG8_WAIT_L(0); PG8_BAR; PG8_MMA(0, 0, At, B0); PG8_MMA(0, 1, At, B1); PG8_BAR; PG8_SCHED;
	s_setprio 1
	s_waitcnt lgkmcnt(0)
	v_mfma_f32_16x16x32_bf16 v[60:63], v[156:159], v[196:199], v[60:63]
	v_mfma_f32_16x16x32_bf16 v[56:59], v[164:167], v[196:199], v[56:59]
	v_mfma_f32_16x16x32_bf16 v[40:43], v[164:167], v[206:209], v[40:43]
	v_mfma_f32_16x16x32_bf16 v[48:51], v[156:159], v[206:209], v[48:51]
	v_mfma_f32_16x16x32_bf16 v[32:35], v[156:159], v[214:217], v[32:35]
	v_mfma_f32_16x16x32_bf16 v[24:27], v[164:167], v[214:217], v[24:27]
	v_mfma_f32_16x16x32_bf16 v[8:11], v[164:167], v[222:225], v[8:11]
	v_mfma_f32_16x16x32_bf16 v[16:19], v[156:159], v[222:225], v[16:19]
	v_mfma_f32_16x16x32_bf16 v[60:63], v[160:163], v[202:205], v[60:63]
	v_mfma_f32_16x16x32_bf16 v[56:59], v[176:179], v[202:205], v[56:59]
	v_mfma_f32_16x16x32_bf16 v[40:43], v[176:179], v[210:213], v[40:43]
	v_mfma_f32_16x16x32_bf16 v[48:51], v[160:163], v[210:213], v[48:51]
	v_mfma_f32_16x16x32_bf16 v[32:35], v[160:163], v[218:221], v[32:35]
	v_mfma_f32_16x16x32_bf16 v[24:27], v[176:179], v[218:221], v[24:27]
	v_mfma_f32_16x16x32_bf16 v[8:11], v[176:179], v[226:229], v[8:11]
	v_mfma_f32_16x16x32_bf16 v[16:19], v[160:163], v[226:229], v[16:19]
	s_setprio 0
	s_setprio 1
	v_mfma_f32_16x16x32_bf16 v[52:55], v[180:183], v[196:199], v[52:55]
	v_mfma_f32_16x16x32_bf16 v[44:47], v[188:191], v[196:199], v[44:47]
	v_mfma_f32_16x16x32_bf16 v[28:31], v[188:191], v[206:209], v[28:31]
	v_mfma_f32_16x16x32_bf16 v[36:39], v[180:183], v[206:209], v[36:39]
	v_mfma_f32_16x16x32_bf16 v[20:23], v[180:183], v[214:217], v[20:23]
	v_mfma_f32_16x16x32_bf16 v[12:15], v[188:191], v[214:217], v[12:15]
	v_mfma_f32_16x16x32_bf16 v[0:3], v[188:191], v[222:225], v[0:3]
	v_mfma_f32_16x16x32_bf16 v[4:7], v[180:183], v[222:225], v[4:7]
	v_mfma_f32_16x16x32_bf16 v[52:55], v[184:187], v[202:205], v[52:55]
	v_mfma_f32_16x16x32_bf16 v[44:47], v[192:195], v[202:205], v[44:47]
	v_mfma_f32_16x16x32_bf16 v[28:31], v[192:195], v[210:213], v[28:31]
	v_mfma_f32_16x16x32_bf16 v[36:39], v[184:187], v[210:213], v[36:39]
	v_mfma_f32_16x16x32_bf16 v[20:23], v[184:187], v[218:221], v[20:23]
	v_mfma_f32_16x16x32_bf16 v[12:15], v[192:195], v[218:221], v[12:15]
	v_mfma_f32_16x16x32_bf16 v[0:3], v[192:195], v[226:229], v[0:3]
	v_mfma_f32_16x16x32_bf16 v[4:7], v[184:187], v[226:229], v[4:7]
	s_setprio 0
	s_barrier
	s_add_i32 s51, 0, 0x18000
	v_add_u32_e32 v155, s51, v148
	s_add_i32 s54, 0, 0x1c000
	ds_read_b128 v[156:159], v155
	ds_read_b128 v[160:163], v155 offset:1024
	ds_read_b128 v[164:167], v155 offset:2048
	ds_read_b128 v[176:179], v155 offset:3072
	v_add_u32_e32 v155, s54, v148
	ds_read_b128 v[180:183], v155
	ds_read_b128 v[184:187], v155 offset:1024
	ds_read_b128 v[188:191], v155 offset:2048
	ds_read_b128 v[192:195], v155 offset:3072
	s_add_u32 s34, s34, 0x80000
	s_addc_u32 s35, s35, 0
	s_mov_b32 m0, s53
	v_lshl_add_u64 v[234:235], s[34:35], 0, v[128:129]
	ds_read_b128 v[196:199], v154 offset:32768
	ds_read_b128 v[202:205], v154 offset:33792
	ds_read_b128 v[206:209], v154 offset:34816
	ds_read_b128 v[210:213], v154 offset:35840
	ds_read_b128 v[214:217], v154 offset:36864
	ds_read_b128 v[218:221], v154 offset:37888
	ds_read_b128 v[222:225], v154 offset:38912
	ds_read_b128 v[226:229], v154 offset:39936
	global_load_lds_dwordx4 v[234:235], off
	v_lshl_add_u64 v[234:235], s[34:35], 0, v[132:133]
	s_mov_b32 m0, s58
	s_nop 0
	global_load_lds_dwordx4 v[234:235], off
	s_waitcnt vmcnt(8)
	s_waitcnt lgkmcnt(0)
	s_barrier
	s_setprio 1
	s_waitcnt lgkmcnt(0)
	v_mfma_f32_16x16x32_bf16 v[124:127], v[156:159], v[196:199], v[124:127]
	v_mfma_f32_16x16x32_bf16 v[120:123], v[164:167], v[196:199], v[120:123]
	v_mfma_f32_16x16x32_bf16 v[108:111], v[164:167], v[206:209], v[108:111]
	v_mfma_f32_16x16x32_bf16 v[116:119], v[156:159], v[206:209], v[116:119]
	v_mfma_f32_16x16x32_bf16 v[96:99], v[156:159], v[214:217], v[96:99]
	v_mfma_f32_16x16x32_bf16 v[88:91], v[164:167], v[214:217], v[88:91]
	v_mfma_f32_16x16x32_bf16 v[72:75], v[164:167], v[222:225], v[72:75]
	v_mfma_f32_16x16x32_bf16 v[80:83], v[156:159], v[222:225], v[80:83]
	v_mfma_f32_16x16x32_bf16 v[124:127], v[160:163], v[202:205], v[124:127]
	v_mfma_f32_16x16x32_bf16 v[120:123], v[176:179], v[202:205], v[120:123]
	v_mfma_f32_16x16x32_bf16 v[108:111], v[176:179], v[210:213], v[108:111]
	v_mfma_f32_16x16x32_bf16 v[116:119], v[160:163], v[210:213], v[116:119]
	v_mfma_f32_16x16x32_bf16 v[96:99], v[160:163], v[218:221], v[96:99]
	v_mfma_f32_16x16x32_bf16 v[88:91], v[176:179], v[218:221], v[88:91]
	v_mfma_f32_16x16x32_bf16 v[72:75], v[176:179], v[226:229], v[72:75]
	v_mfma_f32_16x16x32_bf16 v[80:83], v[160:163], v[226:229], v[80:83]
	s_setprio 0
	s_setprio 1
	v_mfma_f32_16x16x32_bf16 v[112:115], v[180:183], v[196:199], v[112:115]
	v_mfma_f32_16x16x32_bf16 v[104:107], v[188:191], v[196:199], v[104:107]
	v_mfma_f32_16x16x32_bf16 v[92:95], v[188:191], v[206:209], v[92:95]
	v_mfma_f32_16x16x32_bf16 v[100:103], v[180:183], v[206:209], v[100:103]
	v_mfma_f32_16x16x32_bf16 v[84:87], v[180:183], v[214:217], v[84:87]
	v_mfma_f32_16x16x32_bf16 v[76:79], v[188:191], v[214:217], v[76:79]
	v_mfma_f32_16x16x32_bf16 v[64:67], v[188:191], v[222:225], v[64:67]
	v_mfma_f32_16x16x32_bf16 v[68:71], v[180:183], v[222:225], v[68:71]
	v_mfma_f32_16x16x32_bf16 v[112:115], v[184:187], v[202:205], v[112:115]
	v_mfma_f32_16x16x32_bf16 v[104:107], v[192:195], v[202:205], v[104:107]
	v_mfma_f32_16x16x32_bf16 v[92:95], v[192:195], v[210:213], v[92:95]
	v_mfma_f32_16x16x32_bf16 v[100:103], v[184:187], v[210:213], v[100:103]
	v_mfma_f32_16x16x32_bf16 v[84:87], v[184:187], v[218:221], v[84:87]
	v_mfma_f32_16x16x32_bf16 v[76:79], v[192:195], v[218:221], v[76:79]
	v_mfma_f32_16x16x32_bf16 v[64:67], v[192:195], v[226:229], v[64:67]
	v_mfma_f32_16x16x32_bf16 v[68:71], v[184:187], v[226:229], v[68:71]
	s_setprio 0
	s_barrier
; #define PG8_STAGE(bufoff, gbase, voff) do { _Pragma("unroll") for (int _i = 0; _i < 2; ++_i) \
;         __builtin_amdgcn_global_load_lds((const unsigned*)((const char*)(gbase) + (voff)[_i]), (PG8_LAS unsigned*)(lds + (bufoff) + ldsw + _i * 8192), 16, 0, 0); } while (0)
; #define PG8_LDA(dst, b, h) do { _Pragma("unroll") for (int m = 0; m < 4; ++m) _Pragma("unroll") for (int k = 0; k < 2; ++k) dst[m][k] = *(const PG8_LAS bf16x8*)(lds + PG8_SA(b, h) + aoff + m * 2048 + k * 1024); } while (0)
; #define PG8_MMA(ai, bj, At, Bt) do { __builtin_amdgcn_s_setprio(1); _Pragma("unroll") for (int m = 0; m < 4; ++m) _Pragma("unroll") for (int n = 0; n < 2; ++n) _Pragma("unroll") for (int k = 0; k < 2; ++k) \
;         acc[ai][bj][m][n] = __builtin_amdgcn_mfma_f32_16x16x32_bf16(Bt[n][k], At[m][k], acc[ai][bj][m][n], 0, 0, 0); __builtin_amdgcn_s_setprio(0); } while (0)
; #define PG8_WAIT_V(n) asm volatile("s_waitcnt vmcnt(" #n ")" ::: "memory")
; #define PG8_WAIT_L(n) asm volatile("s_waitcnt lgkmcnt(" #n ")" ::: "memory")
; #define PG8_BAR __builtin_amdgcn_s_barrier()
; #define PG8_SCHED __builtin_amdgcn_sched_barrier(0)
; template <class Epi, class Sched, bool ALIGN_EPI = false, bool SP2 = false>
; __device__ __forceinline__ void gemm_phase(PG8_LAS unsigned char* lds, const Gemm g, const Sched& S, const Epi& E) {
;     ...
;             PG8_LDA(At, 1, 1); PG8_STAGE(PG8_SB(1, 0), b3, voffB); PG8_STAGE(PG8_SB(1, 1), b3 + hstepB, voffB); PG8_STAGE(PG8_SA(1, 0), a3, voffA);
;             PG8_WAIT_V(8); PG8_WAIT_L(0); PG8_BAR; PG8_MMA(1, 0, At, B0); PG8_MMA(1, 1, At, B1); PG8_BAR; PG8_SCHED;
;     ...
;         if constexpr (ALIGN_EPI) { if (wr == 0) PG8_BAR; }
	s_add_i32 s34, s51, s42
	v_lshl_add_u64 v[146:147], v[146:147], 0, s[14:15]
	s_mov_b32 m0, s34
	ds_read_b128 v[196:199], v154 offset:49152
	ds_read_b128 v[202:205], v154 offset:50176
	ds_read_b128 v[206:209], v154 offset:51200
	ds_read_b128 v[210:213], v154 offset:52224
	ds_read_b128 v[214:217], v154 offset:53248
	ds_read_b128 v[218:221], v154 offset:54272
	ds_read_b128 v[222:225], v154 offset:55296
	ds_read_b128 v[226:229], v154 offset:56320
	global_load_lds_dwordx4 v[146:147], off
	s_add_i32 m0, s34, 0x2000
	s_add_u32 s30, s30, 0x20080
	v_lshl_add_u64 v[146:147], v[168:169], 0, s[14:15]
	s_addc_u32 s31, s31, 0
	s_add_i32 s34, s54, s42
	global_load_lds_dwordx4 v[146:147], off
	v_lshl_add_u64 v[146:147], s[30:31], 0, v[130:131]
	s_mov_b32 m0, s34
	s_nop 0
	global_load_lds_dwordx4 v[146:147], off
	v_lshl_add_u64 v[146:147], s[30:31], 0, v[134:135]
	s_add_i32 m0, s34, 0x2000
	s_nop 0
	global_load_lds_dwordx4 v[146:147], off
	v_lshl_add_u64 v[146:147], v[230:231], 0, s[14:15]
	s_mov_b32 m0, s60
	s_nop 0
	global_load_lds_dwordx4 v[146:147], off
	v_lshl_add_u64 v[146:147], v[232:233], 0, s[14:15]
	s_mov_b32 m0, s61
	s_nop 0
	global_load_lds_dwordx4 v[146:147], off
	s_waitcnt vmcnt(8)
	s_waitcnt lgkmcnt(0)
	s_barrier
	s_setprio 1
	s_waitcnt lgkmcnt(0)
	v_mfma_f32_16x16x32_bf16 v[60:63], v[156:159], v[196:199], v[60:63]
	v_mfma_f32_16x16x32_bf16 v[56:59], v[164:167], v[196:199], v[56:59]
	v_mfma_f32_16x16x32_bf16 v[40:43], v[164:167], v[206:209], v[40:43]
	v_mfma_f32_16x16x32_bf16 v[48:51], v[156:159], v[206:209], v[48:51]
	v_mfma_f32_16x16x32_bf16 v[32:35], v[156:159], v[214:217], v[32:35]
	v_mfma_f32_16x16x32_bf16 v[24:27], v[164:167], v[214:217], v[24:27]
	v_mfma_f32_16x16x32_bf16 v[8:11], v[164:167], v[222:225], v[8:11]
	v_mfma_f32_16x16x32_bf16 v[16:19], v[156:159], v[222:225], v[16:19]
	v_mfma_f32_16x16x32_bf16 v[60:63], v[160:163], v[202:205], v[60:63]
	v_mfma_f32_16x16x32_bf16 v[56:59], v[176:179], v[202:205], v[56:59]
	v_mfma_f32_16x16x32_bf16 v[40:43], v[176:179], v[210:213], v[40:43]
	v_mfma_f32_16x16x32_bf16 v[48:51], v[160:163], v[210:213], v[48:51]
	v_mfma_f32_16x16x32_bf16 v[32:35], v[160:163], v[218:221], v[32:35]
	v_mfma_f32_16x16x32_bf16 v[24:27], v[176:179], v[218:221], v[24:27]
	v_mfma_f32_16x16x32_bf16 v[8:11], v[176:179], v[226:229], v[8:11]
	v_mfma_f32_16x16x32_bf16 v[16:19], v[160:163], v[226:229], v[16:19]
	s_setprio 0
	s_setprio 1
	v_mfma_f32_16x16x32_bf16 v[52:55], v[180:183], v[196:199], v[52:55]
	v_mfma_f32_16x16x32_bf16 v[44:47], v[188:191], v[196:199], v[44:47]
	v_mfma_f32_16x16x32_bf16 v[28:31], v[188:191], v[206:209], v[28:31]
	v_mfma_f32_16x16x32_bf16 v[36:39], v[180:183], v[206:209], v[36:39]
	v_mfma_f32_16x16x32_bf16 v[20:23], v[180:183], v[214:217], v[20:23]
	v_mfma_f32_16x16x32_bf16 v[12:15], v[188:191], v[214:217], v[12:15]
	v_mfma_f32_16x16x32_bf16 v[0:3], v[188:191], v[222:225], v[0:3]
	v_mfma_f32_16x16x32_bf16 v[4:7], v[180:183], v[222:225], v[4:7]
	v_mfma_f32_16x16x32_bf16 v[52:55], v[184:187], v[202:205], v[52:55]
	v_mfma_f32_16x16x32_bf16 v[44:47], v[192:195], v[202:205], v[44:47]
	v_mfma_f32_16x16x32_bf16 v[28:31], v[192:195], v[210:213], v[28:31]
	v_mfma_f32_16x16x32_bf16 v[36:39], v[184:187], v[210:213], v[36:39]
	v_mfma_f32_16x16x32_bf16 v[20:23], v[184:187], v[218:221], v[20:23]
	v_mfma_f32_16x16x32_bf16 v[12:15], v[192:195], v[218:221], v[12:15]
	v_mfma_f32_16x16x32_bf16 v[0:3], v[192:195], v[226:229], v[0:3]
	v_mfma_f32_16x16x32_bf16 v[4:7], v[184:187], v[226:229], v[4:7]
	s_setprio 0
	s_barrier
	s_add_i32 s50, s50, 2
	s_add_u32 s48, s48, 0x100
	s_addc_u32 s49, s49, 0
	s_add_u32 s28, s28, 0x100
	s_addc_u32 s29, s29, 0
	s_cmp_gt_u32 s50, 29
	s_cbranch_scc0 .LBB0_1507
	s_and_b64 vcc, exec, s[16:17]
	s_cbranch_vccz .LBB0_1510
	s_barrier

; #define PG8_STAGE(bufoff, gbase, voff) do { _Pragma("unroll") for (int _i = 0; _i < 2; ++_i) \
;         __builtin_amdgcn_global_load_lds((const unsigned*)((const char*)(gbase) + (voff)[_i]), (PG8_LAS unsigned*)(lds + (bufoff) + ldsw + _i * 8192), 16, 0, 0); } while (0)
; #define PG8_LDA(dst, b, h) do { _Pragma("unroll") for (int m = 0; m < 4; ++m) _Pragma("unroll") for (int k = 0; k < 2; ++k) dst[m][k] = *(const PG8_LAS bf16x8*)(lds + PG8_SA(b, h) + aoff + m * 2048 + k * 1024); } while (0)
; #define PG8_LDB(dst, b, h) do { _Pragma("unroll") for (int n = 0; n < 2; ++n) _Pragma("unroll") for (int k = 0; k < 2; ++k) dst[n][k] = *(const PG8_LAS bf16x8*)(lds + PG8_SB(b, h) + boff + n * 2048 + k * 1024); } while (0)
; #define PG8_MMA(ai, bj, At, Bt) do { __builtin_amdgcn_s_setprio(1); _Pragma("unroll") for (int m = 0; m < 4; ++m) _Pragma("unroll") for (int n = 0; n < 2; ++n) _Pragma("unroll") for (int k = 0; k < 2; ++k) \
;         acc[ai][bj][m][n] = __builtin_amdgcn_mfma_f32_16x16x32_bf16(Bt[n][k], At[m][k], acc[ai][bj][m][n], 0, 0, 0); __builtin_amdgcn_s_setprio(0); } while (0)
; #define PG8_WAIT_V(n) asm volatile("s_waitcnt vmcnt(" #n ")" ::: "memory")
; #define PG8_WAIT_L(n) asm volatile("s_waitcnt lgkmcnt(" #n ")" ::: "memory")
; #define PG8_BAR __builtin_amdgcn_s_barrier()
; #define PG8_SCHED __builtin_amdgcn_sched_barrier(0)
; template <class Epi, class Sched, bool ALIGN_EPI = false, bool SP2 = false>
; __device__ __forceinline__ void gemm_phase(PG8_LAS unsigned char* lds, const Gemm g, const Sched& S, const Epi& E) {
;     ...
;             const bool last = (t == nt - 2);
;             const char* a1 = cA + (size_t)(t + 1) * kstep;
;             const char* a2 = last ? nA : cA + (size_t)(t + 2) * kstep; const char* b2 = last ? nB : cB + (size_t)(t + 2) * kstep;
;             const char* a3 = a2 + kstep; const char* b3 = b2 + kstep;
;             if (last && has_next) S.a_ready(nxt);
;             if constexpr (SP2) {
;             PG8_LDB(B0, 0, 0); PG8_LDB(B1, 0, 1); PG8_SCHED; PG8_LDA(At, 0, 0); PG8_STAGE(PG8_SA(1, 1), a1 + hstep, voffA);
;             PG8_WAIT_V(8); PG8_WAIT_L(0); PG8_BAR; PG8_MMA(0, 0, At, B0); PG8_MMA(0, 1, At, B1); PG8_BAR; PG8_SCHED;
;             PG8_LDA(At, 0, 1); PG8_STAGE(PG8_SB(0, 0), b2, voffB); PG8_STAGE(PG8_SB(0, 1), b2 + hstepB, voffB); PG8_STAGE(PG8_SA(0, 0), a2, voffA);
.LBB0_1632:
	ds_read_b128 v[128:131], v205
	ds_read_b128 v[132:135], v205 offset:1024
	ds_read_b128 v[136:139], v205 offset:2048
	ds_read_b128 v[140:143], v205 offset:3072
	ds_read_b128 v[144:147], v206
	ds_read_b128 v[148:151], v206 offset:1024
	ds_read_b128 v[152:155], v206 offset:2048
	ds_read_b128 v[156:159], v206 offset:3072
	s_add_u32 s59, s12, 0xfff80080
	s_addc_u32 s65, s13, -1
	s_cmp_eq_u32 s57, 28
	s_cselect_b32 s71, s40, s65
	s_cselect_b32 s70, s41, s59
	s_cselect_b32 s69, s48, s51
	s_cselect_b32 s68, s49, s50
	v_lshl_add_u64 v[168:169], s[12:13], 0, v[188:189]
	s_add_i32 m0, s77, 0xc000
	ds_read_b128 v[160:163], v207
	ds_read_b128 v[164:167], v207 offset:1024
	ds_read_b128 v[194:197], v207 offset:2048
	ds_read_b128 v[214:217], v207 offset:3072
	ds_read_b128 v[218:221], v207 offset:4096
	ds_read_b128 v[222:225], v207 offset:5120
	ds_read_b128 v[226:229], v207 offset:6144
	ds_read_b128 v[230:233], v207 offset:7168
	global_load_lds_dwordx4 v[168:169], off
	v_lshl_add_u64 v[168:169], s[12:13], 0, v[186:187]
	s_add_i32 m0, s77, 0xe000
	s_nop 0
	global_load_lds_dwordx4 v[168:169], off
	s_waitcnt vmcnt(8)
	s_waitcnt lgkmcnt(0)
	s_barrier
	s_setprio 1
	s_waitcnt lgkmcnt(0)
	v_mfma_f32_16x16x32_bf16 v[124:127], v[128:131], v[160:163], v[124:127]
	v_mfma_f32_16x16x32_bf16 v[60:63], v[136:139], v[160:163], v[60:63]
	v_mfma_f32_16x16x32_bf16 v[52:55], v[136:139], v[194:197], v[52:55]
	v_mfma_f32_16x16x32_bf16 v[116:119], v[128:131], v[194:197], v[116:119]
	v_mfma_f32_16x16x32_bf16 v[108:111], v[128:131], v[218:221], v[108:111]
	v_mfma_f32_16x16x32_bf16 v[44:47], v[136:139], v[218:221], v[44:47]
	v_mfma_f32_16x16x32_bf16 v[36:39], v[136:139], v[226:229], v[36:39]
	v_mfma_f32_16x16x32_bf16 v[100:103], v[128:131], v[226:229], v[100:103]
	v_mfma_f32_16x16x32_bf16 v[124:127], v[132:135], v[164:167], v[124:127]
	v_mfma_f32_16x16x32_bf16 v[60:63], v[140:143], v[164:167], v[60:63]
	v_mfma_f32_16x16x32_bf16 v[52:55], v[140:143], v[214:217], v[52:55]
	v_mfma_f32_16x16x32_bf16 v[116:119], v[132:135], v[214:217], v[116:119]
	v_mfma_f32_16x16x32_bf16 v[108:111], v[132:135], v[222:225], v[108:111]
	v_mfma_f32_16x16x32_bf16 v[44:47], v[140:143], v[222:225], v[44:47]
	v_mfma_f32_16x16x32_bf16 v[36:39], v[140:143], v[230:233], v[36:39]
	v_mfma_f32_16x16x32_bf16 v[100:103], v[132:135], v[230:233], v[100:103]
	s_setprio 0
	s_setprio 1
	v_mfma_f32_16x16x32_bf16 v[120:123], v[144:147], v[160:163], v[120:123]
	v_mfma_f32_16x16x32_bf16 v[56:59], v[152:155], v[160:163], v[56:59]
	v_mfma_f32_16x16x32_bf16 v[48:51], v[152:155], v[194:197], v[48:51]
	v_mfma_f32_16x16x32_bf16 v[112:115], v[144:147], v[194:197], v[112:115]
	v_mfma_f32_16x16x32_bf16 v[104:107], v[144:147], v[218:221], v[104:107]
	v_mfma_f32_16x16x32_bf16 v[40:43], v[152:155], v[218:221], v[40:43]
	v_mfma_f32_16x16x32_bf16 v[32:35], v[152:155], v[226:229], v[32:35]
	v_mfma_f32_16x16x32_bf16 v[96:99], v[144:147], v[226:229], v[96:99]
	v_mfma_f32_16x16x32_bf16 v[120:123], v[148:151], v[164:167], v[120:123]
	v_mfma_f32_16x16x32_bf16 v[56:59], v[156:159], v[164:167], v[56:59]
	v_mfma_f32_16x16x32_bf16 v[48:51], v[156:159], v[214:217], v[48:51]
	v_mfma_f32_16x16x32_bf16 v[112:115], v[148:151], v[214:217], v[112:115]
	v_mfma_f32_16x16x32_bf16 v[104:107], v[148:151], v[222:225], v[104:107]
	v_mfma_f32_16x16x32_bf16 v[40:43], v[156:159], v[222:225], v[40:43]
	v_mfma_f32_16x16x32_bf16 v[32:35], v[156:159], v[230:233], v[32:35]
	v_mfma_f32_16x16x32_bf16 v[96:99], v[148:151], v[230:233], v[96:99]
	s_setprio 0
	s_barrier
	s_add_i32 s59, s87, s76
	v_lshl_add_u64 v[168:169], s[68:69], 0, v[178:179]
	s_mov_b32 m0, s59
	ds_read_b128 v[160:163], v207 offset:16384
	ds_read_b128 v[164:167], v207 offset:17408
	ds_read_b128 v[194:197], v207 offset:18432
	ds_read_b128 v[214:217], v207 offset:19456
	ds_read_b128 v[218:221], v207 offset:20480
	ds_read_b128 v[222:225], v207 offset:21504
	ds_read_b128 v[226:229], v207 offset:22528
	ds_read_b128 v[230:233], v207 offset:23552
	global_load_lds_dwordx4 v[168:169], off
	s_add_i32 m0, s59, 0x2000
	s_add_u32 s92, s68, 0x20000
	v_lshl_add_u64 v[198:199], s[68:69], 0, v[182:183]
	s_addc_u32 s93, s69, 0
	s_add_i32 s59, s88, s76
	global_load_lds_dwordx4 v[198:199], off
	v_lshl_add_u64 v[234:235], s[92:93], 0, v[178:179]
	s_mov_b32 m0, s59
	v_lshl_add_u64 v[236:237], s[70:71], 0, v[180:181]
	global_load_lds_dwordx4 v[234:235], off
	v_lshl_add_u64 v[234:235], s[92:93], 0, v[182:183]
	s_add_i32 m0, s59, 0x2000
	s_nop 0
	global_load_lds_dwordx4 v[234:235], off
	v_lshl_add_u64 v[234:235], s[70:71], 0, v[176:177]
	s_mov_b32 m0, s77
	s_nop 0
	global_load_lds_dwordx4 v[234:235], off
	s_mov_b32 m0, s79
	s_nop 0
	global_load_lds_dwordx4 v[236:237], off
	s_waitcnt vmcnt(8)
	s_waitcnt lgkmcnt(0)
	s_barrier
; #define PG8_STAGE(bufoff, gbase, voff) do { _Pragma("unroll") for (int _i = 0; _i < 2; ++_i) \
;         __builtin_amdgcn_global_load_lds((const unsigned*)((const char*)(gbase) + (voff)[_i]), (PG8_LAS unsigned*)(lds + (bufoff) + ldsw + _i * 8192), 16, 0, 0); } while (0)
; #define PG8_LDA(dst, b, h) do { _Pragma("unroll") for (int m = 0; m < 4; ++m) _Pragma("unroll") for (int k = 0; k < 2; ++k) dst[m][k] = *(const PG8_LAS bf16x8*)(lds + PG8_SA(b, h) + aoff + m * 2048 + k * 1024); } while (0)
; #define PG8_LDB(dst, b, h) do { _Pragma("unroll") for (int n = 0; n < 2; ++n) _Pragma("unroll") for (int k = 0; k < 2; ++k) dst[n][k] = *(const PG8_LAS bf16x8*)(lds + PG8_SB(b, h) + boff + n * 2048 + k * 1024); } while (0)
; #define PG8_MMA(ai, bj, At, Bt) do { __builtin_amdgcn_s_setprio(1); _Pragma("unroll") for (int m = 0; m < 4; ++m) _Pragma("unroll") for (int n = 0; n < 2; ++n) _Pragma("unroll") for (int k = 0; k < 2; ++k) \
;         acc[ai][bj][m][n] = __builtin_amdgcn_mfma_f32_16x16x32_bf16(Bt[n][k], At[m][k], acc[ai][bj][m][n], 0, 0, 0); __builtin_amdgcn_s_setprio(0); } while (0)
; #define PG8_WAIT_V(n) asm volatile("s_waitcnt vmcnt(" #n ")" ::: "memory")
; #define PG8_WAIT_L(n) asm volatile("s_waitcnt lgkmcnt(" #n ")" ::: "memory")
; #define PG8_BAR __builtin_amdgcn_s_barrier()
; #define PG8_SCHED __builtin_amdgcn_sched_barrier(0)
; template <class Epi, class Sched, bool ALIGN_EPI = false, bool SP2 = false>
; __device__ __forceinline__ void gemm_phase(PG8_LAS unsigned char* lds, const Gemm g, const Sched& S, const Epi& E) {
;     ...
;             PG8_WAIT_V(8); PG8_WAIT_L(0); PG8_BAR; PG8_MMA(1, 0, At, B0); PG8_MMA(1, 1, At, B1); PG8_BAR; PG8_SCHED;
;             PG8_LDB(B0, 1, 0); PG8_LDB(B1, 1, 1); PG8_SCHED; PG8_LDA(At, 1, 0); PG8_STAGE(PG8_SA(0, 1), a2 + hstep, voffA);
;             PG8_WAIT_V(8); PG8_WAIT_L(0); PG8_BAR; PG8_MMA(0, 0, At, B0); PG8_MMA(0, 1, At, B1); PG8_BAR; PG8_SCHED;
	s_setprio 1
	s_waitcnt lgkmcnt(0)
	v_mfma_f32_16x16x32_bf16 v[92:95], v[128:131], v[160:163], v[92:95]
	v_mfma_f32_16x16x32_bf16 v[28:31], v[136:139], v[160:163], v[28:31]
	v_mfma_f32_16x16x32_bf16 v[20:23], v[136:139], v[194:197], v[20:23]
	v_mfma_f32_16x16x32_bf16 v[84:87], v[128:131], v[194:197], v[84:87]
	v_mfma_f32_16x16x32_bf16 v[76:79], v[128:131], v[218:221], v[76:79]
	v_mfma_f32_16x16x32_bf16 v[12:15], v[136:139], v[218:221], v[12:15]
	v_mfma_f32_16x16x32_bf16 v[4:7], v[136:139], v[226:229], v[4:7]
	v_mfma_f32_16x16x32_bf16 v[68:71], v[128:131], v[226:229], v[68:71]
	v_mfma_f32_16x16x32_bf16 v[92:95], v[132:135], v[164:167], v[92:95]
	v_mfma_f32_16x16x32_bf16 v[28:31], v[140:143], v[164:167], v[28:31]
	v_mfma_f32_16x16x32_bf16 v[20:23], v[140:143], v[214:217], v[20:23]
	v_mfma_f32_16x16x32_bf16 v[84:87], v[132:135], v[214:217], v[84:87]
	v_mfma_f32_16x16x32_bf16 v[76:79], v[132:135], v[222:225], v[76:79]
	v_mfma_f32_16x16x32_bf16 v[12:15], v[140:143], v[222:225], v[12:15]
	v_mfma_f32_16x16x32_bf16 v[4:7], v[140:143], v[230:233], v[4:7]
	v_mfma_f32_16x16x32_bf16 v[68:71], v[132:135], v[230:233], v[68:71]
	s_setprio 0
	s_setprio 1
	v_mfma_f32_16x16x32_bf16 v[88:91], v[144:147], v[160:163], v[88:91]
	v_mfma_f32_16x16x32_bf16 v[24:27], v[152:155], v[160:163], v[24:27]
	v_mfma_f32_16x16x32_bf16 v[16:19], v[152:155], v[194:197], v[16:19]
	v_mfma_f32_16x16x32_bf16 v[80:83], v[144:147], v[194:197], v[80:83]
	v_mfma_f32_16x16x32_bf16 v[72:75], v[144:147], v[218:221], v[72:75]
	v_mfma_f32_16x16x32_bf16 v[8:11], v[152:155], v[218:221], v[8:11]
	v_mfma_f32_16x16x32_bf16 v[0:3], v[152:155], v[226:229], v[0:3]
	v_mfma_f32_16x16x32_bf16 v[64:67], v[144:147], v[226:229], v[64:67]
	v_mfma_f32_16x16x32_bf16 v[88:91], v[148:151], v[164:167], v[88:91]
	v_mfma_f32_16x16x32_bf16 v[24:27], v[156:159], v[164:167], v[24:27]
	v_mfma_f32_16x16x32_bf16 v[16:19], v[156:159], v[214:217], v[16:19]
	v_mfma_f32_16x16x32_bf16 v[80:83], v[148:151], v[214:217], v[80:83]
	v_mfma_f32_16x16x32_bf16 v[72:75], v[148:151], v[222:225], v[72:75]
	v_mfma_f32_16x16x32_bf16 v[8:11], v[156:159], v[222:225], v[8:11]
	v_mfma_f32_16x16x32_bf16 v[0:3], v[156:159], v[230:233], v[0:3]
	v_mfma_f32_16x16x32_bf16 v[64:67], v[148:151], v[230:233], v[64:67]
	s_setprio 0
	s_barrier
	s_add_i32 s59, 0, 0x18000
	s_add_i32 s65, 0, 0x1c000
	v_add_u32_e32 v140, s59, v175
	v_add_u32_e32 v156, s65, v175
	ds_read_b128 v[128:131], v140
	ds_read_b128 v[132:135], v140 offset:1024
	ds_read_b128 v[136:139], v140 offset:2048
	ds_read_b128 v[140:143], v140 offset:3072
	ds_read_b128 v[144:147], v156
	ds_read_b128 v[148:151], v156 offset:1024
	ds_read_b128 v[152:155], v156 offset:2048
	ds_read_b128 v[156:159], v156 offset:3072
	s_add_u32 s70, s70, 0x80000
	s_addc_u32 s71, s71, 0
	s_mov_b32 m0, s80
	v_lshl_add_u64 v[238:239], s[70:71], 0, v[176:177]
	ds_read_b128 v[160:163], v207 offset:32768
	ds_read_b128 v[164:167], v207 offset:33792
	ds_read_b128 v[194:197], v207 offset:34816
	ds_read_b128 v[214:217], v207 offset:35840
	ds_read_b128 v[218:221], v207 offset:36864
	ds_read_b128 v[222:225], v207 offset:37888
	ds_read_b128 v[226:229], v207 offset:38912
	ds_read_b128 v[230:233], v207 offset:39936
	global_load_lds_dwordx4 v[238:239], off
	v_lshl_add_u64 v[238:239], s[70:71], 0, v[180:181]
	s_mov_b32 m0, s81
	s_nop 0
	global_load_lds_dwordx4 v[238:239], off
	s_waitcnt vmcnt(8)
	s_waitcnt lgkmcnt(0)
	s_barrier
	s_setprio 1
	s_waitcnt lgkmcnt(0)
	v_mfma_f32_16x16x32_bf16 v[124:127], v[128:131], v[160:163], v[124:127]
	v_mfma_f32_16x16x32_bf16 v[60:63], v[136:139], v[160:163], v[60:63]
	v_mfma_f32_16x16x32_bf16 v[52:55], v[136:139], v[194:197], v[52:55]
	v_mfma_f32_16x16x32_bf16 v[116:119], v[128:131], v[194:197], v[116:119]
	v_mfma_f32_16x16x32_bf16 v[108:111], v[128:131], v[218:221], v[108:111]
	v_mfma_f32_16x16x32_bf16 v[44:47], v[136:139], v[218:221], v[44:47]
	v_mfma_f32_16x16x32_bf16 v[36:39], v[136:139], v[226:229], v[36:39]
	v_mfma_f32_16x16x32_bf16 v[100:103], v[128:131], v[226:229], v[100:103]
	v_mfma_f32_16x16x32_bf16 v[124:127], v[132:135], v[164:167], v[124:127]
	v_mfma_f32_16x16x32_bf16 v[60:63], v[140:143], v[164:167], v[60:63]
	v_mfma_f32_16x16x32_bf16 v[52:55], v[140:143], v[214:217], v[52:55]
	v_mfma_f32_16x16x32_bf16 v[116:119], v[132:135], v[214:217], v[116:119]
	v_mfma_f32_16x16x32_bf16 v[108:111], v[132:135], v[222:225], v[108:111]
	v_mfma_f32_16x16x32_bf16 v[44:47], v[140:143], v[222:225], v[44:47]
	v_mfma_f32_16x16x32_bf16 v[36:39], v[140:143], v[230:233], v[36:39]
	v_mfma_f32_16x16x32_bf16 v[100:103], v[132:135], v[230:233], v[100:103]
	s_setprio 0
	s_setprio 1
	v_mfma_f32_16x16x32_bf16 v[120:123], v[144:147], v[160:163], v[120:123]
	v_mfma_f32_16x16x32_bf16 v[56:59], v[152:155], v[160:163], v[56:59]
	v_mfma_f32_16x16x32_bf16 v[48:51], v[152:155], v[194:197], v[48:51]
	v_mfma_f32_16x16x32_bf16 v[112:115], v[144:147], v[194:197], v[112:115]
	v_mfma_f32_16x16x32_bf16 v[104:107], v[144:147], v[218:221], v[104:107]
	v_mfma_f32_16x16x32_bf16 v[40:43], v[152:155], v[218:221], v[40:43]
	v_mfma_f32_16x16x32_bf16 v[32:35], v[152:155], v[226:229], v[32:35]
	v_mfma_f32_16x16x32_bf16 v[96:99], v[144:147], v[226:229], v[96:99]
	v_mfma_f32_16x16x32_bf16 v[120:123], v[148:151], v[164:167], v[120:123]
	v_mfma_f32_16x16x32_bf16 v[56:59], v[156:159], v[164:167], v[56:59]
	v_mfma_f32_16x16x32_bf16 v[48:51], v[156:159], v[214:217], v[48:51]
	v_mfma_f32_16x16x32_bf16 v[112:115], v[148:151], v[214:217], v[112:115]
	v_mfma_f32_16x16x32_bf16 v[104:107], v[148:151], v[222:225], v[104:107]
	v_mfma_f32_16x16x32_bf16 v[40:43], v[156:159], v[222:225], v[40:43]
	v_mfma_f32_16x16x32_bf16 v[32:35], v[156:159], v[230:233], v[32:35]
	v_mfma_f32_16x16x32_bf16 v[96:99], v[148:151], v[230:233], v[96:99]
	s_setprio 0
	s_barrier
; #define PG8_STAGE(bufoff, gbase, voff) do { _Pragma("unroll") for (int _i = 0; _i < 2; ++_i) \
;         __builtin_amdgcn_global_load_lds((const unsigned*)((const char*)(gbase) + (voff)[_i]), (PG8_LAS unsigned*)(lds + (bufoff) + ldsw + _i * 8192), 16, 0, 0); } while (0)
; #define PG8_LDA(dst, b, h) do { _Pragma("unroll") for (int m = 0; m < 4; ++m) _Pragma("unroll") for (int k = 0; k < 2; ++k) dst[m][k] = *(const PG8_LAS bf16x8*)(lds + PG8_SA(b, h) + aoff + m * 2048 + k * 1024); } while (0)
; #define PG8_MMA(ai, bj, At, Bt) do { __builtin_amdgcn_s_setprio(1); _Pragma("unroll") for (int m = 0; m < 4; ++m) _Pragma("unroll") for (int n = 0; n < 2; ++n) _Pragma("unroll") for (int k = 0; k < 2; ++k) \
;         acc[ai][bj][m][n] = __builtin_amdgcn_mfma_f32_16x16x32_bf16(Bt[n][k], At[m][k], acc[ai][bj][m][n], 0, 0, 0); __builtin_amdgcn_s_setprio(0); } while (0)
; #define PG8_WAIT_V(n) asm volatile("s_waitcnt vmcnt(" #n ")" ::: "memory")
; #define PG8_WAIT_L(n) asm volatile("s_waitcnt lgkmcnt(" #n ")" ::: "memory")
; #define PG8_BAR __builtin_amdgcn_s_barrier()
; #define PG8_SCHED __builtin_amdgcn_sched_barrier(0)
; template <class Epi, class Sched, bool ALIGN_EPI = false, bool SP2 = false>
; __device__ __forceinline__ void gemm_phase(PG8_LAS unsigned char* lds, const Gemm g, const Sched& S, const Epi& E) {
;     ...
;             PG8_LDA(At, 1, 1); PG8_STAGE(PG8_SB(1, 0), b3, voffB); PG8_STAGE(PG8_SB(1, 1), b3 + hstepB, voffB); PG8_STAGE(PG8_SA(1, 0), a3, voffA);
;             PG8_WAIT_V(8); PG8_WAIT_L(0); PG8_BAR; PG8_MMA(1, 0, At, B0); PG8_MMA(1, 1, At, B1); PG8_BAR; PG8_SCHED;
;     ...
;         if constexpr (ALIGN_EPI) { if (wr == 0) PG8_BAR; }
	s_add_i32 s59, s59, s76
	v_lshl_add_u64 v[168:169], v[168:169], 0, s[36:37]
	s_mov_b32 m0, s59
	ds_read_b128 v[160:163], v207 offset:49152
	ds_read_b128 v[164:167], v207 offset:50176
	ds_read_b128 v[194:197], v207 offset:51200
	ds_read_b128 v[214:217], v207 offset:52224
	ds_read_b128 v[218:221], v207 offset:53248
	ds_read_b128 v[222:225], v207 offset:54272
	ds_read_b128 v[226:229], v207 offset:55296
	ds_read_b128 v[230:233], v207 offset:56320
	global_load_lds_dwordx4 v[168:169], off
	s_add_i32 m0, s59, 0x2000
	s_add_u32 s68, s68, 0x20080
	v_lshl_add_u64 v[168:169], v[198:199], 0, s[36:37]
	s_addc_u32 s69, s69, 0
	s_add_i32 s59, s65, s76
	global_load_lds_dwordx4 v[168:169], off
	v_lshl_add_u64 v[168:169], s[68:69], 0, v[178:179]
	s_mov_b32 m0, s59
	s_nop 0
	global_load_lds_dwordx4 v[168:169], off
	v_lshl_add_u64 v[168:169], s[68:69], 0, v[182:183]
	s_add_i32 m0, s59, 0x2000
	s_nop 0
	global_load_lds_dwordx4 v[168:169], off
	v_lshl_add_u64 v[168:169], v[234:235], 0, s[36:37]
	s_mov_b32 m0, s83
	s_nop 0
	global_load_lds_dwordx4 v[168:169], off
	v_lshl_add_u64 v[168:169], v[236:237], 0, s[36:37]
	s_mov_b32 m0, s84
	s_nop 0
	global_load_lds_dwordx4 v[168:169], off
	s_waitcnt vmcnt(8)
	s_waitcnt lgkmcnt(0)
	s_barrier
	s_setprio 1
	s_waitcnt lgkmcnt(0)
	v_mfma_f32_16x16x32_bf16 v[92:95], v[128:131], v[160:163], v[92:95]
	v_mfma_f32_16x16x32_bf16 v[28:31], v[136:139], v[160:163], v[28:31]
	v_mfma_f32_16x16x32_bf16 v[20:23], v[136:139], v[194:197], v[20:23]
	v_mfma_f32_16x16x32_bf16 v[84:87], v[128:131], v[194:197], v[84:87]
	v_mfma_f32_16x16x32_bf16 v[76:79], v[128:131], v[218:221], v[76:79]
	v_mfma_f32_16x16x32_bf16 v[12:15], v[136:139], v[218:221], v[12:15]
	v_mfma_f32_16x16x32_bf16 v[4:7], v[136:139], v[226:229], v[4:7]
	v_mfma_f32_16x16x32_bf16 v[68:71], v[128:131], v[226:229], v[68:71]
	v_mfma_f32_16x16x32_bf16 v[92:95], v[132:135], v[164:167], v[92:95]
	v_mfma_f32_16x16x32_bf16 v[28:31], v[140:143], v[164:167], v[28:31]
	v_mfma_f32_16x16x32_bf16 v[20:23], v[140:143], v[214:217], v[20:23]
	v_mfma_f32_16x16x32_bf16 v[84:87], v[132:135], v[214:217], v[84:87]
	v_mfma_f32_16x16x32_bf16 v[76:79], v[132:135], v[222:225], v[76:79]
	v_mfma_f32_16x16x32_bf16 v[12:15], v[140:143], v[222:225], v[12:15]
	v_mfma_f32_16x16x32_bf16 v[4:7], v[140:143], v[230:233], v[4:7]
	v_mfma_f32_16x16x32_bf16 v[68:71], v[132:135], v[230:233], v[68:71]
	s_setprio 0
	s_setprio 1
	v_mfma_f32_16x16x32_bf16 v[88:91], v[144:147], v[160:163], v[88:91]
	v_mfma_f32_16x16x32_bf16 v[24:27], v[152:155], v[160:163], v[24:27]
	v_mfma_f32_16x16x32_bf16 v[16:19], v[152:155], v[194:197], v[16:19]
	v_mfma_f32_16x16x32_bf16 v[80:83], v[144:147], v[194:197], v[80:83]
	v_mfma_f32_16x16x32_bf16 v[72:75], v[144:147], v[218:221], v[72:75]
	v_mfma_f32_16x16x32_bf16 v[8:11], v[152:155], v[218:221], v[8:11]
	v_mfma_f32_16x16x32_bf16 v[0:3], v[152:155], v[226:229], v[0:3]
	v_mfma_f32_16x16x32_bf16 v[64:67], v[144:147], v[226:229], v[64:67]
	v_mfma_f32_16x16x32_bf16 v[88:91], v[148:151], v[164:167], v[88:91]
	v_mfma_f32_16x16x32_bf16 v[24:27], v[156:159], v[164:167], v[24:27]
	v_mfma_f32_16x16x32_bf16 v[16:19], v[156:159], v[214:217], v[16:19]
	v_mfma_f32_16x16x32_bf16 v[80:83], v[148:151], v[214:217], v[80:83]
	v_mfma_f32_16x16x32_bf16 v[72:75], v[148:151], v[222:225], v[72:75]
	v_mfma_f32_16x16x32_bf16 v[8:11], v[156:159], v[222:225], v[8:11]
	v_mfma_f32_16x16x32_bf16 v[0:3], v[156:159], v[230:233], v[0:3]
	v_mfma_f32_16x16x32_bf16 v[64:67], v[148:151], v[230:233], v[64:67]
	s_setprio 0
	s_barrier
	s_add_i32 s57, s57, 2
	s_add_u32 s50, s50, 0x100
	s_addc_u32 s51, s51, 0
	s_add_u32 s12, s12, 0x100
	s_addc_u32 s13, s13, 0
	s_cmp_gt_u32 s57, 29
	s_cbranch_scc0 .LBB0_1632
	s_and_b64 vcc, exec, s[38:39]
	s_cbranch_vccz .LBB0_1635
	s_barrier

; #define PG8_STAGE(bufoff, gbase, voff) do { _Pragma("unroll") for (int _i = 0; _i < 2; ++_i) \
;         __builtin_amdgcn_global_load_lds((const unsigned*)((const char*)(gbase) + (voff)[_i]), (PG8_LAS unsigned*)(lds + (bufoff) + ldsw + _i * 8192), 16, 0, 0); } while (0)
; #define PG8_LDA(dst, b, h) do { _Pragma("unroll") for (int m = 0; m < 4; ++m) _Pragma("unroll") for (int k = 0; k < 2; ++k) dst[m][k] = *(const PG8_LAS bf16x8*)(lds + PG8_SA(b, h) + aoff + m * 2048 + k * 1024); } while (0)
; #define PG8_LDB(dst, b, h) do { _Pragma("unroll") for (int n = 0; n < 2; ++n) _Pragma("unroll") for (int k = 0; k < 2; ++k) dst[n][k] = *(const PG8_LAS bf16x8*)(lds + PG8_SB(b, h) + boff + n * 2048 + k * 1024); } while (0)
; #define PG8_MMA(ai, bj, At, Bt) do { __builtin_amdgcn_s_setprio(1); _Pragma("unroll") for (int m = 0; m < 4; ++m) _Pragma("unroll") for (int n = 0; n < 2; ++n) _Pragma("unroll") for (int k = 0; k < 2; ++k) \
;         acc[ai][bj][m][n] = __builtin_amdgcn_mfma_f32_16x16x32_bf16(Bt[n][k], At[m][k], acc[ai][bj][m][n], 0, 0, 0); __builtin_amdgcn_s_setprio(0); } while (0)
; #define PG8_WAIT_V(n) asm volatile("s_waitcnt vmcnt(" #n ")" ::: "memory")
; #define PG8_WAIT_L(n) asm volatile("s_waitcnt lgkmcnt(" #n ")" ::: "memory")
; #define PG8_BAR __builtin_amdgcn_s_barrier()
; #define PG8_SCHED __builtin_amdgcn_sched_barrier(0)
; template <class Epi, class Sched, bool ALIGN_EPI = false, bool SP2 = false>
; __device__ __forceinline__ void gemm_phase(PG8_LAS unsigned char* lds, const Gemm g, const Sched& S, const Epi& E) {
;     ...
;             const bool last = (t == nt - 2);
;             const char* a1 = cA + (size_t)(t + 1) * kstep;
;             const char* a2 = last ? nA : cA + (size_t)(t + 2) * kstep; const char* b2 = last ? nB : cB + (size_t)(t + 2) * kstep;
;             const char* a3 = a2 + kstep; const char* b3 = b2 + kstep;
;             if (last && has_next) S.a_ready(nxt);
;             if constexpr (SP2) {
;             PG8_LDB(B0, 0, 0); PG8_LDB(B1, 0, 1); PG8_SCHED; PG8_LDA(At, 0, 0); PG8_STAGE(PG8_SA(1, 1), a1 + hstep, voffA);
;             PG8_WAIT_V(8); PG8_WAIT_L(0); PG8_BAR; PG8_MMA(0, 0, At, B0); PG8_MMA(0, 1, At, B1); PG8_BAR; PG8_SCHED;
;             PG8_LDA(At, 0, 1); PG8_STAGE(PG8_SB(0, 0), b2, voffB); PG8_STAGE(PG8_SB(0, 1), b2 + hstepB, voffB); PG8_STAGE(PG8_SA(0, 0), a2, voffA);
.LBB0_1785:
	ds_read_b128 v[156:159], v152
	ds_read_b128 v[160:163], v152 offset:1024
	ds_read_b128 v[164:167], v152 offset:2048
	ds_read_b128 v[174:177], v152 offset:3072
	ds_read_b128 v[178:181], v153
	ds_read_b128 v[182:185], v153 offset:1024
	ds_read_b128 v[186:189], v153 offset:2048
	ds_read_b128 v[190:193], v153 offset:3072
	s_add_u32 s24, s22, 0x100
	s_addc_u32 s25, s23, 0
	s_cmpk_eq_i32 s48, 0x54
	s_cselect_b32 s29, s9, s25
	s_cselect_b32 s28, s8, s24
	s_cselect_b32 s27, s21, s41
	s_cselect_b32 s26, s20, s40
	v_lshl_add_u64 v[146:147], s[22:23], 0, v[140:141]
	s_add_i32 m0, s37, 0xc000
	ds_read_b128 v[194:197], v154
	ds_read_b128 v[202:205], v154 offset:1024
	ds_read_b128 v[206:209], v154 offset:2048
	ds_read_b128 v[210:213], v154 offset:3072
	ds_read_b128 v[214:217], v154 offset:4096
	ds_read_b128 v[218:221], v154 offset:5120
	ds_read_b128 v[222:225], v154 offset:6144
	ds_read_b128 v[226:229], v154 offset:7168
	global_load_lds_dwordx4 v[146:147], off
	v_lshl_add_u64 v[146:147], s[22:23], 0, v[138:139]
	s_add_i32 m0, s37, 0xe000
	s_nop 0
	global_load_lds_dwordx4 v[146:147], off
	s_waitcnt vmcnt(8)
	s_waitcnt lgkmcnt(0)
	s_barrier
	s_setprio 1
	s_waitcnt lgkmcnt(0)
	v_mfma_f32_16x16x32_bf16 v[124:127], v[156:159], v[194:197], v[124:127]
	v_mfma_f32_16x16x32_bf16 v[120:123], v[164:167], v[194:197], v[120:123]
	v_mfma_f32_16x16x32_bf16 v[108:111], v[164:167], v[206:209], v[108:111]
	v_mfma_f32_16x16x32_bf16 v[116:119], v[156:159], v[206:209], v[116:119]
	v_mfma_f32_16x16x32_bf16 v[96:99], v[156:159], v[214:217], v[96:99]
	v_mfma_f32_16x16x32_bf16 v[88:91], v[164:167], v[214:217], v[88:91]
	v_mfma_f32_16x16x32_bf16 v[72:75], v[164:167], v[222:225], v[72:75]
	v_mfma_f32_16x16x32_bf16 v[80:83], v[156:159], v[222:225], v[80:83]
	v_mfma_f32_16x16x32_bf16 v[124:127], v[160:163], v[202:205], v[124:127]
	v_mfma_f32_16x16x32_bf16 v[120:123], v[174:177], v[202:205], v[120:123]
	v_mfma_f32_16x16x32_bf16 v[108:111], v[174:177], v[210:213], v[108:111]
	v_mfma_f32_16x16x32_bf16 v[116:119], v[160:163], v[210:213], v[116:119]
	v_mfma_f32_16x16x32_bf16 v[96:99], v[160:163], v[218:221], v[96:99]
	v_mfma_f32_16x16x32_bf16 v[88:91], v[174:177], v[218:221], v[88:91]
	v_mfma_f32_16x16x32_bf16 v[72:75], v[174:177], v[226:229], v[72:75]
	v_mfma_f32_16x16x32_bf16 v[80:83], v[160:163], v[226:229], v[80:83]
	s_setprio 0
	s_setprio 1
	v_mfma_f32_16x16x32_bf16 v[112:115], v[178:181], v[194:197], v[112:115]
	v_mfma_f32_16x16x32_bf16 v[104:107], v[186:189], v[194:197], v[104:107]
	v_mfma_f32_16x16x32_bf16 v[92:95], v[186:189], v[206:209], v[92:95]
	v_mfma_f32_16x16x32_bf16 v[100:103], v[178:181], v[206:209], v[100:103]
	v_mfma_f32_16x16x32_bf16 v[84:87], v[178:181], v[214:217], v[84:87]
	v_mfma_f32_16x16x32_bf16 v[76:79], v[186:189], v[214:217], v[76:79]
	v_mfma_f32_16x16x32_bf16 v[64:67], v[186:189], v[222:225], v[64:67]
	v_mfma_f32_16x16x32_bf16 v[68:71], v[178:181], v[222:225], v[68:71]
	v_mfma_f32_16x16x32_bf16 v[112:115], v[182:185], v[202:205], v[112:115]
	v_mfma_f32_16x16x32_bf16 v[104:107], v[190:193], v[202:205], v[104:107]
	v_mfma_f32_16x16x32_bf16 v[92:95], v[190:193], v[210:213], v[92:95]
	v_mfma_f32_16x16x32_bf16 v[100:103], v[182:185], v[210:213], v[100:103]
	v_mfma_f32_16x16x32_bf16 v[84:87], v[182:185], v[218:221], v[84:87]
	v_mfma_f32_16x16x32_bf16 v[76:79], v[190:193], v[218:221], v[76:79]
	v_mfma_f32_16x16x32_bf16 v[64:67], v[190:193], v[226:229], v[64:67]
	v_mfma_f32_16x16x32_bf16 v[68:71], v[182:185], v[226:229], v[68:71]
	s_setprio 0
	s_barrier
	s_add_i32 s22, s58, s36
	v_lshl_add_u64 v[146:147], s[26:27], 0, v[130:131]
	s_mov_b32 m0, s22
	ds_read_b128 v[194:197], v154 offset:16384
	ds_read_b128 v[202:205], v154 offset:17408
	ds_read_b128 v[206:209], v154 offset:18432
	ds_read_b128 v[210:213], v154 offset:19456
	ds_read_b128 v[214:217], v154 offset:20480
	ds_read_b128 v[218:221], v154 offset:21504
	ds_read_b128 v[222:225], v154 offset:22528
	ds_read_b128 v[226:229], v154 offset:23552
	global_load_lds_dwordx4 v[146:147], off
	s_add_i32 m0, s22, 0x2000
	s_add_u32 s22, s26, 0x58000
	v_lshl_add_u64 v[168:169], s[26:27], 0, v[134:135]
	s_addc_u32 s23, s27, 0
	s_add_i32 s49, s59, s36
	global_load_lds_dwordx4 v[168:169], off
	v_lshl_add_u64 v[198:199], s[22:23], 0, v[130:131]
	s_mov_b32 m0, s49
	v_lshl_add_u64 v[230:231], s[28:29], 0, v[132:133]
	global_load_lds_dwordx4 v[198:199], off
	v_lshl_add_u64 v[198:199], s[22:23], 0, v[134:135]
	s_add_i32 m0, s49, 0x2000
	s_nop 0
	global_load_lds_dwordx4 v[198:199], off
	v_lshl_add_u64 v[198:199], s[28:29], 0, v[128:129]
	s_mov_b32 m0, s37
	s_nop 0
	global_load_lds_dwordx4 v[198:199], off
	s_mov_b32 m0, s38
	s_nop 0
	global_load_lds_dwordx4 v[230:231], off
	s_waitcnt vmcnt(8)
	s_waitcnt lgkmcnt(0)
	s_barrier
; #define PG8_STAGE(bufoff, gbase, voff) do { _Pragma("unroll") for (int _i = 0; _i < 2; ++_i) \
;         __builtin_amdgcn_global_load_lds((const unsigned*)((const char*)(gbase) + (voff)[_i]), (PG8_LAS unsigned*)(lds + (bufoff) + ldsw + _i * 8192), 16, 0, 0); } while (0)
; #define PG8_LDA(dst, b, h) do { _Pragma("unroll") for (int m = 0; m < 4; ++m) _Pragma("unroll") for (int k = 0; k < 2; ++k) dst[m][k] = *(const PG8_LAS bf16x8*)(lds + PG8_SA(b, h) + aoff + m * 2048 + k * 1024); } while (0)
; #define PG8_LDB(dst, b, h) do { _Pragma("unroll") for (int n = 0; n < 2; ++n) _Pragma("unroll") for (int k = 0; k < 2; ++k) dst[n][k] = *(const PG8_LAS bf16x8*)(lds + PG8_SB(b, h) + boff + n * 2048 + k * 1024); } while (0)
; #define PG8_MMA(ai, bj, At, Bt) do { __builtin_amdgcn_s_setprio(1); _Pragma("unroll") for (int m = 0; m < 4; ++m) _Pragma("unroll") for (int n = 0; n < 2; ++n) _Pragma("unroll") for (int k = 0; k < 2; ++k) \
;         acc[ai][bj][m][n] = __builtin_amdgcn_mfma_f32_16x16x32_bf16(Bt[n][k], At[m][k], acc[ai][bj][m][n], 0, 0, 0); __builtin_amdgcn_s_setprio(0); } while (0)
; #define PG8_WAIT_V(n) asm volatile("s_waitcnt vmcnt(" #n ")" ::: "memory")
; #define PG8_WAIT_L(n) asm volatile("s_waitcnt lgkmcnt(" #n ")" ::: "memory")
; #define PG8_BAR __builtin_amdgcn_s_barrier()
; #define PG8_SCHED __builtin_amdgcn_sched_barrier(0)
; template <class Epi, class Sched, bool ALIGN_EPI = false, bool SP2 = false>
; __device__ __forceinline__ void gemm_phase(PG8_LAS unsigned char* lds, const Gemm g, const Sched& S, const Epi& E) {
;     ...
;             PG8_WAIT_V(8); PG8_WAIT_L(0); PG8_BAR; PG8_MMA(1, 0, At, B0); PG8_MMA(1, 1, At, B1); PG8_BAR; PG8_SCHED;
;             PG8_LDB(B0, 1, 0); PG8_LDB(B1, 1, 1); PG8_SCHED; PG8_LDA(At, 1, 0); PG8_STAGE(PG8_SA(0, 1), a2 + hstep, voffA);
;             PG8_WAIT_V(8); PG8_WAIT_L(0); PG8_BAR; PG8_MMA(0, 0, At, B0); PG8_MMA(0, 1, At, B1); PG8_BAR; PG8_SCHED;
	s_setprio 1
	s_waitcnt lgkmcnt(0)
	v_mfma_f32_16x16x32_bf16 v[60:63], v[156:159], v[194:197], v[60:63]
	v_mfma_f32_16x16x32_bf16 v[56:59], v[164:167], v[194:197], v[56:59]
	v_mfma_f32_16x16x32_bf16 v[40:43], v[164:167], v[206:209], v[40:43]
	v_mfma_f32_16x16x32_bf16 v[48:51], v[156:159], v[206:209], v[48:51]
	v_mfma_f32_16x16x32_bf16 v[32:35], v[156:159], v[214:217], v[32:35]
	v_mfma_f32_16x16x32_bf16 v[24:27], v[164:167], v[214:217], v[24:27]
	v_mfma_f32_16x16x32_bf16 v[8:11], v[164:167], v[222:225], v[8:11]
	v_mfma_f32_16x16x32_bf16 v[16:19], v[156:159], v[222:225], v[16:19]
	v_mfma_f32_16x16x32_bf16 v[60:63], v[160:163], v[202:205], v[60:63]
	v_mfma_f32_16x16x32_bf16 v[56:59], v[174:177], v[202:205], v[56:59]
	v_mfma_f32_16x16x32_bf16 v[40:43], v[174:177], v[210:213], v[40:43]
	v_mfma_f32_16x16x32_bf16 v[48:51], v[160:163], v[210:213], v[48:51]
	v_mfma_f32_16x16x32_bf16 v[32:35], v[160:163], v[218:221], v[32:35]
	v_mfma_f32_16x16x32_bf16 v[24:27], v[174:177], v[218:221], v[24:27]
	v_mfma_f32_16x16x32_bf16 v[8:11], v[174:177], v[226:229], v[8:11]
	v_mfma_f32_16x16x32_bf16 v[16:19], v[160:163], v[226:229], v[16:19]
	s_setprio 0
	s_setprio 1
	v_mfma_f32_16x16x32_bf16 v[52:55], v[178:181], v[194:197], v[52:55]
	v_mfma_f32_16x16x32_bf16 v[44:47], v[186:189], v[194:197], v[44:47]
	v_mfma_f32_16x16x32_bf16 v[28:31], v[186:189], v[206:209], v[28:31]
	v_mfma_f32_16x16x32_bf16 v[36:39], v[178:181], v[206:209], v[36:39]
	v_mfma_f32_16x16x32_bf16 v[20:23], v[178:181], v[214:217], v[20:23]
	v_mfma_f32_16x16x32_bf16 v[12:15], v[186:189], v[214:217], v[12:15]
	v_mfma_f32_16x16x32_bf16 v[0:3], v[186:189], v[222:225], v[0:3]
	v_mfma_f32_16x16x32_bf16 v[4:7], v[178:181], v[222:225], v[4:7]
	v_mfma_f32_16x16x32_bf16 v[52:55], v[182:185], v[202:205], v[52:55]
	v_mfma_f32_16x16x32_bf16 v[44:47], v[190:193], v[202:205], v[44:47]
	v_mfma_f32_16x16x32_bf16 v[28:31], v[190:193], v[210:213], v[28:31]
	v_mfma_f32_16x16x32_bf16 v[36:39], v[182:185], v[210:213], v[36:39]
	v_mfma_f32_16x16x32_bf16 v[20:23], v[182:185], v[218:221], v[20:23]
	v_mfma_f32_16x16x32_bf16 v[12:15], v[190:193], v[218:221], v[12:15]
	v_mfma_f32_16x16x32_bf16 v[0:3], v[190:193], v[226:229], v[0:3]
	v_mfma_f32_16x16x32_bf16 v[4:7], v[182:185], v[226:229], v[4:7]
	s_setprio 0
	s_barrier
	s_add_i32 s49, 0, 0x18000
	v_add_u32_e32 v155, s49, v148
	s_add_i32 s50, 0, 0x1c000
	ds_read_b128 v[156:159], v155
	ds_read_b128 v[160:163], v155 offset:1024
	ds_read_b128 v[164:167], v155 offset:2048
	ds_read_b128 v[174:177], v155 offset:3072
	v_add_u32_e32 v155, s50, v148
	ds_read_b128 v[178:181], v155
	ds_read_b128 v[182:185], v155 offset:1024
	ds_read_b128 v[186:189], v155 offset:2048
	ds_read_b128 v[190:193], v155 offset:3072
	s_add_u32 s22, s28, 0x160000
	s_addc_u32 s23, s29, 0
	s_mov_b32 m0, s39
	v_lshl_add_u64 v[232:233], s[22:23], 0, v[128:129]
	ds_read_b128 v[194:197], v154 offset:32768
	ds_read_b128 v[202:205], v154 offset:33792
	ds_read_b128 v[206:209], v154 offset:34816
	ds_read_b128 v[210:213], v154 offset:35840
	ds_read_b128 v[214:217], v154 offset:36864
	ds_read_b128 v[218:221], v154 offset:37888
	ds_read_b128 v[222:225], v154 offset:38912
	ds_read_b128 v[226:229], v154 offset:39936
	global_load_lds_dwordx4 v[232:233], off
	v_lshl_add_u64 v[232:233], s[22:23], 0, v[132:133]
	s_mov_b32 m0, s42
	s_nop 0
	global_load_lds_dwordx4 v[232:233], off
	s_waitcnt vmcnt(8)
	s_waitcnt lgkmcnt(0)
	s_barrier
	s_setprio 1
	s_waitcnt lgkmcnt(0)
	v_mfma_f32_16x16x32_bf16 v[124:127], v[156:159], v[194:197], v[124:127]
	v_mfma_f32_16x16x32_bf16 v[120:123], v[164:167], v[194:197], v[120:123]
	v_mfma_f32_16x16x32_bf16 v[108:111], v[164:167], v[206:209], v[108:111]
	v_mfma_f32_16x16x32_bf16 v[116:119], v[156:159], v[206:209], v[116:119]
	v_mfma_f32_16x16x32_bf16 v[96:99], v[156:159], v[214:217], v[96:99]
	v_mfma_f32_16x16x32_bf16 v[88:91], v[164:167], v[214:217], v[88:91]
	v_mfma_f32_16x16x32_bf16 v[72:75], v[164:167], v[222:225], v[72:75]
	v_mfma_f32_16x16x32_bf16 v[80:83], v[156:159], v[222:225], v[80:83]
	v_mfma_f32_16x16x32_bf16 v[124:127], v[160:163], v[202:205], v[124:127]
	v_mfma_f32_16x16x32_bf16 v[120:123], v[174:177], v[202:205], v[120:123]
	v_mfma_f32_16x16x32_bf16 v[108:111], v[174:177], v[210:213], v[108:111]
	v_mfma_f32_16x16x32_bf16 v[116:119], v[160:163], v[210:213], v[116:119]
	v_mfma_f32_16x16x32_bf16 v[96:99], v[160:163], v[218:221], v[96:99]
	v_mfma_f32_16x16x32_bf16 v[88:91], v[174:177], v[218:221], v[88:91]
	v_mfma_f32_16x16x32_bf16 v[72:75], v[174:177], v[226:229], v[72:75]
	v_mfma_f32_16x16x32_bf16 v[80:83], v[160:163], v[226:229], v[80:83]
	s_setprio 0
	s_setprio 1
	v_mfma_f32_16x16x32_bf16 v[112:115], v[178:181], v[194:197], v[112:115]
	v_mfma_f32_16x16x32_bf16 v[104:107], v[186:189], v[194:197], v[104:107]
	v_mfma_f32_16x16x32_bf16 v[92:95], v[186:189], v[206:209], v[92:95]
	v_mfma_f32_16x16x32_bf16 v[100:103], v[178:181], v[206:209], v[100:103]
	v_mfma_f32_16x16x32_bf16 v[84:87], v[178:181], v[214:217], v[84:87]
	v_mfma_f32_16x16x32_bf16 v[76:79], v[186:189], v[214:217], v[76:79]
	v_mfma_f32_16x16x32_bf16 v[64:67], v[186:189], v[222:225], v[64:67]
	v_mfma_f32_16x16x32_bf16 v[68:71], v[178:181], v[222:225], v[68:71]
	v_mfma_f32_16x16x32_bf16 v[112:115], v[182:185], v[202:205], v[112:115]
	v_mfma_f32_16x16x32_bf16 v[104:107], v[190:193], v[202:205], v[104:107]
	v_mfma_f32_16x16x32_bf16 v[92:95], v[190:193], v[210:213], v[92:95]
	v_mfma_f32_16x16x32_bf16 v[100:103], v[182:185], v[210:213], v[100:103]
	v_mfma_f32_16x16x32_bf16 v[84:87], v[182:185], v[218:221], v[84:87]
	v_mfma_f32_16x16x32_bf16 v[76:79], v[190:193], v[218:221], v[76:79]
	v_mfma_f32_16x16x32_bf16 v[64:67], v[190:193], v[226:229], v[64:67]
	v_mfma_f32_16x16x32_bf16 v[68:71], v[182:185], v[226:229], v[68:71]
	s_setprio 0
	s_barrier
; #define PG8_STAGE(bufoff, gbase, voff) do { _Pragma("unroll") for (int _i = 0; _i < 2; ++_i) \
;         __builtin_amdgcn_global_load_lds((const unsigned*)((const char*)(gbase) + (voff)[_i]), (PG8_LAS unsigned*)(lds + (bufoff) + ldsw + _i * 8192), 16, 0, 0); } while (0)
; #define PG8_LDA(dst, b, h) do { _Pragma("unroll") for (int m = 0; m < 4; ++m) _Pragma("unroll") for (int k = 0; k < 2; ++k) dst[m][k] = *(const PG8_LAS bf16x8*)(lds + PG8_SA(b, h) + aoff + m * 2048 + k * 1024); } while (0)
; #define PG8_MMA(ai, bj, At, Bt) do { __builtin_amdgcn_s_setprio(1); _Pragma("unroll") for (int m = 0; m < 4; ++m) _Pragma("unroll") for (int n = 0; n < 2; ++n) _Pragma("unroll") for (int k = 0; k < 2; ++k) \
;         acc[ai][bj][m][n] = __builtin_amdgcn_mfma_f32_16x16x32_bf16(Bt[n][k], At[m][k], acc[ai][bj][m][n], 0, 0, 0); __builtin_amdgcn_s_setprio(0); } while (0)
; #define PG8_WAIT_V(n) asm volatile("s_waitcnt vmcnt(" #n ")" ::: "memory")
; #define PG8_WAIT_L(n) asm volatile("s_waitcnt lgkmcnt(" #n ")" ::: "memory")
; #define PG8_BAR __builtin_amdgcn_s_barrier()
; #define PG8_SCHED __builtin_amdgcn_sched_barrier(0)
; template <class Epi, class Sched, bool ALIGN_EPI = false, bool SP2 = false>
; __device__ __forceinline__ void gemm_phase(PG8_LAS unsigned char* lds, const Gemm g, const Sched& S, const Epi& E) {
;     ...
;             PG8_LDA(At, 1, 1); PG8_STAGE(PG8_SB(1, 0), b3, voffB); PG8_STAGE(PG8_SB(1, 1), b3 + hstepB, voffB); PG8_STAGE(PG8_SA(1, 0), a3, voffA);
;             PG8_WAIT_V(8); PG8_WAIT_L(0); PG8_BAR; PG8_MMA(1, 0, At, B0); PG8_MMA(1, 1, At, B1); PG8_BAR; PG8_SCHED;
;     ...
;         if constexpr (ALIGN_EPI) { if (wr == 0) PG8_BAR; }
	s_add_i32 s22, s49, s36
	v_lshl_add_u64 v[146:147], v[146:147], 0, s[16:17]
	s_mov_b32 m0, s22
	ds_read_b128 v[194:197], v154 offset:49152
	ds_read_b128 v[202:205], v154 offset:50176
	ds_read_b128 v[206:209], v154 offset:51200
	ds_read_b128 v[210:213], v154 offset:52224
	ds_read_b128 v[214:217], v154 offset:53248
	ds_read_b128 v[218:221], v154 offset:54272
	ds_read_b128 v[222:225], v154 offset:55296
	ds_read_b128 v[226:229], v154 offset:56320
	global_load_lds_dwordx4 v[146:147], off
	s_add_i32 m0, s22, 0x2000
	s_add_u32 s22, s26, 0x58080
	v_lshl_add_u64 v[146:147], v[168:169], 0, s[16:17]
	s_addc_u32 s23, s27, 0
	s_add_i32 s26, s50, s36
	global_load_lds_dwordx4 v[146:147], off
	v_lshl_add_u64 v[146:147], s[22:23], 0, v[130:131]
	s_mov_b32 m0, s26
	s_nop 0
	global_load_lds_dwordx4 v[146:147], off
	v_lshl_add_u64 v[146:147], s[22:23], 0, v[134:135]
	s_add_i32 m0, s26, 0x2000
	s_nop 0
	global_load_lds_dwordx4 v[146:147], off
	v_lshl_add_u64 v[146:147], v[198:199], 0, s[16:17]
	s_mov_b32 m0, s54
	s_nop 0
	global_load_lds_dwordx4 v[146:147], off
	v_lshl_add_u64 v[146:147], v[230:231], 0, s[16:17]
	s_mov_b32 m0, s55
	s_nop 0
	global_load_lds_dwordx4 v[146:147], off
	s_waitcnt vmcnt(8)
	s_waitcnt lgkmcnt(0)
	s_barrier
	s_setprio 1
	s_waitcnt lgkmcnt(0)
	v_mfma_f32_16x16x32_bf16 v[60:63], v[156:159], v[194:197], v[60:63]
	v_mfma_f32_16x16x32_bf16 v[56:59], v[164:167], v[194:197], v[56:59]
	v_mfma_f32_16x16x32_bf16 v[40:43], v[164:167], v[206:209], v[40:43]
	v_mfma_f32_16x16x32_bf16 v[48:51], v[156:159], v[206:209], v[48:51]
	v_mfma_f32_16x16x32_bf16 v[32:35], v[156:159], v[214:217], v[32:35]
	v_mfma_f32_16x16x32_bf16 v[24:27], v[164:167], v[214:217], v[24:27]
	v_mfma_f32_16x16x32_bf16 v[8:11], v[164:167], v[222:225], v[8:11]
	v_mfma_f32_16x16x32_bf16 v[16:19], v[156:159], v[222:225], v[16:19]
	v_mfma_f32_16x16x32_bf16 v[60:63], v[160:163], v[202:205], v[60:63]
	v_mfma_f32_16x16x32_bf16 v[56:59], v[174:177], v[202:205], v[56:59]
	v_mfma_f32_16x16x32_bf16 v[40:43], v[174:177], v[210:213], v[40:43]
	v_mfma_f32_16x16x32_bf16 v[48:51], v[160:163], v[210:213], v[48:51]
	v_mfma_f32_16x16x32_bf16 v[32:35], v[160:163], v[218:221], v[32:35]
	v_mfma_f32_16x16x32_bf16 v[24:27], v[174:177], v[218:221], v[24:27]
	v_mfma_f32_16x16x32_bf16 v[8:11], v[174:177], v[226:229], v[8:11]
	v_mfma_f32_16x16x32_bf16 v[16:19], v[160:163], v[226:229], v[16:19]
	s_setprio 0
	s_setprio 1
	v_mfma_f32_16x16x32_bf16 v[52:55], v[178:181], v[194:197], v[52:55]
	v_mfma_f32_16x16x32_bf16 v[44:47], v[186:189], v[194:197], v[44:47]
	v_mfma_f32_16x16x32_bf16 v[28:31], v[186:189], v[206:209], v[28:31]
	v_mfma_f32_16x16x32_bf16 v[36:39], v[178:181], v[206:209], v[36:39]
	v_mfma_f32_16x16x32_bf16 v[20:23], v[178:181], v[214:217], v[20:23]
	v_mfma_f32_16x16x32_bf16 v[12:15], v[186:189], v[214:217], v[12:15]
	v_mfma_f32_16x16x32_bf16 v[0:3], v[186:189], v[222:225], v[0:3]
	v_mfma_f32_16x16x32_bf16 v[4:7], v[178:181], v[222:225], v[4:7]
	v_mfma_f32_16x16x32_bf16 v[52:55], v[182:185], v[202:205], v[52:55]
	v_mfma_f32_16x16x32_bf16 v[44:47], v[190:193], v[202:205], v[44:47]
	v_mfma_f32_16x16x32_bf16 v[28:31], v[190:193], v[210:213], v[28:31]
	v_mfma_f32_16x16x32_bf16 v[36:39], v[182:185], v[210:213], v[36:39]
	v_mfma_f32_16x16x32_bf16 v[20:23], v[182:185], v[218:221], v[20:23]
	v_mfma_f32_16x16x32_bf16 v[12:15], v[190:193], v[218:221], v[12:15]
	v_mfma_f32_16x16x32_bf16 v[0:3], v[190:193], v[226:229], v[0:3]
	v_mfma_f32_16x16x32_bf16 v[4:7], v[182:185], v[226:229], v[4:7]
	s_setprio 0
	s_barrier
	s_add_i32 s48, s48, 2
	s_add_u32 s40, s40, 0x100
	s_addc_u32 s41, s41, 0
	s_cmpk_gt_u32 s48, 0x55
	s_mov_b64 s[22:23], s[24:25]
	s_cbranch_scc0 .LBB0_1785
	s_and_b64 vcc, exec, s[18:19]
	s_cbranch_vccz .LBB0_1788
	s_barrier
